# fused residual stages issue their x/gain loads before the rstd reduction; P9+P10 fused as well (rstd2 for the six tile panels derived at P11 start from 16 partials in the dead qb buffer)
# speedup vs baseline: 1.0239x; 1.0167x over previous
.LBB0_852:
	s_or_b64 exec, exec, s[0:1]
	s_waitcnt lgkmcnt(0)
	s_barrier
	s_and_b32 s98, s2, 7
	s_lshl_b32 s98, s98, 3
	s_bfe_u32 s99, s2, 0x30003
	s_or_b32 s98, s98, s99
	s_lshr_b32 s99, s2, 6
	v_and_b32_e32 v172, 0xff, v136
	v_lshrrev_b32_e32 v173, 8, v136
	v_mul_u32_u24_e32 v173, 0x84000, v173
	v_lshl_add_u32 v172, v172, 2, v173
	s_lshl_b32 s24, s98, 10
	s_add_u32 s18, s44, s24
	s_addc_u32 s19, s45, 0
	global_load_dword v164, v172, s[18:19]
	s_add_u32 s18, s18, 0x10800
	s_addc_u32 s19, s19, 0
	global_load_dword v165, v172, s[18:19]
	s_add_u32 s18, s18, 0x10800
	s_addc_u32 s19, s19, 0
	global_load_dword v166, v172, s[18:19]
	s_add_u32 s18, s18, 0x10800
	s_addc_u32 s19, s19, 0
	global_load_dword v167, v172, s[18:19]
	s_add_u32 s18, s18, 0x10800
	s_addc_u32 s19, s19, 0
	global_load_dword v168, v172, s[18:19]
	s_add_u32 s18, s18, 0x10800
	s_addc_u32 s19, s19, 0
	global_load_dword v169, v172, s[18:19]
	s_add_u32 s18, s18, 0x10800
	s_addc_u32 s19, s19, 0
	global_load_dword v170, v172, s[18:19]
	s_add_u32 s18, s18, 0x10800
	s_addc_u32 s19, s19, 0
	global_load_dword v171, v172, s[18:19]
	v_lshrrev_b32_e32 v141, 8, v136
	v_and_b32_e32 v142, 15, v136
	v_lshl_add_u32 v141, v141, 6, v142
	v_bfe_u32 v144, v136, 6, 2
	v_bfe_u32 v145, v136, 4, 2
	v_lshlrev_b32_e32 v144, 5, v144
	v_lshl_add_u32 v144, v145, 3, v144
	s_lshl_b32 s24, s99, 8
	v_add_u32_e32 v144, s24, v144
	s_lshl_b32 s25, s98, 8
	v_add_u32_e32 v145, s25, v141
	v_lshl_add_u32 v146, v145, 10, v144
	v_lshlrev_b32_e32 v140, 1, v146
	v_lshlrev_b32_e32 v147, 2, v144
	v_readlane_b32 s18, v253, 3
	v_readlane_b32 s19, v253, 4
	v_readlane_b32 s20, v253, 53
	v_readlane_b32 s21, v253, 54
	s_nop 4
	s_add_u32 s18, s18, 0x1000
	s_addc_u32 s19, s19, 0
	global_load_dwordx4 v[148:151], v147, s[18:19]
	global_load_dwordx4 v[152:155], v147, s[18:19] offset:16
	global_load_dwordx4 v[156:159], v147, s[18:19] offset:512
	global_load_dwordx4 v[160:163], v147, s[18:19] offset:528
	s_add_u32 s22, s20, 0x0
	s_addc_u32 s23, s21, 0
	global_load_dwordx4 v[188:191], v140, s[22:23] nt
	global_load_dwordx4 v[192:195], v140, s[22:23] offset:256 nt
	s_add_u32 s22, s20, 0x8000
	s_addc_u32 s23, s21, 0
	global_load_dwordx4 v[196:199], v140, s[22:23] nt
	global_load_dwordx4 v[200:203], v140, s[22:23] offset:256 nt
	s_add_u32 s22, s20, 0x10000
	s_addc_u32 s23, s21, 0
	global_load_dwordx4 v[204:207], v140, s[22:23] nt
	global_load_dwordx4 v[208:211], v140, s[22:23] offset:256 nt
	s_add_u32 s22, s20, 0x18000
	s_addc_u32 s23, s21, 0
	global_load_dwordx4 v[212:215], v140, s[22:23] nt
	global_load_dwordx4 v[216:219], v140, s[22:23] offset:256 nt
	s_add_u32 s22, s20, 0x40000
	s_addc_u32 s23, s21, 0
	global_load_dwordx4 v[220:223], v140, s[22:23] nt
	global_load_dwordx4 v[224:227], v140, s[22:23] offset:256 nt
	s_add_u32 s22, s20, 0x48000
	s_addc_u32 s23, s21, 0
	global_load_dwordx4 v[228:231], v140, s[22:23] nt
	global_load_dwordx4 v[232:235], v140, s[22:23] offset:256 nt
	s_add_u32 s22, s20, 0x50000
	s_addc_u32 s23, s21, 0
	global_load_dwordx4 v[236:239], v140, s[22:23] nt
	global_load_dwordx4 v[240:243], v140, s[22:23] offset:256 nt
	s_add_u32 s22, s20, 0x58000
	s_addc_u32 s23, s21, 0
	global_load_dwordx4 v[244:247], v140, s[22:23] nt
	global_load_dwordx4 v[248:251], v140, s[22:23] offset:256 nt
	s_waitcnt vmcnt(20)
	v_add_f32_e32 v164, v164, v165
	v_add_f32_e32 v164, v164, v166
	v_add_f32_e32 v164, v164, v167
	v_add_f32_e32 v164, v164, v168
	v_add_f32_e32 v164, v164, v169
	v_add_f32_e32 v164, v164, v170
	v_add_f32_e32 v164, v164, v171
	v_lshlrev_b32_e32 v173, 2, v136
	ds_write_b32 v173, v164
	s_waitcnt lgkmcnt(0)
	s_barrier
	v_lshlrev_b32_e32 v142, 2, v141
	ds_read_b32 v128, v142 offset:0
	ds_read_b32 v174, v142 offset:1024
	ds_read_b32 v129, v142 offset:64
	ds_read_b32 v175, v142 offset:1088
	ds_read_b32 v130, v142 offset:128
	ds_read_b32 v176, v142 offset:1152
	ds_read_b32 v131, v142 offset:192
	ds_read_b32 v177, v142 offset:1216
	ds_read_b32 v132, v142 offset:512
	ds_read_b32 v178, v142 offset:1536
	ds_read_b32 v133, v142 offset:576
	ds_read_b32 v179, v142 offset:1600
	ds_read_b32 v134, v142 offset:640
	ds_read_b32 v180, v142 offset:1664
	ds_read_b32 v135, v142 offset:704
	ds_read_b32 v181, v142 offset:1728
	s_waitcnt lgkmcnt(0)
	s_mov_b32 s101, 0x3a800000
	v_mov_b32_e32 v143, 0x358637bd
	v_add_f32_e32 v128, v128, v174
	v_add_f32_e32 v129, v129, v175
	v_add_f32_e32 v130, v130, v176
	v_add_f32_e32 v131, v131, v177
	v_add_f32_e32 v132, v132, v178
	v_add_f32_e32 v133, v133, v179
	v_add_f32_e32 v134, v134, v180
	v_add_f32_e32 v135, v135, v181
	v_fma_f32 v128, v128, s101, v143
	v_fma_f32 v129, v129, s101, v143
	v_fma_f32 v130, v130, s101, v143
	v_fma_f32 v131, v131, s101, v143
	v_fma_f32 v132, v132, s101, v143
	v_fma_f32 v133, v133, s101, v143
	v_fma_f32 v134, v134, s101, v143
	v_fma_f32 v135, v135, s101, v143
	v_rsq_f32_e32 v128, v128
	v_rsq_f32_e32 v129, v129
	v_rsq_f32_e32 v130, v130
	v_rsq_f32_e32 v131, v131
	v_rsq_f32_e32 v132, v132
	v_rsq_f32_e32 v133, v133
	v_rsq_f32_e32 v134, v134
	v_rsq_f32_e32 v135, v135
	s_waitcnt vmcnt(0)
	s_add_u32 s22, s60, 0x0
	s_addc_u32 s23, s61, 0
	v_lshlrev_b32_e32 v164, 16, v188
	v_and_b32_e32 v165, 0xffff0000, v188
	v_lshlrev_b32_e32 v166, 16, v189
	v_and_b32_e32 v167, 0xffff0000, v189
	v_lshlrev_b32_e32 v168, 16, v190
	v_and_b32_e32 v169, 0xffff0000, v190
	v_lshlrev_b32_e32 v170, 16, v191
	v_and_b32_e32 v171, 0xffff0000, v191
	v_mul_f32_e32 v124, v124, v128
	v_mul_f32_e32 v125, v125, v128
	v_mul_f32_e32 v126, v126, v128
	v_mul_f32_e32 v127, v127, v128
	v_mul_f32_e32 v112, v112, v128
	v_mul_f32_e32 v113, v113, v128
	v_mul_f32_e32 v114, v114, v128
	v_mul_f32_e32 v115, v115, v128
	v_fmac_f32_e32 v164, v124, v148
	v_fmac_f32_e32 v165, v125, v149
	v_fmac_f32_e32 v166, v126, v150
	v_fmac_f32_e32 v167, v127, v151
	v_fmac_f32_e32 v168, v112, v152
	v_fmac_f32_e32 v169, v113, v153
	v_fmac_f32_e32 v170, v114, v154
	v_fmac_f32_e32 v171, v115, v155
	v_mul_f32_e32 v138, v164, v164
	v_fmac_f32_e32 v138, v165, v165
	v_fmac_f32_e32 v138, v166, v166
	v_fmac_f32_e32 v138, v167, v167
	v_fmac_f32_e32 v138, v168, v168
	v_fmac_f32_e32 v138, v169, v169
	v_fmac_f32_e32 v138, v170, v170
	v_fmac_f32_e32 v138, v171, v171
	v_cvt_pk_bf16_f32 v180, v164, v165
	v_cvt_pk_bf16_f32 v181, v166, v167
	v_cvt_pk_bf16_f32 v182, v168, v169
	v_cvt_pk_bf16_f32 v183, v170, v171
	global_store_dwordx4 v140, v[180:183], s[22:23]
	v_lshlrev_b32_e32 v172, 16, v192
	v_and_b32_e32 v173, 0xffff0000, v192
	v_lshlrev_b32_e32 v174, 16, v193
	v_and_b32_e32 v175, 0xffff0000, v193
	v_lshlrev_b32_e32 v176, 16, v194
	v_and_b32_e32 v177, 0xffff0000, v194
	v_lshlrev_b32_e32 v178, 16, v195
	v_and_b32_e32 v179, 0xffff0000, v195
	v_mul_f32_e32 v120, v120, v128
	v_mul_f32_e32 v121, v121, v128
	v_mul_f32_e32 v122, v122, v128
	v_mul_f32_e32 v123, v123, v128
	v_mul_f32_e32 v116, v116, v128
	v_mul_f32_e32 v117, v117, v128
	v_mul_f32_e32 v118, v118, v128
	v_mul_f32_e32 v119, v119, v128
	v_fmac_f32_e32 v172, v120, v156
	v_fmac_f32_e32 v173, v121, v157
	v_fmac_f32_e32 v174, v122, v158
	v_fmac_f32_e32 v175, v123, v159
	v_fmac_f32_e32 v176, v116, v160
	v_fmac_f32_e32 v177, v117, v161
	v_fmac_f32_e32 v178, v118, v162
	v_fmac_f32_e32 v179, v119, v163
	v_fmac_f32_e32 v138, v172, v172
	v_fmac_f32_e32 v138, v173, v173
	v_fmac_f32_e32 v138, v174, v174
	v_fmac_f32_e32 v138, v175, v175
	v_fmac_f32_e32 v138, v176, v176
	v_fmac_f32_e32 v138, v177, v177
	v_fmac_f32_e32 v138, v178, v178
	v_fmac_f32_e32 v138, v179, v179
	v_cvt_pk_bf16_f32 v184, v172, v173
	v_cvt_pk_bf16_f32 v185, v174, v175
	v_cvt_pk_bf16_f32 v186, v176, v177
	v_cvt_pk_bf16_f32 v187, v178, v179
	global_store_dwordx4 v140, v[184:187], s[22:23] offset:256
	s_add_u32 s22, s60, 0x8000
	s_addc_u32 s23, s61, 0
	v_lshlrev_b32_e32 v164, 16, v196
	v_and_b32_e32 v165, 0xffff0000, v196
	v_lshlrev_b32_e32 v166, 16, v197
	v_and_b32_e32 v167, 0xffff0000, v197
	v_lshlrev_b32_e32 v168, 16, v198
	v_and_b32_e32 v169, 0xffff0000, v198
	v_lshlrev_b32_e32 v170, 16, v199
	v_and_b32_e32 v171, 0xffff0000, v199
	v_mul_f32_e32 v108, v108, v129
	v_mul_f32_e32 v109, v109, v129
	v_mul_f32_e32 v110, v110, v129
	v_mul_f32_e32 v111, v111, v129
	v_mul_f32_e32 v96, v96, v129
	v_mul_f32_e32 v97, v97, v129
	v_mul_f32_e32 v98, v98, v129
	v_mul_f32_e32 v99, v99, v129
	v_fmac_f32_e32 v164, v108, v148
	v_fmac_f32_e32 v165, v109, v149
	v_fmac_f32_e32 v166, v110, v150
	v_fmac_f32_e32 v167, v111, v151
	v_fmac_f32_e32 v168, v96, v152
	v_fmac_f32_e32 v169, v97, v153
	v_fmac_f32_e32 v170, v98, v154
	v_fmac_f32_e32 v171, v99, v155
	v_mul_f32_e32 v139, v164, v164
	v_fmac_f32_e32 v139, v165, v165
	v_fmac_f32_e32 v139, v166, v166
	v_fmac_f32_e32 v139, v167, v167
	v_fmac_f32_e32 v139, v168, v168
	v_fmac_f32_e32 v139, v169, v169
	v_fmac_f32_e32 v139, v170, v170
	v_fmac_f32_e32 v139, v171, v171
	v_cvt_pk_bf16_f32 v180, v164, v165
	v_cvt_pk_bf16_f32 v181, v166, v167
	v_cvt_pk_bf16_f32 v182, v168, v169
	v_cvt_pk_bf16_f32 v183, v170, v171
	global_store_dwordx4 v140, v[180:183], s[22:23]
	v_lshlrev_b32_e32 v172, 16, v200
	v_and_b32_e32 v173, 0xffff0000, v200
	v_lshlrev_b32_e32 v174, 16, v201
	v_and_b32_e32 v175, 0xffff0000, v201
	v_lshlrev_b32_e32 v176, 16, v202
	v_and_b32_e32 v177, 0xffff0000, v202
	v_lshlrev_b32_e32 v178, 16, v203
	v_and_b32_e32 v179, 0xffff0000, v203
	v_mul_f32_e32 v100, v100, v129
	v_mul_f32_e32 v101, v101, v129
	v_mul_f32_e32 v102, v102, v129
	v_mul_f32_e32 v103, v103, v129
	v_mul_f32_e32 v104, v104, v129
	v_mul_f32_e32 v105, v105, v129
	v_mul_f32_e32 v106, v106, v129
	v_mul_f32_e32 v107, v107, v129
	v_fmac_f32_e32 v172, v100, v156
	v_fmac_f32_e32 v173, v101, v157
	v_fmac_f32_e32 v174, v102, v158
	v_fmac_f32_e32 v175, v103, v159
	v_fmac_f32_e32 v176, v104, v160
	v_fmac_f32_e32 v177, v105, v161
	v_fmac_f32_e32 v178, v106, v162
	v_fmac_f32_e32 v179, v107, v163
	v_fmac_f32_e32 v139, v172, v172
	v_fmac_f32_e32 v139, v173, v173
	v_fmac_f32_e32 v139, v174, v174
	v_fmac_f32_e32 v139, v175, v175
	v_fmac_f32_e32 v139, v176, v176
	v_fmac_f32_e32 v139, v177, v177
	v_fmac_f32_e32 v139, v178, v178
	v_fmac_f32_e32 v139, v179, v179
	v_cvt_pk_bf16_f32 v184, v172, v173
	v_cvt_pk_bf16_f32 v185, v174, v175
	v_cvt_pk_bf16_f32 v186, v176, v177
	v_cvt_pk_bf16_f32 v187, v178, v179
	global_store_dwordx4 v140, v[184:187], s[22:23] offset:256
	s_add_u32 s22, s60, 0x10000
	s_addc_u32 s23, s61, 0
	v_lshlrev_b32_e32 v164, 16, v204
	v_and_b32_e32 v165, 0xffff0000, v204
	v_lshlrev_b32_e32 v166, 16, v205
	v_and_b32_e32 v167, 0xffff0000, v205
	v_lshlrev_b32_e32 v168, 16, v206
	v_and_b32_e32 v169, 0xffff0000, v206
	v_lshlrev_b32_e32 v170, 16, v207
	v_and_b32_e32 v171, 0xffff0000, v207
	v_mul_f32_e32 v92, v92, v130
	v_mul_f32_e32 v93, v93, v130
	v_mul_f32_e32 v94, v94, v130
	v_mul_f32_e32 v95, v95, v130
	v_mul_f32_e32 v80, v80, v130
	v_mul_f32_e32 v81, v81, v130
	v_mul_f32_e32 v82, v82, v130
	v_mul_f32_e32 v83, v83, v130
	v_fmac_f32_e32 v164, v92, v148
	v_fmac_f32_e32 v165, v93, v149
	v_fmac_f32_e32 v166, v94, v150
	v_fmac_f32_e32 v167, v95, v151
	v_fmac_f32_e32 v168, v80, v152
	v_fmac_f32_e32 v169, v81, v153
	v_fmac_f32_e32 v170, v82, v154
	v_fmac_f32_e32 v171, v83, v155
	v_mul_f32_e32 v141, v164, v164
	v_fmac_f32_e32 v141, v165, v165
	v_fmac_f32_e32 v141, v166, v166
	v_fmac_f32_e32 v141, v167, v167
	v_fmac_f32_e32 v141, v168, v168
	v_fmac_f32_e32 v141, v169, v169
	v_fmac_f32_e32 v141, v170, v170
	v_fmac_f32_e32 v141, v171, v171
	v_cvt_pk_bf16_f32 v180, v164, v165
	v_cvt_pk_bf16_f32 v181, v166, v167
	v_cvt_pk_bf16_f32 v182, v168, v169
	v_cvt_pk_bf16_f32 v183, v170, v171
	global_store_dwordx4 v140, v[180:183], s[22:23]
	v_lshlrev_b32_e32 v172, 16, v208
	v_and_b32_e32 v173, 0xffff0000, v208
	v_lshlrev_b32_e32 v174, 16, v209
	v_and_b32_e32 v175, 0xffff0000, v209
	v_lshlrev_b32_e32 v176, 16, v210
	v_and_b32_e32 v177, 0xffff0000, v210
	v_lshlrev_b32_e32 v178, 16, v211
	v_and_b32_e32 v179, 0xffff0000, v211
	v_mul_f32_e32 v84, v84, v130
	v_mul_f32_e32 v85, v85, v130
	v_mul_f32_e32 v86, v86, v130
	v_mul_f32_e32 v87, v87, v130
	v_mul_f32_e32 v88, v88, v130
	v_mul_f32_e32 v89, v89, v130
	v_mul_f32_e32 v90, v90, v130
	v_mul_f32_e32 v91, v91, v130
	v_fmac_f32_e32 v172, v84, v156
	v_fmac_f32_e32 v173, v85, v157
	v_fmac_f32_e32 v174, v86, v158
	v_fmac_f32_e32 v175, v87, v159
	v_fmac_f32_e32 v176, v88, v160
	v_fmac_f32_e32 v177, v89, v161
	v_fmac_f32_e32 v178, v90, v162
	v_fmac_f32_e32 v179, v91, v163
	v_fmac_f32_e32 v141, v172, v172
	v_fmac_f32_e32 v141, v173, v173
	v_fmac_f32_e32 v141, v174, v174
	v_fmac_f32_e32 v141, v175, v175
	v_fmac_f32_e32 v141, v176, v176
	v_fmac_f32_e32 v141, v177, v177
	v_fmac_f32_e32 v141, v178, v178
	v_fmac_f32_e32 v141, v179, v179
	v_cvt_pk_bf16_f32 v184, v172, v173
	v_cvt_pk_bf16_f32 v185, v174, v175
	v_cvt_pk_bf16_f32 v186, v176, v177
	v_cvt_pk_bf16_f32 v187, v178, v179
	global_store_dwordx4 v140, v[184:187], s[22:23] offset:256
	s_add_u32 s22, s60, 0x18000
	s_addc_u32 s23, s61, 0
	v_lshlrev_b32_e32 v164, 16, v212
	v_and_b32_e32 v165, 0xffff0000, v212
	v_lshlrev_b32_e32 v166, 16, v213
	v_and_b32_e32 v167, 0xffff0000, v213
	v_lshlrev_b32_e32 v168, 16, v214
	v_and_b32_e32 v169, 0xffff0000, v214
	v_lshlrev_b32_e32 v170, 16, v215
	v_and_b32_e32 v171, 0xffff0000, v215
	v_mul_f32_e32 v76, v76, v131
	v_mul_f32_e32 v77, v77, v131
	v_mul_f32_e32 v78, v78, v131
	v_mul_f32_e32 v79, v79, v131
	v_mul_f32_e32 v64, v64, v131
	v_mul_f32_e32 v65, v65, v131
	v_mul_f32_e32 v66, v66, v131
	v_mul_f32_e32 v67, v67, v131
	v_fmac_f32_e32 v164, v76, v148
	v_fmac_f32_e32 v165, v77, v149
	v_fmac_f32_e32 v166, v78, v150
	v_fmac_f32_e32 v167, v79, v151
	v_fmac_f32_e32 v168, v64, v152
	v_fmac_f32_e32 v169, v65, v153
	v_fmac_f32_e32 v170, v66, v154
	v_fmac_f32_e32 v171, v67, v155
	v_mul_f32_e32 v142, v164, v164
	v_fmac_f32_e32 v142, v165, v165
	v_fmac_f32_e32 v142, v166, v166
	v_fmac_f32_e32 v142, v167, v167
	v_fmac_f32_e32 v142, v168, v168
	v_fmac_f32_e32 v142, v169, v169
	v_fmac_f32_e32 v142, v170, v170
	v_fmac_f32_e32 v142, v171, v171
	v_cvt_pk_bf16_f32 v180, v164, v165
	v_cvt_pk_bf16_f32 v181, v166, v167
	v_cvt_pk_bf16_f32 v182, v168, v169
	v_cvt_pk_bf16_f32 v183, v170, v171
	global_store_dwordx4 v140, v[180:183], s[22:23]
	v_lshlrev_b32_e32 v172, 16, v216
	v_and_b32_e32 v173, 0xffff0000, v216
	v_lshlrev_b32_e32 v174, 16, v217
	v_and_b32_e32 v175, 0xffff0000, v217
	v_lshlrev_b32_e32 v176, 16, v218
	v_and_b32_e32 v177, 0xffff0000, v218
	v_lshlrev_b32_e32 v178, 16, v219
	v_and_b32_e32 v179, 0xffff0000, v219
	v_mul_f32_e32 v68, v68, v131
	v_mul_f32_e32 v69, v69, v131
	v_mul_f32_e32 v70, v70, v131
	v_mul_f32_e32 v71, v71, v131
	v_mul_f32_e32 v72, v72, v131
	v_mul_f32_e32 v73, v73, v131
	v_mul_f32_e32 v74, v74, v131
	v_mul_f32_e32 v75, v75, v131
	v_fmac_f32_e32 v172, v68, v156
	v_fmac_f32_e32 v173, v69, v157
	v_fmac_f32_e32 v174, v70, v158
	v_fmac_f32_e32 v175, v71, v159
	v_fmac_f32_e32 v176, v72, v160
	v_fmac_f32_e32 v177, v73, v161
	v_fmac_f32_e32 v178, v74, v162
	v_fmac_f32_e32 v179, v75, v163
	v_fmac_f32_e32 v142, v172, v172
	v_fmac_f32_e32 v142, v173, v173
	v_fmac_f32_e32 v142, v174, v174
	v_fmac_f32_e32 v142, v175, v175
	v_fmac_f32_e32 v142, v176, v176
	v_fmac_f32_e32 v142, v177, v177
	v_fmac_f32_e32 v142, v178, v178
	v_fmac_f32_e32 v142, v179, v179
	v_cvt_pk_bf16_f32 v184, v172, v173
	v_cvt_pk_bf16_f32 v185, v174, v175
	v_cvt_pk_bf16_f32 v186, v176, v177
	v_cvt_pk_bf16_f32 v187, v178, v179
	global_store_dwordx4 v140, v[184:187], s[22:23] offset:256
	s_add_u32 s22, s60, 0x40000
	s_addc_u32 s23, s61, 0
	v_lshlrev_b32_e32 v164, 16, v220
	v_and_b32_e32 v165, 0xffff0000, v220
	v_lshlrev_b32_e32 v166, 16, v221
	v_and_b32_e32 v167, 0xffff0000, v221
	v_lshlrev_b32_e32 v168, 16, v222
	v_and_b32_e32 v169, 0xffff0000, v222
	v_lshlrev_b32_e32 v170, 16, v223
	v_and_b32_e32 v171, 0xffff0000, v223
	v_mul_f32_e32 v60, v60, v132
	v_mul_f32_e32 v61, v61, v132
	v_mul_f32_e32 v62, v62, v132
	v_mul_f32_e32 v63, v63, v132
	v_mul_f32_e32 v48, v48, v132
	v_mul_f32_e32 v49, v49, v132
	v_mul_f32_e32 v50, v50, v132
	v_mul_f32_e32 v51, v51, v132
	v_fmac_f32_e32 v164, v60, v148
	v_fmac_f32_e32 v165, v61, v149
	v_fmac_f32_e32 v166, v62, v150
	v_fmac_f32_e32 v167, v63, v151
	v_fmac_f32_e32 v168, v48, v152
	v_fmac_f32_e32 v169, v49, v153
	v_fmac_f32_e32 v170, v50, v154
	v_fmac_f32_e32 v171, v51, v155
	v_mul_f32_e32 v143, v164, v164
	v_fmac_f32_e32 v143, v165, v165
	v_fmac_f32_e32 v143, v166, v166
	v_fmac_f32_e32 v143, v167, v167
	v_fmac_f32_e32 v143, v168, v168
	v_fmac_f32_e32 v143, v169, v169
	v_fmac_f32_e32 v143, v170, v170
	v_fmac_f32_e32 v143, v171, v171
	v_cvt_pk_bf16_f32 v180, v164, v165
	v_cvt_pk_bf16_f32 v181, v166, v167
	v_cvt_pk_bf16_f32 v182, v168, v169
	v_cvt_pk_bf16_f32 v183, v170, v171
	global_store_dwordx4 v140, v[180:183], s[22:23]
	v_lshlrev_b32_e32 v172, 16, v224
	v_and_b32_e32 v173, 0xffff0000, v224
	v_lshlrev_b32_e32 v174, 16, v225
	v_and_b32_e32 v175, 0xffff0000, v225
	v_lshlrev_b32_e32 v176, 16, v226
	v_and_b32_e32 v177, 0xffff0000, v226
	v_lshlrev_b32_e32 v178, 16, v227
	v_and_b32_e32 v179, 0xffff0000, v227
	v_mul_f32_e32 v52, v52, v132
	v_mul_f32_e32 v53, v53, v132
	v_mul_f32_e32 v54, v54, v132
	v_mul_f32_e32 v55, v55, v132
	v_mul_f32_e32 v56, v56, v132
	v_mul_f32_e32 v57, v57, v132
	v_mul_f32_e32 v58, v58, v132
	v_mul_f32_e32 v59, v59, v132
	v_fmac_f32_e32 v172, v52, v156
	v_fmac_f32_e32 v173, v53, v157
	v_fmac_f32_e32 v174, v54, v158
	v_fmac_f32_e32 v175, v55, v159
	v_fmac_f32_e32 v176, v56, v160
	v_fmac_f32_e32 v177, v57, v161
	v_fmac_f32_e32 v178, v58, v162
	v_fmac_f32_e32 v179, v59, v163
	v_fmac_f32_e32 v143, v172, v172
	v_fmac_f32_e32 v143, v173, v173
	v_fmac_f32_e32 v143, v174, v174
	v_fmac_f32_e32 v143, v175, v175
	v_fmac_f32_e32 v143, v176, v176
	v_fmac_f32_e32 v143, v177, v177
	v_fmac_f32_e32 v143, v178, v178
	v_fmac_f32_e32 v143, v179, v179
	v_cvt_pk_bf16_f32 v184, v172, v173
	v_cvt_pk_bf16_f32 v185, v174, v175
	v_cvt_pk_bf16_f32 v186, v176, v177
	v_cvt_pk_bf16_f32 v187, v178, v179
	global_store_dwordx4 v140, v[184:187], s[22:23] offset:256
	s_add_u32 s22, s60, 0x48000
	s_addc_u32 s23, s61, 0
	v_lshlrev_b32_e32 v164, 16, v228
	v_and_b32_e32 v165, 0xffff0000, v228
	v_lshlrev_b32_e32 v166, 16, v229
	v_and_b32_e32 v167, 0xffff0000, v229
	v_lshlrev_b32_e32 v168, 16, v230
	v_and_b32_e32 v169, 0xffff0000, v230
	v_lshlrev_b32_e32 v170, 16, v231
	v_and_b32_e32 v171, 0xffff0000, v231
	v_mul_f32_e32 v44, v44, v133
	v_mul_f32_e32 v45, v45, v133
	v_mul_f32_e32 v46, v46, v133
	v_mul_f32_e32 v47, v47, v133
	v_mul_f32_e32 v32, v32, v133
	v_mul_f32_e32 v33, v33, v133
	v_mul_f32_e32 v34, v34, v133
	v_mul_f32_e32 v35, v35, v133
	v_fmac_f32_e32 v164, v44, v148
	v_fmac_f32_e32 v165, v45, v149
	v_fmac_f32_e32 v166, v46, v150
	v_fmac_f32_e32 v167, v47, v151
	v_fmac_f32_e32 v168, v32, v152
	v_fmac_f32_e32 v169, v33, v153
	v_fmac_f32_e32 v170, v34, v154
	v_fmac_f32_e32 v171, v35, v155
	v_mul_f32_e32 v144, v164, v164
	v_fmac_f32_e32 v144, v165, v165
	v_fmac_f32_e32 v144, v166, v166
	v_fmac_f32_e32 v144, v167, v167
	v_fmac_f32_e32 v144, v168, v168
	v_fmac_f32_e32 v144, v169, v169
	v_fmac_f32_e32 v144, v170, v170
	v_fmac_f32_e32 v144, v171, v171
	v_cvt_pk_bf16_f32 v180, v164, v165
	v_cvt_pk_bf16_f32 v181, v166, v167
	v_cvt_pk_bf16_f32 v182, v168, v169
	v_cvt_pk_bf16_f32 v183, v170, v171
	global_store_dwordx4 v140, v[180:183], s[22:23]
	v_lshlrev_b32_e32 v172, 16, v232
	v_and_b32_e32 v173, 0xffff0000, v232
	v_lshlrev_b32_e32 v174, 16, v233
	v_and_b32_e32 v175, 0xffff0000, v233
	v_lshlrev_b32_e32 v176, 16, v234
	v_and_b32_e32 v177, 0xffff0000, v234
	v_lshlrev_b32_e32 v178, 16, v235
	v_and_b32_e32 v179, 0xffff0000, v235
	v_mul_f32_e32 v36, v36, v133
	v_mul_f32_e32 v37, v37, v133
	v_mul_f32_e32 v38, v38, v133
	v_mul_f32_e32 v39, v39, v133
	v_mul_f32_e32 v40, v40, v133
	v_mul_f32_e32 v41, v41, v133
	v_mul_f32_e32 v42, v42, v133
	v_mul_f32_e32 v43, v43, v133
	v_fmac_f32_e32 v172, v36, v156
	v_fmac_f32_e32 v173, v37, v157
	v_fmac_f32_e32 v174, v38, v158
	v_fmac_f32_e32 v175, v39, v159
	v_fmac_f32_e32 v176, v40, v160
	v_fmac_f32_e32 v177, v41, v161
	v_fmac_f32_e32 v178, v42, v162
	v_fmac_f32_e32 v179, v43, v163
	v_fmac_f32_e32 v144, v172, v172
	v_fmac_f32_e32 v144, v173, v173
	v_fmac_f32_e32 v144, v174, v174
	v_fmac_f32_e32 v144, v175, v175
	v_fmac_f32_e32 v144, v176, v176
	v_fmac_f32_e32 v144, v177, v177
	v_fmac_f32_e32 v144, v178, v178
	v_fmac_f32_e32 v144, v179, v179
	v_cvt_pk_bf16_f32 v184, v172, v173
	v_cvt_pk_bf16_f32 v185, v174, v175
	v_cvt_pk_bf16_f32 v186, v176, v177
	v_cvt_pk_bf16_f32 v187, v178, v179
	global_store_dwordx4 v140, v[184:187], s[22:23] offset:256
	s_add_u32 s22, s60, 0x50000
	s_addc_u32 s23, s61, 0
	v_lshlrev_b32_e32 v164, 16, v236
	v_and_b32_e32 v165, 0xffff0000, v236
	v_lshlrev_b32_e32 v166, 16, v237
	v_and_b32_e32 v167, 0xffff0000, v237
	v_lshlrev_b32_e32 v168, 16, v238
	v_and_b32_e32 v169, 0xffff0000, v238
	v_lshlrev_b32_e32 v170, 16, v239
	v_and_b32_e32 v171, 0xffff0000, v239
	v_mul_f32_e32 v28, v28, v134
	v_mul_f32_e32 v29, v29, v134
	v_mul_f32_e32 v30, v30, v134
	v_mul_f32_e32 v31, v31, v134
	v_mul_f32_e32 v16, v16, v134
	v_mul_f32_e32 v17, v17, v134
	v_mul_f32_e32 v18, v18, v134
	v_mul_f32_e32 v19, v19, v134
	v_fmac_f32_e32 v164, v28, v148
	v_fmac_f32_e32 v165, v29, v149
	v_fmac_f32_e32 v166, v30, v150
	v_fmac_f32_e32 v167, v31, v151
	v_fmac_f32_e32 v168, v16, v152
	v_fmac_f32_e32 v169, v17, v153
	v_fmac_f32_e32 v170, v18, v154
	v_fmac_f32_e32 v171, v19, v155
	v_mul_f32_e32 v145, v164, v164
	v_fmac_f32_e32 v145, v165, v165
	v_fmac_f32_e32 v145, v166, v166
	v_fmac_f32_e32 v145, v167, v167
	v_fmac_f32_e32 v145, v168, v168
	v_fmac_f32_e32 v145, v169, v169
	v_fmac_f32_e32 v145, v170, v170
	v_fmac_f32_e32 v145, v171, v171
	v_cvt_pk_bf16_f32 v180, v164, v165
	v_cvt_pk_bf16_f32 v181, v166, v167
	v_cvt_pk_bf16_f32 v182, v168, v169
	v_cvt_pk_bf16_f32 v183, v170, v171
	global_store_dwordx4 v140, v[180:183], s[22:23]
	v_lshlrev_b32_e32 v172, 16, v240
	v_and_b32_e32 v173, 0xffff0000, v240
	v_lshlrev_b32_e32 v174, 16, v241
	v_and_b32_e32 v175, 0xffff0000, v241
	v_lshlrev_b32_e32 v176, 16, v242
	v_and_b32_e32 v177, 0xffff0000, v242
	v_lshlrev_b32_e32 v178, 16, v243
	v_and_b32_e32 v179, 0xffff0000, v243
	v_mul_f32_e32 v20, v20, v134
	v_mul_f32_e32 v21, v21, v134
	v_mul_f32_e32 v22, v22, v134
	v_mul_f32_e32 v23, v23, v134
	v_mul_f32_e32 v24, v24, v134
	v_mul_f32_e32 v25, v25, v134
	v_mul_f32_e32 v26, v26, v134
	v_mul_f32_e32 v27, v27, v134
	v_fmac_f32_e32 v172, v20, v156
	v_fmac_f32_e32 v173, v21, v157
	v_fmac_f32_e32 v174, v22, v158
	v_fmac_f32_e32 v175, v23, v159
	v_fmac_f32_e32 v176, v24, v160
	v_fmac_f32_e32 v177, v25, v161
	v_fmac_f32_e32 v178, v26, v162
	v_fmac_f32_e32 v179, v27, v163
	v_fmac_f32_e32 v145, v172, v172
	v_fmac_f32_e32 v145, v173, v173
	v_fmac_f32_e32 v145, v174, v174
	v_fmac_f32_e32 v145, v175, v175
	v_fmac_f32_e32 v145, v176, v176
	v_fmac_f32_e32 v145, v177, v177
	v_fmac_f32_e32 v145, v178, v178
	v_fmac_f32_e32 v145, v179, v179
	v_cvt_pk_bf16_f32 v184, v172, v173
	v_cvt_pk_bf16_f32 v185, v174, v175
	v_cvt_pk_bf16_f32 v186, v176, v177
	v_cvt_pk_bf16_f32 v187, v178, v179
	global_store_dwordx4 v140, v[184:187], s[22:23] offset:256
	s_add_u32 s22, s60, 0x58000
	s_addc_u32 s23, s61, 0
	v_lshlrev_b32_e32 v164, 16, v244
	v_and_b32_e32 v165, 0xffff0000, v244
	v_lshlrev_b32_e32 v166, 16, v245
	v_and_b32_e32 v167, 0xffff0000, v245
	v_lshlrev_b32_e32 v168, 16, v246
	v_and_b32_e32 v169, 0xffff0000, v246
	v_lshlrev_b32_e32 v170, 16, v247
	v_and_b32_e32 v171, 0xffff0000, v247
	v_mul_f32_e32 v12, v12, v135
	v_mul_f32_e32 v13, v13, v135
	v_mul_f32_e32 v14, v14, v135
	v_mul_f32_e32 v15, v15, v135
	v_mul_f32_e32 v0, v0, v135
	v_mul_f32_e32 v1, v1, v135
	v_mul_f32_e32 v2, v2, v135
	v_mul_f32_e32 v3, v3, v135
	v_fmac_f32_e32 v164, v12, v148
	v_fmac_f32_e32 v165, v13, v149
	v_fmac_f32_e32 v166, v14, v150
	v_fmac_f32_e32 v167, v15, v151
	v_fmac_f32_e32 v168, v0, v152
	v_fmac_f32_e32 v169, v1, v153
	v_fmac_f32_e32 v170, v2, v154
	v_fmac_f32_e32 v171, v3, v155
	v_mul_f32_e32 v146, v164, v164
	v_fmac_f32_e32 v146, v165, v165
	v_fmac_f32_e32 v146, v166, v166
	v_fmac_f32_e32 v146, v167, v167
	v_fmac_f32_e32 v146, v168, v168
	v_fmac_f32_e32 v146, v169, v169
	v_fmac_f32_e32 v146, v170, v170
	v_fmac_f32_e32 v146, v171, v171
	v_cvt_pk_bf16_f32 v180, v164, v165
	v_cvt_pk_bf16_f32 v181, v166, v167
	v_cvt_pk_bf16_f32 v182, v168, v169
	v_cvt_pk_bf16_f32 v183, v170, v171
	global_store_dwordx4 v140, v[180:183], s[22:23]
	v_lshlrev_b32_e32 v172, 16, v248
	v_and_b32_e32 v173, 0xffff0000, v248
	v_lshlrev_b32_e32 v174, 16, v249
	v_and_b32_e32 v175, 0xffff0000, v249
	v_lshlrev_b32_e32 v176, 16, v250
	v_and_b32_e32 v177, 0xffff0000, v250
	v_lshlrev_b32_e32 v178, 16, v251
	v_and_b32_e32 v179, 0xffff0000, v251
	v_mul_f32_e32 v4, v4, v135
	v_mul_f32_e32 v5, v5, v135
	v_mul_f32_e32 v6, v6, v135
	v_mul_f32_e32 v7, v7, v135
	v_mul_f32_e32 v8, v8, v135
	v_mul_f32_e32 v9, v9, v135
	v_mul_f32_e32 v10, v10, v135
	v_mul_f32_e32 v11, v11, v135
	v_fmac_f32_e32 v172, v4, v156
	v_fmac_f32_e32 v173, v5, v157
	v_fmac_f32_e32 v174, v6, v158
	v_fmac_f32_e32 v175, v7, v159
	v_fmac_f32_e32 v176, v8, v160
	v_fmac_f32_e32 v177, v9, v161
	v_fmac_f32_e32 v178, v10, v162
	v_fmac_f32_e32 v179, v11, v163
	v_fmac_f32_e32 v146, v172, v172
	v_fmac_f32_e32 v146, v173, v173
	v_fmac_f32_e32 v146, v174, v174
	v_fmac_f32_e32 v146, v175, v175
	v_fmac_f32_e32 v146, v176, v176
	v_fmac_f32_e32 v146, v177, v177
	v_fmac_f32_e32 v146, v178, v178
	v_fmac_f32_e32 v146, v179, v179
	v_cvt_pk_bf16_f32 v184, v172, v173
	v_cvt_pk_bf16_f32 v185, v174, v175
	v_cvt_pk_bf16_f32 v186, v176, v177
	v_cvt_pk_bf16_f32 v187, v178, v179
	global_store_dwordx4 v140, v[184:187], s[22:23] offset:256
	v_mov_b32_e32 v148, v138
	v_mov_b32_e32 v149, v139
	v_mov_b32_e32 v150, v141
	v_mov_b32_e32 v151, v142
	v_mov_b32_e32 v152, v143
	v_mov_b32_e32 v153, v144
	v_mov_b32_e32 v154, v145
	v_mov_b32_e32 v155, v146
	v_xor_b32_e32 v138, 16, v137
	v_xor_b32_e32 v139, 32, v137
	v_lshlrev_b32_e32 v138, 2, v138
	v_lshlrev_b32_e32 v139, 2, v139
	ds_bpermute_b32 v164, v138, v148
	ds_bpermute_b32 v165, v138, v149
	ds_bpermute_b32 v166, v138, v150
	ds_bpermute_b32 v167, v138, v151
	ds_bpermute_b32 v168, v138, v152
	ds_bpermute_b32 v169, v138, v153
	ds_bpermute_b32 v170, v138, v154
	ds_bpermute_b32 v171, v138, v155
	s_waitcnt lgkmcnt(0)
	v_add_f32_e32 v148, v148, v164
	v_add_f32_e32 v149, v149, v165
	v_add_f32_e32 v150, v150, v166
	v_add_f32_e32 v151, v151, v167
	v_add_f32_e32 v152, v152, v168
	v_add_f32_e32 v153, v153, v169
	v_add_f32_e32 v154, v154, v170
	v_add_f32_e32 v155, v155, v171
	ds_bpermute_b32 v164, v139, v148
	ds_bpermute_b32 v165, v139, v149
	ds_bpermute_b32 v166, v139, v150
	ds_bpermute_b32 v167, v139, v151
	ds_bpermute_b32 v168, v139, v152
	ds_bpermute_b32 v169, v139, v153
	ds_bpermute_b32 v170, v139, v154
	ds_bpermute_b32 v171, v139, v155
	s_waitcnt lgkmcnt(0)
	v_add_f32_e32 v148, v148, v164
	v_add_f32_e32 v149, v149, v165
	v_add_f32_e32 v150, v150, v166
	v_add_f32_e32 v151, v151, v167
	v_add_f32_e32 v152, v152, v168
	v_add_f32_e32 v153, v153, v169
	v_add_f32_e32 v154, v154, v170
	v_add_f32_e32 v155, v155, v171
	s_and_b32 s98, s2, 7
	s_lshl_b32 s98, s98, 3
	s_bfe_u32 s99, s2, 0x30003
	s_or_b32 s98, s98, s99
	s_lshr_b32 s99, s2, 6
	s_mul_i32 s99, s99, 0x42000
	s_lshl_b32 s98, s98, 10
	s_add_u32 s100, s56, s99
	s_addc_u32 s101, s57, 0
	s_add_u32 s100, s100, s98
	s_addc_u32 s101, s101, 0
	v_lshrrev_b32_e32 v158, 8, v136
	v_bfe_u32 v159, v136, 6, 2
	v_and_b32_e32 v160, 15, v136
	v_lshl_add_u32 v160, v158, 6, v160
	v_mul_u32_u24_e32 v159, 0x4200, v159
	v_add_u32_e32 v160, v160, v159
	v_lshlrev_b32_e32 v160, 2, v160
	v_bfe_u32 v161, v136, 4, 2
	v_cmp_eq_u32_e32 vcc, 0, v161
	s_and_saveexec_b64 s[0:1], vcc
	global_store_dword v160, v148, s[100:101]
	global_store_dword v160, v149, s[100:101] offset:64
	global_store_dword v160, v150, s[100:101] offset:128
	global_store_dword v160, v151, s[100:101] offset:192
	global_store_dword v160, v152, s[100:101] offset:512
	global_store_dword v160, v153, s[100:101] offset:576
	global_store_dword v160, v154, s[100:101] offset:640
	global_store_dword v160, v155, s[100:101] offset:704
	s_or_b64 exec, exec, s[0:1]
	v_bfe_u32 v183, v136, 1, 2
	v_lshrrev_b32_e32 v187, 6, v136
	v_lshlrev_b32_e32 v190, 11, v136
	v_lshrrev_b32_e32 v252, 1, v136
	v_and_b32_e32 v132, 48, v136
	v_and_b32_e32 v189, 63, v136
	v_lshrrev_b32_e32 v182, 3, v136
	v_lshlrev_b32_e32 v188, 2, v136
	v_lshl_add_u32 v186, v183, 6, 0
	v_and_b32_e32 v191, 15, v136
	s_cmpk_lt_i32 s2, 0x420
	v_mov_b32_e32 v0, v136
	s_cselect_b64 s[8:9], -1, 0
	s_cmpk_gt_i32 s2, 0x41f
	s_cbranch_scc1 .LBB0_863
	v_and_b32_e32 v4, 63, v0
	v_ashrrev_i32_e32 v0, 5, v0
	v_readlane_b32 s12, v253, 3
	v_and_b32_e32 v5, -2, v0
	v_lshlrev_b32_e32 v0, 4, v4
	v_mov_b32_e32 v1, 0
	v_readlane_b32 s13, v253, 4
	s_mov_b64 s[0:1], 0x1000
	v_readlane_b32 s14, v253, 5
	v_lshl_add_u64 v[2:3], s[12:13], 0, v[0:1]
	v_lshl_add_u64 v[16:17], v[2:3], 0, s[0:1]
	v_and_b32_e32 v2, 64, v137
	v_add_u32_e32 v2, 64, v2
	v_xor_b32_e32 v3, 32, v137
	v_cmp_lt_i32_e64 s[0:1], v3, v2
	v_readlane_b32 s15, v253, 6
	v_readlane_b32 s16, v253, 7
	v_cndmask_b32_e64 v3, v137, v3, s[0:1]
	v_lshlrev_b32_e32 v50, 2, v3
	v_xor_b32_e32 v3, 16, v137
	v_cmp_lt_i32_e64 s[0:1], v3, v2
	v_readlane_b32 s17, v253, 8
	v_readlane_b32 s18, v253, 9
	v_cndmask_b32_e64 v3, v137, v3, s[0:1]
	v_lshlrev_b32_e32 v51, 2, v3
	v_xor_b32_e32 v3, 8, v137
	v_cmp_lt_i32_e64 s[0:1], v3, v2
	v_readlane_b32 s19, v253, 10
	v_readlane_b32 s20, v253, 11
	v_cndmask_b32_e64 v3, v137, v3, s[0:1]
	v_lshlrev_b32_e32 v52, 2, v3
	v_xor_b32_e32 v3, 4, v137
	v_cmp_lt_i32_e64 s[0:1], v3, v2
	v_readlane_b32 s21, v253, 12
	v_readlane_b32 s22, v253, 13
	v_cndmask_b32_e64 v3, v137, v3, s[0:1]
	v_lshlrev_b32_e32 v53, 2, v3
	v_xor_b32_e32 v3, 2, v137
	v_cmp_lt_i32_e64 s[0:1], v3, v2
	v_readlane_b32 s23, v253, 14
	v_readlane_b32 s24, v253, 15
	v_cndmask_b32_e64 v3, v137, v3, s[0:1]
	v_readlane_b32 s25, v253, 16
	v_readlane_b32 s26, v253, 17
	v_readlane_b32 s27, v253, 18
	v_mul_u32_u24_e32 v0, 0x4200, v4
	v_lshlrev_b32_e32 v54, 2, v3
	v_xor_b32_e32 v3, 1, v137
	v_cmp_lt_i32_e64 s[0:1], v3, v2
	v_lshlrev_b32_e32 v0, 2, v0
	v_readlane_b32 s12, v253, 51
	v_cndmask_b32_e64 v2, v137, v3, s[0:1]
	v_lshl_add_u64 v[18:19], s[44:45], 0, v[0:1]
	v_lshlrev_b32_e32 v0, 3, v4
	v_readlane_b32 s13, v253, 52
	v_readlane_b32 s14, v253, 53
	v_readlane_b32 s15, v253, 54
	v_cmp_gt_u32_e32 vcc, 16, v4
	v_lshlrev_b32_e32 v55, 2, v2
	v_cmp_eq_u32_e64 s[0:1], 0, v4
	v_lshl_add_u64 v[20:21], s[60:61], 0, v[0:1]
	v_lshl_add_u64 v[22:23], s[14:15], 0, v[0:1]
	v_lshl_add_u64 v[24:25], s[58:59], 0, v[0:1]
	v_lshl_add_u32 v26, s2, 4, v5
	s_lshl_b32 s3, s38, 4
	v_mov_b32_e32 v56, 0x358637bd
	s_mov_b32 s12, 0x800000
	s_mov_b32 s13, s2
	v_readlane_b32 s16, v253, 55
	v_readlane_b32 s17, v253, 56
	v_readlane_b32 s18, v253, 57
	v_readlane_b32 s19, v253, 58
	v_readlane_b32 s20, v253, 59
	v_readlane_b32 s21, v253, 60
	v_readlane_b32 s22, v253, 61
	v_readlane_b32 s23, v253, 62
	v_readlane_b32 s24, v253, 63
	v_readlane_b32 s25, v254, 0
	v_readlane_b32 s26, v254, 1
	v_readlane_b32 s27, v254, 2
	s_addk_i32 s13, 0x400
	v_add_u32_e32 v26, 0x4000, v26
	s_cmpk_lt_i32 s13, 0x420
	s_cbranch_scc0 .LBB0_863
	s_branch .LBB0_855

.LBB0_1172:
	ds_read_b128 v[148:151], v146
	ds_read_b128 v[152:155], v146 offset:1024
	ds_read_b128 v[156:159], v146 offset:2048
	ds_read_b128 v[160:163], v146 offset:3072
	v_lshl_add_u64 v[180:181], v[134:135], 0, s[24:25]
	s_mov_b32 m0, s36
	v_lshl_add_u64 v[184:185], v[180:181], 0, s[10:11]
	ds_read_b128 v[164:167], v144
	ds_read_b128 v[168:171], v144 offset:1024
	ds_read_b128 v[172:175], v144 offset:2048
	ds_read_b128 v[176:179], v144 offset:3072
	ds_read_b128 v[192:195], v144 offset:4096
	ds_read_b128 v[196:199], v144 offset:5120
	ds_read_b128 v[200:203], v144 offset:6144
	ds_read_b128 v[204:207], v144 offset:7168
	global_load_lds_dwordx4 v[184:185], off
	v_lshl_add_u64 v[184:185], v[138:139], 0, s[24:25]
	v_lshl_add_u64 v[208:209], v[184:185], 0, s[10:11]
	s_mov_b32 m0, s26
	s_nop 0
	global_load_lds_dwordx4 v[208:209], off
	s_waitcnt lgkmcnt(8)
	s_barrier
	s_waitcnt lgkmcnt(0)
	s_setprio 1
	s_waitcnt lgkmcnt(0)
	v_mfma_f32_16x16x32_bf16 v[124:127], v[148:151], v[164:167], v[124:127]
	v_mfma_f32_16x16x32_bf16 v[120:123], v[156:159], v[164:167], v[120:123]
	v_mfma_f32_16x16x32_bf16 v[116:119], v[148:151], v[172:175], v[116:119]
	v_mfma_f32_16x16x32_bf16 v[112:115], v[156:159], v[172:175], v[112:115]
	v_mfma_f32_16x16x32_bf16 v[108:111], v[148:151], v[192:195], v[108:111]
	v_mfma_f32_16x16x32_bf16 v[104:107], v[156:159], v[192:195], v[104:107]
	v_mfma_f32_16x16x32_bf16 v[100:103], v[148:151], v[200:203], v[100:103]
	v_mfma_f32_16x16x32_bf16 v[96:99], v[156:159], v[200:203], v[96:99]
	v_mfma_f32_16x16x32_bf16 v[124:127], v[152:155], v[168:171], v[124:127]
	v_mfma_f32_16x16x32_bf16 v[120:123], v[160:163], v[168:171], v[120:123]
	v_mfma_f32_16x16x32_bf16 v[116:119], v[152:155], v[176:179], v[116:119]
	v_mfma_f32_16x16x32_bf16 v[112:115], v[160:163], v[176:179], v[112:115]
	v_mfma_f32_16x16x32_bf16 v[108:111], v[152:155], v[196:199], v[108:111]
	v_mfma_f32_16x16x32_bf16 v[104:107], v[160:163], v[196:199], v[104:107]
	v_mfma_f32_16x16x32_bf16 v[100:103], v[152:155], v[204:207], v[100:103]
	v_mfma_f32_16x16x32_bf16 v[96:99], v[160:163], v[204:207], v[96:99]
	s_setprio 0
	s_barrier
	v_lshl_add_u64 v[224:225], v[140:141], 0, s[24:25]
	s_add_i32 s37, s42, s21
	v_lshl_add_u64 v[226:227], v[224:225], 0, s[12:13]
	s_mov_b32 m0, s37
	ds_read_b128 v[208:211], v147
	ds_read_b128 v[212:215], v147 offset:1024
	ds_read_b128 v[216:219], v147 offset:2048
	ds_read_b128 v[220:223], v147 offset:3072
	global_load_lds_dwordx4 v[226:227], off
	v_lshl_add_u64 v[226:227], v[142:143], 0, s[24:25]
	v_lshl_add_u64 v[228:229], v[226:227], 0, s[12:13]
	s_add_i32 m0, s37, 0x2000
	s_nop 0
	global_load_lds_dwordx4 v[228:229], off
	s_barrier
	s_waitcnt lgkmcnt(0)
	s_setprio 1
	s_waitcnt lgkmcnt(0)
	v_mfma_f32_16x16x32_bf16 v[92:95], v[208:211], v[164:167], v[92:95]
	v_mfma_f32_16x16x32_bf16 v[88:91], v[216:219], v[164:167], v[88:91]
	v_mfma_f32_16x16x32_bf16 v[84:87], v[208:211], v[172:175], v[84:87]
	v_mfma_f32_16x16x32_bf16 v[80:83], v[216:219], v[172:175], v[80:83]
	v_mfma_f32_16x16x32_bf16 v[76:79], v[208:211], v[192:195], v[76:79]
	v_mfma_f32_16x16x32_bf16 v[72:75], v[216:219], v[192:195], v[72:75]
	v_mfma_f32_16x16x32_bf16 v[68:71], v[208:211], v[200:203], v[68:71]
	v_mfma_f32_16x16x32_bf16 v[64:67], v[216:219], v[200:203], v[64:67]
	v_mfma_f32_16x16x32_bf16 v[92:95], v[212:215], v[168:171], v[92:95]
	v_mfma_f32_16x16x32_bf16 v[88:91], v[220:223], v[168:171], v[88:91]
	v_mfma_f32_16x16x32_bf16 v[84:87], v[212:215], v[176:179], v[84:87]
	v_mfma_f32_16x16x32_bf16 v[80:83], v[220:223], v[176:179], v[80:83]
	v_mfma_f32_16x16x32_bf16 v[76:79], v[212:215], v[196:199], v[76:79]
	v_mfma_f32_16x16x32_bf16 v[72:75], v[220:223], v[196:199], v[72:75]
	v_mfma_f32_16x16x32_bf16 v[68:71], v[212:215], v[204:207], v[68:71]
	v_mfma_f32_16x16x32_bf16 v[64:67], v[220:223], v[204:207], v[64:67]
	s_setprio 0
	s_mov_b32 m0, s29
	v_lshl_add_u64 v[228:229], v[180:181], 0, s[12:13]
	s_barrier
	ds_read_b128 v[164:167], v144 offset:16384
	ds_read_b128 v[168:171], v144 offset:17408
	ds_read_b128 v[172:175], v144 offset:18432
	ds_read_b128 v[176:179], v144 offset:19456
	ds_read_b128 v[192:195], v144 offset:20480
	ds_read_b128 v[196:199], v144 offset:21504
	ds_read_b128 v[200:203], v144 offset:22528
	ds_read_b128 v[204:207], v144 offset:23552
	global_load_lds_dwordx4 v[228:229], off
	v_lshl_add_u64 v[228:229], v[184:185], 0, s[12:13]
	s_mov_b32 m0, s30
	s_nop 0
	global_load_lds_dwordx4 v[228:229], off
	s_barrier
	s_waitcnt lgkmcnt(0)
	s_setprio 1
	s_waitcnt lgkmcnt(0)
	v_mfma_f32_16x16x32_bf16 v[60:63], v[148:151], v[164:167], v[60:63]
	v_mfma_f32_16x16x32_bf16 v[56:59], v[156:159], v[164:167], v[56:59]
	v_mfma_f32_16x16x32_bf16 v[52:55], v[148:151], v[172:175], v[52:55]
	v_mfma_f32_16x16x32_bf16 v[48:51], v[156:159], v[172:175], v[48:51]
	v_mfma_f32_16x16x32_bf16 v[44:47], v[148:151], v[192:195], v[44:47]
	v_mfma_f32_16x16x32_bf16 v[40:43], v[156:159], v[192:195], v[40:43]
	v_mfma_f32_16x16x32_bf16 v[36:39], v[148:151], v[200:203], v[36:39]
	v_mfma_f32_16x16x32_bf16 v[32:35], v[156:159], v[200:203], v[32:35]
	v_mfma_f32_16x16x32_bf16 v[60:63], v[152:155], v[168:171], v[60:63]
	v_mfma_f32_16x16x32_bf16 v[56:59], v[160:163], v[168:171], v[56:59]
	v_mfma_f32_16x16x32_bf16 v[52:55], v[152:155], v[176:179], v[52:55]
	v_mfma_f32_16x16x32_bf16 v[48:51], v[160:163], v[176:179], v[48:51]
	v_mfma_f32_16x16x32_bf16 v[44:47], v[152:155], v[196:199], v[44:47]
	v_mfma_f32_16x16x32_bf16 v[40:43], v[160:163], v[196:199], v[40:43]
	v_mfma_f32_16x16x32_bf16 v[36:39], v[152:155], v[204:207], v[36:39]
	v_mfma_f32_16x16x32_bf16 v[32:35], v[160:163], v[204:207], v[32:35]
	s_setprio 0
	s_barrier
	s_add_i32 s37, s43, s21
	v_lshl_add_u64 v[148:149], v[224:225], 0, s[14:15]
	s_mov_b32 m0, s37
	s_nop 0
	global_load_lds_dwordx4 v[148:149], off
	v_lshl_add_u64 v[148:149], v[226:227], 0, s[14:15]
	s_add_i32 m0, s37, 0x2000
	s_nop 0
	global_load_lds_dwordx4 v[148:149], off
	s_waitcnt vmcnt(6)
	s_barrier
	s_setprio 1
	v_mfma_f32_16x16x32_bf16 v[28:31], v[208:211], v[164:167], v[28:31]
	v_mfma_f32_16x16x32_bf16 v[24:27], v[216:219], v[164:167], v[24:27]
	v_mfma_f32_16x16x32_bf16 v[20:23], v[208:211], v[172:175], v[20:23]
	v_mfma_f32_16x16x32_bf16 v[16:19], v[216:219], v[172:175], v[16:19]
	v_mfma_f32_16x16x32_bf16 v[12:15], v[208:211], v[192:195], v[12:15]
	v_mfma_f32_16x16x32_bf16 v[8:11], v[216:219], v[192:195], v[8:11]
	v_mfma_f32_16x16x32_bf16 v[4:7], v[208:211], v[200:203], v[4:7]
	v_mfma_f32_16x16x32_bf16 v[0:3], v[216:219], v[200:203], v[0:3]
	v_mfma_f32_16x16x32_bf16 v[28:31], v[212:215], v[168:171], v[28:31]
	v_mfma_f32_16x16x32_bf16 v[24:27], v[220:223], v[168:171], v[24:27]
	v_mfma_f32_16x16x32_bf16 v[20:23], v[212:215], v[176:179], v[20:23]
	v_mfma_f32_16x16x32_bf16 v[16:19], v[220:223], v[176:179], v[16:19]
	v_mfma_f32_16x16x32_bf16 v[12:15], v[212:215], v[196:199], v[12:15]
	v_mfma_f32_16x16x32_bf16 v[8:11], v[220:223], v[196:199], v[8:11]
	v_mfma_f32_16x16x32_bf16 v[4:7], v[212:215], v[204:207], v[4:7]
	v_mfma_f32_16x16x32_bf16 v[0:3], v[220:223], v[204:207], v[0:3]
	s_setprio 0
	s_add_i32 s37, 0, 0x18000
	v_add_u32_e32 v160, s37, v145
	s_barrier
	ds_read_b128 v[148:151], v160
	ds_read_b128 v[152:155], v160 offset:1024
	ds_read_b128 v[156:159], v160 offset:2048
	ds_read_b128 v[160:163], v160 offset:3072
	s_mov_b32 m0, s31
	v_lshl_add_u64 v[208:209], v[180:181], 0, s[14:15]
	ds_read_b128 v[164:167], v144 offset:32768
	ds_read_b128 v[168:171], v144 offset:33792
	ds_read_b128 v[172:175], v144 offset:34816
	ds_read_b128 v[176:179], v144 offset:35840
	ds_read_b128 v[192:195], v144 offset:36864
	ds_read_b128 v[196:199], v144 offset:37888
	ds_read_b128 v[200:203], v144 offset:38912
	ds_read_b128 v[204:207], v144 offset:39936
	global_load_lds_dwordx4 v[208:209], off
	v_lshl_add_u64 v[208:209], v[184:185], 0, s[14:15]
	s_mov_b32 m0, s33
	s_nop 0
	global_load_lds_dwordx4 v[208:209], off
	s_waitcnt lgkmcnt(8)
	s_barrier
	s_waitcnt lgkmcnt(0)
	s_setprio 1
	s_waitcnt lgkmcnt(0)
	v_mfma_f32_16x16x32_bf16 v[124:127], v[148:151], v[164:167], v[124:127]
	v_mfma_f32_16x16x32_bf16 v[120:123], v[156:159], v[164:167], v[120:123]
	v_mfma_f32_16x16x32_bf16 v[116:119], v[148:151], v[172:175], v[116:119]
	v_mfma_f32_16x16x32_bf16 v[112:115], v[156:159], v[172:175], v[112:115]
	v_mfma_f32_16x16x32_bf16 v[108:111], v[148:151], v[192:195], v[108:111]
	v_mfma_f32_16x16x32_bf16 v[104:107], v[156:159], v[192:195], v[104:107]
	v_mfma_f32_16x16x32_bf16 v[100:103], v[148:151], v[200:203], v[100:103]
	v_mfma_f32_16x16x32_bf16 v[96:99], v[156:159], v[200:203], v[96:99]
	v_mfma_f32_16x16x32_bf16 v[124:127], v[152:155], v[168:171], v[124:127]
	v_mfma_f32_16x16x32_bf16 v[120:123], v[160:163], v[168:171], v[120:123]
	v_mfma_f32_16x16x32_bf16 v[116:119], v[152:155], v[176:179], v[116:119]
	v_mfma_f32_16x16x32_bf16 v[112:115], v[160:163], v[176:179], v[112:115]
	v_mfma_f32_16x16x32_bf16 v[108:111], v[152:155], v[196:199], v[108:111]
	v_mfma_f32_16x16x32_bf16 v[104:107], v[160:163], v[196:199], v[104:107]
	v_mfma_f32_16x16x32_bf16 v[100:103], v[152:155], v[204:207], v[100:103]
	v_mfma_f32_16x16x32_bf16 v[96:99], v[160:163], v[204:207], v[96:99]
	s_setprio 0
	s_barrier
	s_add_i32 s40, 0, 0x1c000
	s_add_i32 s37, s37, s21
	v_add_u32_e32 v190, s40, v145
	v_lshl_add_u64 v[228:229], v[224:225], 0, s[16:17]
	s_mov_b32 m0, s37
	ds_read_b128 v[208:211], v190
	ds_read_b128 v[212:215], v190 offset:1024
	ds_read_b128 v[216:219], v190 offset:2048
	ds_read_b128 v[220:223], v190 offset:3072
	global_load_lds_dwordx4 v[228:229], off
	v_lshl_add_u64 v[228:229], v[226:227], 0, s[16:17]
	s_add_i32 m0, s37, 0x2000
	s_nop 0
	global_load_lds_dwordx4 v[228:229], off
	s_barrier
	s_waitcnt lgkmcnt(0)
	s_setprio 1
	s_waitcnt lgkmcnt(0)
	v_mfma_f32_16x16x32_bf16 v[92:95], v[208:211], v[164:167], v[92:95]
	v_mfma_f32_16x16x32_bf16 v[88:91], v[216:219], v[164:167], v[88:91]
	v_mfma_f32_16x16x32_bf16 v[84:87], v[208:211], v[172:175], v[84:87]
	v_mfma_f32_16x16x32_bf16 v[80:83], v[216:219], v[172:175], v[80:83]
	v_mfma_f32_16x16x32_bf16 v[76:79], v[208:211], v[192:195], v[76:79]
	v_mfma_f32_16x16x32_bf16 v[72:75], v[216:219], v[192:195], v[72:75]
	v_mfma_f32_16x16x32_bf16 v[68:71], v[208:211], v[200:203], v[68:71]
	v_mfma_f32_16x16x32_bf16 v[64:67], v[216:219], v[200:203], v[64:67]
	v_mfma_f32_16x16x32_bf16 v[92:95], v[212:215], v[168:171], v[92:95]
	v_mfma_f32_16x16x32_bf16 v[88:91], v[220:223], v[168:171], v[88:91]
	v_mfma_f32_16x16x32_bf16 v[84:87], v[212:215], v[176:179], v[84:87]
	v_mfma_f32_16x16x32_bf16 v[80:83], v[220:223], v[176:179], v[80:83]
	v_mfma_f32_16x16x32_bf16 v[76:79], v[212:215], v[196:199], v[76:79]
	v_mfma_f32_16x16x32_bf16 v[72:75], v[220:223], v[196:199], v[72:75]
	v_mfma_f32_16x16x32_bf16 v[68:71], v[212:215], v[204:207], v[68:71]
	v_mfma_f32_16x16x32_bf16 v[64:67], v[220:223], v[204:207], v[64:67]
	s_setprio 0
	s_mov_b32 m0, s34
	v_lshl_add_u64 v[180:181], v[180:181], 0, s[16:17]
	s_barrier
	ds_read_b128 v[164:167], v144 offset:49152
	ds_read_b128 v[168:171], v144 offset:50176
	ds_read_b128 v[172:175], v144 offset:51200
	ds_read_b128 v[176:179], v144 offset:52224
	ds_read_b128 v[192:195], v144 offset:53248
	ds_read_b128 v[196:199], v144 offset:54272
	ds_read_b128 v[200:203], v144 offset:55296
	ds_read_b128 v[204:207], v144 offset:56320
	global_load_lds_dwordx4 v[180:181], off
	v_lshl_add_u64 v[180:181], v[184:185], 0, s[16:17]
	s_mov_b32 m0, s35
	s_nop 0
	global_load_lds_dwordx4 v[180:181], off
	s_barrier
	s_waitcnt lgkmcnt(0)
	s_setprio 1
	s_waitcnt lgkmcnt(0)
	v_mfma_f32_16x16x32_bf16 v[60:63], v[148:151], v[164:167], v[60:63]
	v_mfma_f32_16x16x32_bf16 v[56:59], v[156:159], v[164:167], v[56:59]
	v_mfma_f32_16x16x32_bf16 v[52:55], v[148:151], v[172:175], v[52:55]
	v_mfma_f32_16x16x32_bf16 v[48:51], v[156:159], v[172:175], v[48:51]
	v_mfma_f32_16x16x32_bf16 v[44:47], v[148:151], v[192:195], v[44:47]
	v_mfma_f32_16x16x32_bf16 v[40:43], v[156:159], v[192:195], v[40:43]
	v_mfma_f32_16x16x32_bf16 v[36:39], v[148:151], v[200:203], v[36:39]
	v_mfma_f32_16x16x32_bf16 v[32:35], v[156:159], v[200:203], v[32:35]
	v_mfma_f32_16x16x32_bf16 v[60:63], v[152:155], v[168:171], v[60:63]
	v_mfma_f32_16x16x32_bf16 v[56:59], v[160:163], v[168:171], v[56:59]
	v_mfma_f32_16x16x32_bf16 v[52:55], v[152:155], v[176:179], v[52:55]
	v_mfma_f32_16x16x32_bf16 v[48:51], v[160:163], v[176:179], v[48:51]
	v_mfma_f32_16x16x32_bf16 v[44:47], v[152:155], v[196:199], v[44:47]
	v_mfma_f32_16x16x32_bf16 v[40:43], v[160:163], v[196:199], v[40:43]
	v_mfma_f32_16x16x32_bf16 v[36:39], v[152:155], v[204:207], v[36:39]
	v_mfma_f32_16x16x32_bf16 v[32:35], v[160:163], v[204:207], v[32:35]
	s_setprio 0
	s_barrier
	s_add_i32 s37, s40, s21
	v_lshl_add_u64 v[148:149], v[224:225], 0, s[18:19]
	s_mov_b32 m0, s37
	s_nop 0
	global_load_lds_dwordx4 v[148:149], off
	v_lshl_add_u64 v[148:149], v[226:227], 0, s[18:19]
	s_add_i32 m0, s37, 0x2000
	s_nop 0
	global_load_lds_dwordx4 v[148:149], off
	s_waitcnt vmcnt(6)
	s_barrier
	s_setprio 1
	v_mfma_f32_16x16x32_bf16 v[28:31], v[208:211], v[164:167], v[28:31]
	v_mfma_f32_16x16x32_bf16 v[24:27], v[216:219], v[164:167], v[24:27]
	v_mfma_f32_16x16x32_bf16 v[20:23], v[208:211], v[172:175], v[20:23]
	v_mfma_f32_16x16x32_bf16 v[16:19], v[216:219], v[172:175], v[16:19]
	v_mfma_f32_16x16x32_bf16 v[12:15], v[208:211], v[192:195], v[12:15]
	v_mfma_f32_16x16x32_bf16 v[8:11], v[216:219], v[192:195], v[8:11]
	v_mfma_f32_16x16x32_bf16 v[4:7], v[208:211], v[200:203], v[4:7]
	v_mfma_f32_16x16x32_bf16 v[0:3], v[216:219], v[200:203], v[0:3]
	v_mfma_f32_16x16x32_bf16 v[28:31], v[212:215], v[168:171], v[28:31]
	v_mfma_f32_16x16x32_bf16 v[24:27], v[220:223], v[168:171], v[24:27]
	v_mfma_f32_16x16x32_bf16 v[20:23], v[212:215], v[176:179], v[20:23]
	v_mfma_f32_16x16x32_bf16 v[16:19], v[220:223], v[176:179], v[16:19]
	v_mfma_f32_16x16x32_bf16 v[12:15], v[212:215], v[196:199], v[12:15]
	v_mfma_f32_16x16x32_bf16 v[8:11], v[220:223], v[196:199], v[8:11]
	v_mfma_f32_16x16x32_bf16 v[4:7], v[212:215], v[204:207], v[4:7]
	v_mfma_f32_16x16x32_bf16 v[0:3], v[220:223], v[204:207], v[0:3]
	s_setprio 0
	s_add_i32 s27, s27, 2
	s_add_u32 s24, s24, 0x100
	s_addc_u32 s25, s25, 0
	s_cmp_gt_u32 s27, 11
	s_barrier
	s_cbranch_scc0 .LBB0_1172
	v_add_u32_e32 v142, 0, v145
	s_add_u32 s22, s22, 0x40780
	v_add_u32_e32 v134, 0x10000, v142
	s_addc_u32 s23, s23, 0
	s_mov_b32 m0, s36
	ds_read_b128 v[138:141], v134
	ds_read_b128 v[146:149], v134 offset:1024
	ds_read_b128 v[150:153], v134 offset:2048
	ds_read_b128 v[154:157], v134 offset:3072
	ds_read_b128 v[158:161], v144
	ds_read_b128 v[162:165], v144 offset:1024
	ds_read_b128 v[166:169], v144 offset:2048
	ds_read_b128 v[170:173], v144 offset:3072
	ds_read_b128 v[174:177], v144 offset:4096
	ds_read_b128 v[178:181], v144 offset:5120
	ds_read_b128 v[192:195], v144 offset:6144
	ds_read_b128 v[196:199], v144 offset:7168
	v_lshl_add_u64 v[134:135], s[22:23], 0, v[128:129]
	global_load_lds_dwordx4 v[134:135], off
	v_lshl_add_u64 v[130:131], s[22:23], 0, v[130:131]
	s_mov_b32 m0, s26
	s_nop 0
	global_load_lds_dwordx4 v[130:131], off
	s_barrier
	s_waitcnt lgkmcnt(0)
	s_setprio 1
	s_waitcnt lgkmcnt(0)
	v_mfma_f32_16x16x32_bf16 v[124:127], v[138:141], v[158:161], v[124:127]
	v_mfma_f32_16x16x32_bf16 v[120:123], v[150:153], v[158:161], v[120:123]
	v_mfma_f32_16x16x32_bf16 v[116:119], v[138:141], v[166:169], v[116:119]
	v_mfma_f32_16x16x32_bf16 v[104:107], v[150:153], v[174:177], v[104:107]
	v_mfma_f32_16x16x32_bf16 v[100:103], v[138:141], v[192:195], v[100:103]
	v_mfma_f32_16x16x32_bf16 v[124:127], v[146:149], v[162:165], v[124:127]
	v_mfma_f32_16x16x32_bf16 v[120:123], v[154:157], v[162:165], v[120:123]
	v_mfma_f32_16x16x32_bf16 v[116:119], v[146:149], v[170:173], v[116:119]
	v_mfma_f32_16x16x32_bf16 v[112:115], v[150:153], v[166:169], v[112:115]
	v_mfma_f32_16x16x32_bf16 v[108:111], v[138:141], v[174:177], v[108:111]
	v_mfma_f32_16x16x32_bf16 v[104:107], v[154:157], v[178:181], v[104:107]
	v_mfma_f32_16x16x32_bf16 v[100:103], v[146:149], v[196:199], v[100:103]
	v_mfma_f32_16x16x32_bf16 v[96:99], v[150:153], v[192:195], v[96:99]
	v_mfma_f32_16x16x32_bf16 v[200:203], v[154:157], v[170:173], v[112:115]
	v_mfma_f32_16x16x32_bf16 v[204:207], v[146:149], v[178:181], v[108:111]
	v_mfma_f32_16x16x32_bf16 v[208:211], v[154:157], v[196:199], v[96:99]
	s_setprio 0
	v_add_u32_e32 v128, 0x14000, v142
	s_barrier
	s_nop 1
	ds_read_b128 v[96:99], v128
	ds_read_b128 v[108:111], v128 offset:1024
	ds_read_b128 v[112:115], v128 offset:2048
	ds_read_b128 v[212:215], v128 offset:3072
	s_barrier
	s_waitcnt lgkmcnt(0)
	s_setprio 1
	s_waitcnt lgkmcnt(0)
	v_mfma_f32_16x16x32_bf16 v[88:91], v[112:115], v[158:161], v[88:91]
	v_mfma_f32_16x16x32_bf16 v[84:87], v[96:99], v[166:169], v[84:87]
	v_mfma_f32_16x16x32_bf16 v[72:75], v[112:115], v[174:177], v[72:75]
	v_mfma_f32_16x16x32_bf16 v[68:71], v[96:99], v[192:195], v[68:71]
	v_mfma_f32_16x16x32_bf16 v[92:95], v[96:99], v[158:161], v[92:95]
	v_mfma_f32_16x16x32_bf16 v[88:91], v[212:215], v[162:165], v[88:91]
	v_mfma_f32_16x16x32_bf16 v[84:87], v[108:111], v[170:173], v[84:87]
	v_mfma_f32_16x16x32_bf16 v[80:83], v[112:115], v[166:169], v[80:83]
	v_mfma_f32_16x16x32_bf16 v[76:79], v[96:99], v[174:177], v[76:79]
	v_mfma_f32_16x16x32_bf16 v[72:75], v[212:215], v[178:181], v[72:75]
	v_mfma_f32_16x16x32_bf16 v[68:71], v[108:111], v[196:199], v[68:71]
	v_mfma_f32_16x16x32_bf16 v[64:67], v[112:115], v[192:195], v[64:67]
	v_mfma_f32_16x16x32_bf16 v[216:219], v[108:111], v[162:165], v[92:95]
	v_mfma_f32_16x16x32_bf16 v[158:161], v[212:215], v[170:173], v[80:83]
	v_mfma_f32_16x16x32_bf16 v[162:165], v[108:111], v[178:181], v[76:79]
	v_mfma_f32_16x16x32_bf16 v[166:169], v[212:215], v[196:199], v[64:67]
	s_setprio 0
	s_barrier
	s_nop 1
	ds_read_b128 v[64:67], v144 offset:16384
	ds_read_b128 v[76:79], v144 offset:17408
	ds_read_b128 v[80:83], v144 offset:18432
	ds_read_b128 v[92:95], v144 offset:19456
	ds_read_b128 v[170:173], v144 offset:20480
	ds_read_b128 v[174:177], v144 offset:21504
	ds_read_b128 v[178:181], v144 offset:22528
	ds_read_b128 v[192:195], v144 offset:23552
	s_waitcnt vmcnt(4)
	s_barrier
	s_waitcnt lgkmcnt(0)
	s_setprio 1
	s_waitcnt lgkmcnt(0)
	v_mfma_f32_16x16x32_bf16 v[60:63], v[138:141], v[64:67], v[60:63]
	v_mfma_f32_16x16x32_bf16 v[56:59], v[150:153], v[64:67], v[56:59]
	v_mfma_f32_16x16x32_bf16 v[52:55], v[138:141], v[80:83], v[52:55]
	v_mfma_f32_16x16x32_bf16 v[40:43], v[150:153], v[170:173], v[40:43]
	v_mfma_f32_16x16x32_bf16 v[36:39], v[138:141], v[178:181], v[36:39]
	v_mfma_f32_16x16x32_bf16 v[60:63], v[146:149], v[76:79], v[60:63]
	v_mfma_f32_16x16x32_bf16 v[56:59], v[154:157], v[76:79], v[56:59]
	v_mfma_f32_16x16x32_bf16 v[52:55], v[146:149], v[92:95], v[52:55]
	v_mfma_f32_16x16x32_bf16 v[48:51], v[150:153], v[80:83], v[48:51]
	v_mfma_f32_16x16x32_bf16 v[44:47], v[138:141], v[170:173], v[44:47]
	v_mfma_f32_16x16x32_bf16 v[40:43], v[154:157], v[174:177], v[40:43]
	v_mfma_f32_16x16x32_bf16 v[36:39], v[146:149], v[192:195], v[36:39]
	v_mfma_f32_16x16x32_bf16 v[32:35], v[150:153], v[178:181], v[32:35]
	v_mfma_f32_16x16x32_bf16 v[196:199], v[154:157], v[92:95], v[48:51]
	v_mfma_f32_16x16x32_bf16 v[220:223], v[146:149], v[174:177], v[44:47]
	v_mfma_f32_16x16x32_bf16 v[138:141], v[154:157], v[192:195], v[32:35]
	s_setprio 0
	s_setprio 1
	v_mfma_f32_16x16x32_bf16 v[24:27], v[112:115], v[64:67], v[24:27]
	v_mfma_f32_16x16x32_bf16 v[20:23], v[96:99], v[80:83], v[20:23]
	v_mfma_f32_16x16x32_bf16 v[8:11], v[112:115], v[170:173], v[8:11]
	v_mfma_f32_16x16x32_bf16 v[4:7], v[96:99], v[178:181], v[4:7]
	v_mfma_f32_16x16x32_bf16 v[28:31], v[96:99], v[64:67], v[28:31]
	v_mfma_f32_16x16x32_bf16 v[24:27], v[212:215], v[76:79], v[24:27]
	v_mfma_f32_16x16x32_bf16 v[20:23], v[108:111], v[92:95], v[20:23]
	v_mfma_f32_16x16x32_bf16 v[16:19], v[112:115], v[80:83], v[16:19]
	v_mfma_f32_16x16x32_bf16 v[12:15], v[96:99], v[170:173], v[12:15]
	v_mfma_f32_16x16x32_bf16 v[8:11], v[212:215], v[174:177], v[8:11]
	v_mfma_f32_16x16x32_bf16 v[4:7], v[108:111], v[192:195], v[4:7]
	v_mfma_f32_16x16x32_bf16 v[0:3], v[112:115], v[178:181], v[0:3]
	v_mfma_f32_16x16x32_bf16 v[146:149], v[108:111], v[76:79], v[28:31]
	v_mfma_f32_16x16x32_bf16 v[150:153], v[212:215], v[92:95], v[16:19]
	v_mfma_f32_16x16x32_bf16 v[154:157], v[108:111], v[174:177], v[12:15]
	v_mfma_f32_16x16x32_bf16 v[170:173], v[212:215], v[192:195], v[0:3]
	s_setprio 0
	v_add_u32_e32 v16, 0x18000, v142
	s_barrier
	s_nop 0
	ds_read_b128 v[0:3], v16
	ds_read_b128 v[12:15], v16 offset:1024
	ds_read_b128 v[174:177], v16 offset:2048
	ds_read_b128 v[178:181], v16 offset:3072
	ds_read_b128 v[16:19], v144 offset:32768
	ds_read_b128 v[28:31], v144 offset:33792
	ds_read_b128 v[32:35], v144 offset:34816
	ds_read_b128 v[44:47], v144 offset:35840
	ds_read_b128 v[48:51], v144 offset:36864
	ds_read_b128 v[192:195], v144 offset:37888
	ds_read_b128 v[212:215], v144 offset:38912
	ds_read_b128 v[224:227], v144 offset:39936
	s_waitcnt vmcnt(2)
	s_barrier
	s_waitcnt lgkmcnt(0)
	s_setprio 1
	s_waitcnt lgkmcnt(0)
	v_mfma_f32_16x16x32_bf16 v[64:67], v[0:3], v[16:19], v[124:127]
	v_mfma_f32_16x16x32_bf16 v[124:127], v[12:15], v[28:31], v[64:67]
	v_mfma_f32_16x16x32_bf16 v[64:67], v[174:177], v[16:19], v[120:123]
	v_mfma_f32_16x16x32_bf16 v[112:115], v[178:181], v[28:31], v[64:67]
	v_mfma_f32_16x16x32_bf16 v[64:67], v[0:3], v[32:35], v[116:119]
	v_mfma_f32_16x16x32_bf16 v[108:111], v[12:15], v[44:47], v[64:67]
	v_mfma_f32_16x16x32_bf16 v[64:67], v[174:177], v[32:35], v[200:203]
	v_mfma_f32_16x16x32_bf16 v[96:99], v[178:181], v[44:47], v[64:67]
	v_mfma_f32_16x16x32_bf16 v[64:67], v[0:3], v[48:51], v[204:207]
	v_mfma_f32_16x16x32_bf16 v[92:95], v[12:15], v[192:195], v[64:67]
	v_mfma_f32_16x16x32_bf16 v[64:67], v[174:177], v[48:51], v[104:107]
	v_mfma_f32_16x16x32_bf16 v[80:83], v[178:181], v[192:195], v[64:67]
	v_mfma_f32_16x16x32_bf16 v[64:67], v[0:3], v[212:215], v[100:103]
	v_mfma_f32_16x16x32_bf16 v[76:79], v[12:15], v[224:227], v[64:67]
	v_mfma_f32_16x16x32_bf16 v[64:67], v[174:177], v[212:215], v[208:211]
	v_mfma_f32_16x16x32_bf16 v[64:67], v[178:181], v[224:227], v[64:67]
	s_setprio 0
	v_add_u32_e32 v100, 0x1c000, v142
	s_barrier
	ds_read_b128 v[200:203], v100
	ds_read_b128 v[204:207], v100 offset:1024
	ds_read_b128 v[208:211], v100 offset:2048
	ds_read_b128 v[228:231], v100 offset:3072
	s_waitcnt vmcnt(0)
	s_barrier
	s_waitcnt lgkmcnt(0)
	s_setprio 1
	s_waitcnt lgkmcnt(0)
	v_mfma_f32_16x16x32_bf16 v[100:103], v[200:203], v[16:19], v[216:219]
	v_mfma_f32_16x16x32_bf16 v[16:19], v[208:211], v[16:19], v[88:91]
	v_mfma_f32_16x16x32_bf16 v[116:119], v[228:231], v[28:31], v[16:19]
	v_mfma_f32_16x16x32_bf16 v[16:19], v[200:203], v[32:35], v[84:87]
	v_mfma_f32_16x16x32_bf16 v[120:123], v[204:207], v[28:31], v[100:103]
	v_mfma_f32_16x16x32_bf16 v[100:103], v[204:207], v[44:47], v[16:19]
	v_mfma_f32_16x16x32_bf16 v[16:19], v[208:211], v[32:35], v[158:161]
	v_mfma_f32_16x16x32_bf16 v[104:107], v[228:231], v[44:47], v[16:19]
	v_mfma_f32_16x16x32_bf16 v[16:19], v[200:203], v[48:51], v[162:165]
	v_mfma_f32_16x16x32_bf16 v[84:87], v[204:207], v[192:195], v[16:19]
	v_mfma_f32_16x16x32_bf16 v[16:19], v[208:211], v[48:51], v[72:75]
	v_mfma_f32_16x16x32_bf16 v[88:91], v[228:231], v[192:195], v[16:19]
	v_mfma_f32_16x16x32_bf16 v[16:19], v[200:203], v[212:215], v[68:71]
	v_mfma_f32_16x16x32_bf16 v[68:71], v[204:207], v[224:227], v[16:19]
	v_mfma_f32_16x16x32_bf16 v[16:19], v[208:211], v[212:215], v[166:169]
	v_mfma_f32_16x16x32_bf16 v[72:75], v[228:231], v[224:227], v[16:19]
	s_setprio 0
	s_barrier
	ds_read_b128 v[158:161], v144 offset:49152
	ds_read_b128 v[162:165], v144 offset:50176
	ds_read_b128 v[166:169], v144 offset:51200
	ds_read_b128 v[192:195], v144 offset:52224
	ds_read_b128 v[212:215], v144 offset:53248
	ds_read_b128 v[216:219], v144 offset:54272
	ds_read_b128 v[224:227], v144 offset:55296
	ds_read_b128 v[142:145], v144 offset:56320
	s_barrier
	s_waitcnt lgkmcnt(0)
	s_setprio 1
	s_waitcnt lgkmcnt(0)
	v_mfma_f32_16x16x32_bf16 v[16:19], v[0:3], v[158:161], v[60:63]
	v_mfma_f32_16x16x32_bf16 v[60:63], v[12:15], v[162:165], v[16:19]
	v_mfma_f32_16x16x32_bf16 v[16:19], v[174:177], v[158:161], v[56:59]
	v_mfma_f32_16x16x32_bf16 v[48:51], v[178:181], v[162:165], v[16:19]
	v_mfma_f32_16x16x32_bf16 v[16:19], v[0:3], v[166:169], v[52:55]
	v_mfma_f32_16x16x32_bf16 v[44:47], v[12:15], v[192:195], v[16:19]
	v_mfma_f32_16x16x32_bf16 v[16:19], v[174:177], v[166:169], v[196:199]
	v_mfma_f32_16x16x32_bf16 v[32:35], v[178:181], v[192:195], v[16:19]
	v_mfma_f32_16x16x32_bf16 v[16:19], v[0:3], v[212:215], v[220:223]
	v_mfma_f32_16x16x32_bf16 v[0:3], v[0:3], v[224:227], v[36:39]
	v_mfma_f32_16x16x32_bf16 v[28:31], v[12:15], v[216:219], v[16:19]
	v_mfma_f32_16x16x32_bf16 v[16:19], v[174:177], v[212:215], v[40:43]
	v_mfma_f32_16x16x32_bf16 v[12:15], v[12:15], v[142:145], v[0:3]
	v_mfma_f32_16x16x32_bf16 v[0:3], v[174:177], v[224:227], v[138:141]
	v_mfma_f32_16x16x32_bf16 v[16:19], v[178:181], v[216:219], v[16:19]
	v_mfma_f32_16x16x32_bf16 v[0:3], v[178:181], v[142:145], v[0:3]
	s_setprio 0
	s_setprio 1
	v_mfma_f32_16x16x32_bf16 v[36:39], v[200:203], v[158:161], v[146:149]
	v_mfma_f32_16x16x32_bf16 v[20:23], v[200:203], v[166:169], v[20:23]
	v_mfma_f32_16x16x32_bf16 v[52:55], v[204:207], v[162:165], v[36:39]
	v_mfma_f32_16x16x32_bf16 v[24:27], v[208:211], v[158:161], v[24:27]
	v_mfma_f32_16x16x32_bf16 v[36:39], v[204:207], v[192:195], v[20:23]
	v_mfma_f32_16x16x32_bf16 v[20:23], v[208:211], v[166:169], v[150:153]
	v_mfma_f32_16x16x32_bf16 v[8:11], v[208:211], v[212:215], v[8:11]
	v_mfma_f32_16x16x32_bf16 v[56:59], v[228:231], v[162:165], v[24:27]
	v_mfma_f32_16x16x32_bf16 v[40:43], v[228:231], v[192:195], v[20:23]
	v_mfma_f32_16x16x32_bf16 v[20:23], v[200:203], v[212:215], v[154:157]
	v_mfma_f32_16x16x32_bf16 v[24:27], v[228:231], v[216:219], v[8:11]
	v_mfma_f32_16x16x32_bf16 v[4:7], v[200:203], v[224:227], v[4:7]
	v_mfma_f32_16x16x32_bf16 v[8:11], v[208:211], v[224:227], v[170:173]
	v_mfma_f32_16x16x32_bf16 v[20:23], v[204:207], v[216:219], v[20:23]
	v_mfma_f32_16x16x32_bf16 v[4:7], v[204:207], v[142:145], v[4:7]
	v_mfma_f32_16x16x32_bf16 v[8:11], v[228:231], v[142:145], v[8:11]
	s_setprio 0
	s_cmpk_lt_u32 s1, 0x100
	s_barrier
	s_cbranch_scc0 .LBB0_1175
	s_barrier
.LBB0_1175:
	s_nop 7
	v_xor_b32_e32 v138, 16, v137
	v_xor_b32_e32 v139, 32, v137
	v_lshlrev_b32_e32 v138, 2, v138
	v_lshlrev_b32_e32 v139, 2, v139
	v_mul_f32_e32 v140, v124, v124
	v_mul_f32_e32 v141, v108, v108
	v_mul_f32_e32 v142, v92, v92
	v_mul_f32_e32 v143, v76, v76
	v_mul_f32_e32 v144, v60, v60
	v_mul_f32_e32 v145, v44, v44
	v_mul_f32_e32 v146, v28, v28
	v_mul_f32_e32 v147, v12, v12
	v_fmac_f32_e32 v140, v125, v125
	v_fmac_f32_e32 v141, v109, v109
	v_fmac_f32_e32 v142, v93, v93
	v_fmac_f32_e32 v143, v77, v77
	v_fmac_f32_e32 v144, v61, v61
	v_fmac_f32_e32 v145, v45, v45
	v_fmac_f32_e32 v146, v29, v29
	v_fmac_f32_e32 v147, v13, v13
	v_fmac_f32_e32 v140, v126, v126
	v_fmac_f32_e32 v141, v110, v110
	v_fmac_f32_e32 v142, v94, v94
	v_fmac_f32_e32 v143, v78, v78
	v_fmac_f32_e32 v144, v62, v62
	v_fmac_f32_e32 v145, v46, v46
	v_fmac_f32_e32 v146, v30, v30
	v_fmac_f32_e32 v147, v14, v14
	v_fmac_f32_e32 v140, v127, v127
	v_fmac_f32_e32 v141, v111, v111
	v_fmac_f32_e32 v142, v95, v95
	v_fmac_f32_e32 v143, v79, v79
	v_fmac_f32_e32 v144, v63, v63
	v_fmac_f32_e32 v145, v47, v47
	v_fmac_f32_e32 v146, v31, v31
	v_fmac_f32_e32 v147, v15, v15
	v_fmac_f32_e32 v140, v112, v112
	v_fmac_f32_e32 v141, v96, v96
	v_fmac_f32_e32 v142, v80, v80
	v_fmac_f32_e32 v143, v64, v64
	v_fmac_f32_e32 v144, v48, v48
	v_fmac_f32_e32 v145, v32, v32
	v_fmac_f32_e32 v146, v16, v16
	v_fmac_f32_e32 v147, v0, v0
	v_fmac_f32_e32 v140, v113, v113
	v_fmac_f32_e32 v141, v97, v97
	v_fmac_f32_e32 v142, v81, v81
	v_fmac_f32_e32 v143, v65, v65
	v_fmac_f32_e32 v144, v49, v49
	v_fmac_f32_e32 v145, v33, v33
	v_fmac_f32_e32 v146, v17, v17
	v_fmac_f32_e32 v147, v1, v1
	v_fmac_f32_e32 v140, v114, v114
	v_fmac_f32_e32 v141, v98, v98
	v_fmac_f32_e32 v142, v82, v82
	v_fmac_f32_e32 v143, v66, v66
	v_fmac_f32_e32 v144, v50, v50
	v_fmac_f32_e32 v145, v34, v34
	v_fmac_f32_e32 v146, v18, v18
	v_fmac_f32_e32 v147, v2, v2
	v_fmac_f32_e32 v140, v115, v115
	v_fmac_f32_e32 v141, v99, v99
	v_fmac_f32_e32 v142, v83, v83
	v_fmac_f32_e32 v143, v67, v67
	v_fmac_f32_e32 v144, v51, v51
	v_fmac_f32_e32 v145, v35, v35
	v_fmac_f32_e32 v146, v19, v19
	v_fmac_f32_e32 v147, v3, v3
	v_fmac_f32_e32 v140, v120, v120
	v_fmac_f32_e32 v141, v100, v100
	v_fmac_f32_e32 v142, v84, v84
	v_fmac_f32_e32 v143, v68, v68
	v_fmac_f32_e32 v144, v52, v52
	v_fmac_f32_e32 v145, v36, v36
	v_fmac_f32_e32 v146, v20, v20
	v_fmac_f32_e32 v147, v4, v4
	v_fmac_f32_e32 v140, v121, v121
	v_fmac_f32_e32 v141, v101, v101
	v_fmac_f32_e32 v142, v85, v85
	v_fmac_f32_e32 v143, v69, v69
	v_fmac_f32_e32 v144, v53, v53
	v_fmac_f32_e32 v145, v37, v37
	v_fmac_f32_e32 v146, v21, v21
	v_fmac_f32_e32 v147, v5, v5
	v_fmac_f32_e32 v140, v122, v122
	v_fmac_f32_e32 v141, v102, v102
	v_fmac_f32_e32 v142, v86, v86
	v_fmac_f32_e32 v143, v70, v70
	v_fmac_f32_e32 v144, v54, v54
	v_fmac_f32_e32 v145, v38, v38
	v_fmac_f32_e32 v146, v22, v22
	v_fmac_f32_e32 v147, v6, v6
	v_fmac_f32_e32 v140, v123, v123
	v_fmac_f32_e32 v141, v103, v103
	v_fmac_f32_e32 v142, v87, v87
	v_fmac_f32_e32 v143, v71, v71
	v_fmac_f32_e32 v144, v55, v55
	v_fmac_f32_e32 v145, v39, v39
	v_fmac_f32_e32 v146, v23, v23
	v_fmac_f32_e32 v147, v7, v7
	v_fmac_f32_e32 v140, v116, v116
	v_fmac_f32_e32 v141, v104, v104
	v_fmac_f32_e32 v142, v88, v88
	v_fmac_f32_e32 v143, v72, v72
	v_fmac_f32_e32 v144, v56, v56
	v_fmac_f32_e32 v145, v40, v40
	v_fmac_f32_e32 v146, v24, v24
	v_fmac_f32_e32 v147, v8, v8
	v_fmac_f32_e32 v140, v117, v117
	v_fmac_f32_e32 v141, v105, v105
	v_fmac_f32_e32 v142, v89, v89
	v_fmac_f32_e32 v143, v73, v73
	v_fmac_f32_e32 v144, v57, v57
	v_fmac_f32_e32 v145, v41, v41
	v_fmac_f32_e32 v146, v25, v25
	v_fmac_f32_e32 v147, v9, v9
	v_fmac_f32_e32 v140, v118, v118
	v_fmac_f32_e32 v141, v106, v106
	v_fmac_f32_e32 v142, v90, v90
	v_fmac_f32_e32 v143, v74, v74
	v_fmac_f32_e32 v144, v58, v58
	v_fmac_f32_e32 v145, v42, v42
	v_fmac_f32_e32 v146, v26, v26
	v_fmac_f32_e32 v147, v10, v10
	v_fmac_f32_e32 v140, v119, v119
	v_fmac_f32_e32 v141, v107, v107
	v_fmac_f32_e32 v142, v91, v91
	v_fmac_f32_e32 v143, v75, v75
	v_fmac_f32_e32 v144, v59, v59
	v_fmac_f32_e32 v145, v43, v43
	v_fmac_f32_e32 v146, v27, v27
	v_fmac_f32_e32 v147, v11, v11
	ds_bpermute_b32 v148, v138, v140
	ds_bpermute_b32 v149, v138, v141
	ds_bpermute_b32 v150, v138, v142
	ds_bpermute_b32 v151, v138, v143
	ds_bpermute_b32 v152, v138, v144
	ds_bpermute_b32 v153, v138, v145
	ds_bpermute_b32 v154, v138, v146
	ds_bpermute_b32 v155, v138, v147
	s_waitcnt lgkmcnt(0)
	v_add_f32_e32 v140, v140, v148
	v_add_f32_e32 v141, v141, v149
	v_add_f32_e32 v142, v142, v150
	v_add_f32_e32 v143, v143, v151
	v_add_f32_e32 v144, v144, v152
	v_add_f32_e32 v145, v145, v153
	v_add_f32_e32 v146, v146, v154
	v_add_f32_e32 v147, v147, v155
	ds_bpermute_b32 v148, v139, v140
	ds_bpermute_b32 v149, v139, v141
	ds_bpermute_b32 v150, v139, v142
	ds_bpermute_b32 v151, v139, v143
	ds_bpermute_b32 v152, v139, v144
	ds_bpermute_b32 v153, v139, v145
	ds_bpermute_b32 v154, v139, v146
	ds_bpermute_b32 v155, v139, v147
	s_waitcnt lgkmcnt(0)
	v_add_f32_e32 v140, v140, v148
	v_add_f32_e32 v141, v141, v149
	v_add_f32_e32 v142, v142, v150
	v_add_f32_e32 v143, v143, v151
	v_add_f32_e32 v144, v144, v152
	v_add_f32_e32 v145, v145, v153
	v_add_f32_e32 v146, v146, v154
	v_add_f32_e32 v147, v147, v155
	s_and_b32 s98, s2, 7
	s_lshl_b32 s98, s98, 3
	s_bfe_u32 s99, s2, 0x30003
	s_or_b32 s98, s98, s99
	s_lshr_b32 s99, s2, 6
	s_mul_i32 s99, s99, 0x42000
	s_lshl_b32 s98, s98, 10
	s_add_u32 s100, s44, s99
	s_addc_u32 s101, s45, 0
	s_add_u32 s100, s100, s98
	s_addc_u32 s101, s101, 0
	v_lshrrev_b32_e32 v158, 8, v136
	v_bfe_u32 v159, v136, 6, 2
	v_and_b32_e32 v160, 15, v136
	v_lshl_add_u32 v160, v158, 6, v160
	v_mul_u32_u24_e32 v159, 0x4200, v159
	v_add_u32_e32 v160, v160, v159
	v_lshlrev_b32_e32 v160, 2, v160
	v_bfe_u32 v161, v136, 4, 2
	v_cmp_eq_u32_e32 vcc, 0, v161
	s_and_saveexec_b64 s[0:1], vcc
	global_store_dword v160, v140, s[100:101]
	global_store_dword v160, v141, s[100:101] offset:64
	global_store_dword v160, v142, s[100:101] offset:128
	global_store_dword v160, v143, s[100:101] offset:192
	global_store_dword v160, v144, s[100:101] offset:512
	global_store_dword v160, v145, s[100:101] offset:576
	global_store_dword v160, v146, s[100:101] offset:640
	global_store_dword v160, v147, s[100:101] offset:704
	s_or_b64 exec, exec, s[0:1]
	s_branch .LBB0_1167
.LBB0_1191:
	s_waitcnt vmcnt(0)
	s_waitcnt vmcnt(0) lgkmcnt(0)
	s_barrier
	s_mov_b64 s[0:1], exec
	v_readlane_b32 s6, v253, 1
	v_readlane_b32 s7, v253, 2
	v_readlane_b32 s64, v254, 20
	s_and_b64 s[6:7], s[0:1], s[6:7]
	v_readlane_b32 s65, v254, 21
	v_readlane_b32 s66, v254, 22
	v_readlane_b32 s67, v254, 23
	v_readlane_b32 s68, v254, 24
	v_readlane_b32 s69, v254, 25
	v_readlane_b32 s70, v254, 26
	v_readlane_b32 s71, v254, 27
	v_readlane_b32 s72, v254, 28
	v_readlane_b32 s73, v254, 29
	v_readlane_b32 s74, v254, 30
	v_readlane_b32 s75, v254, 31
	v_readlane_b32 s76, v254, 32
	v_readlane_b32 s77, v254, 33
	v_readlane_b32 s78, v254, 34
	v_readlane_b32 s79, v254, 35
	s_mov_b64 exec, s[6:7]
	s_cbranch_execz .LBB0_1243
	s_add_i32 s3, 0, 0x20000
	v_mov_b32_e32 v140, s3
	s_waitcnt vmcnt(0) expcnt(0) lgkmcnt(0)
	ds_read_b32 v142, v140
	s_add_i32 s3, 0, 0x20004
	v_mov_b32_e32 v140, s3
	ds_read_b32 v140, v140
	s_waitcnt lgkmcnt(1)
	v_cmp_ne_u32_e32 vcc, 0, v142
	s_cbranch_vccnz .LBB0_1207
	s_add_u32 s6, s54, 0x1000
	s_addc_u32 s7, s55, 0
	s_add_u32 s10, s54, 0x1100
	s_addc_u32 s11, s55, 0
	s_add_u32 s12, s54, 0x1200
	v_readlane_b32 s3, v253, 0
	s_addc_u32 s13, s55, 0
	s_mul_i32 s3, s39, s3
	s_add_u32 s14, s54, 0x1300
	s_mul_i32 s3, s3, s38
	s_addc_u32 s15, s55, 0
	s_mov_b32 s22, 1
	v_mov_b32_e32 v156, 0
	s_branch .LBB0_1195

.LBB0_1195:
	global_load_dword v155, v156, s[54:55] offset:1024 sc1
	s_waitcnt lgkmcnt(0)
	global_load_dword v140, v156, s[54:55] offset:1280 sc1
	global_load_dword v141, v156, s[54:55] offset:1536 sc1
	global_load_dword v142, v156, s[54:55] offset:1792 sc1
	global_load_dword v143, v156, s[54:55] offset:2048 sc1
	global_load_dword v144, v156, s[54:55] offset:2304 sc1
	global_load_dword v145, v156, s[54:55] offset:2560 sc1
	global_load_dword v146, v156, s[54:55] offset:2816 sc1
	global_load_dword v147, v156, s[54:55] offset:3072 sc1
	global_load_dword v148, v156, s[54:55] offset:3328 sc1
	global_load_dword v149, v156, s[54:55] offset:3584 sc1
	global_load_dword v150, v156, s[54:55] offset:3840 sc1
	global_load_dword v151, v156, s[6:7] sc1
	global_load_dword v152, v156, s[10:11] sc1
	global_load_dword v153, v156, s[12:13] sc1
	global_load_dword v154, v156, s[14:15] sc1
	s_mov_b64 s[16:17], -1
	s_mov_b64 s[18:19], -1
	s_waitcnt vmcnt(14)
	v_add_u32_e32 v157, v140, v155
	s_waitcnt vmcnt(13)
	v_add_u32_e32 v157, v157, v141
	s_waitcnt vmcnt(12)
	v_add_u32_e32 v157, v157, v142
	s_waitcnt vmcnt(11)
	v_add_u32_e32 v157, v157, v143
	s_waitcnt vmcnt(10)
	v_add_u32_e32 v157, v157, v144
	s_waitcnt vmcnt(9)
	v_add_u32_e32 v157, v157, v145
	s_waitcnt vmcnt(8)
	v_add_u32_e32 v157, v157, v146
	s_waitcnt vmcnt(7)
	v_add_u32_e32 v157, v157, v147
	s_waitcnt vmcnt(6)
	v_add_u32_e32 v157, v157, v148
	s_waitcnt vmcnt(5)
	v_add_u32_e32 v157, v157, v149
	s_waitcnt vmcnt(4)
	v_add_u32_e32 v157, v157, v150
	s_waitcnt vmcnt(3)
	v_add_u32_e32 v157, v157, v151
	s_waitcnt vmcnt(2)
	v_add_u32_e32 v157, v157, v152
	s_waitcnt vmcnt(1)
	v_add_u32_e32 v157, v157, v153
	s_waitcnt vmcnt(0)
	v_add_u32_e32 v157, v157, v154
	v_cmp_eq_u32_e32 vcc, s3, v157
	s_cbranch_vccnz .LBB0_1194
	s_and_b32 s16, s22, 0xff
	s_cmp_eq_u32 s16, 0
	s_mov_b64 s[16:17], -1
	s_mov_b64 s[20:21], -1
	s_sleep 1
	s_cbranch_scc1 .LBB0_1199
	s_and_b64 vcc, exec, s[20:21]
	s_cbranch_vccz .LBB0_1194
.LBB0_1198:
	s_add_i32 s22, s22, 1
	s_mov_b64 s[18:19], 0
	s_branch .LBB0_1194
.LBB0_1199:
	global_load_dword v157, v156, s[54:55] offset:512 sc1
	s_waitcnt vmcnt(0)
	v_cmp_eq_u32_e32 vcc, 0, v157
	s_cbranch_vccnz .LBB0_1201
	s_branch .LBB0_1194
.LBB0_1201:
	s_cmp_lt_u32 s22, 0x40001
	s_mov_b64 s[16:17], 0
	s_cselect_b64 s[20:21], -1, 0
	s_and_b64 vcc, exec, s[20:21]
	s_cbranch_vccnz .LBB0_1198
	s_branch .LBB0_1194
.LBB0_1202:
	s_andn2_b64 vcc, exec, s[16:17]
	s_cbranch_vccz .LBB0_1206
	s_mov_b64 s[10:11], exec
	v_mbcnt_lo_u32_b32 v156, s10, 0
	v_mbcnt_hi_u32_b32 v156, s11, v156
	v_cmp_eq_u32_e32 vcc, 0, v156
	s_and_saveexec_b64 s[6:7], vcc
	s_cbranch_execz .LBB0_1205
	s_bcnt1_i32_b64 s3, s[10:11]
	v_mov_b32_e32 v156, 0
	v_mov_b32_e32 v157, s3
	global_atomic_add v156, v157, s[54:55] offset:512
.LBB0_1205:
	s_or_b64 exec, exec, s[6:7]
.LBB0_1206:
	v_readlane_b32 s3, v254, 3
	s_cmp_eq_u32 s3, 0
	s_cselect_b64 vcc, -1, 0
	s_cmp_eq_u32 s3, 1
	v_cndmask_b32_e32 v156, 0, v155, vcc
	s_cselect_b64 vcc, -1, 0
	s_cmp_eq_u32 s3, 2
	v_cndmask_b32_e32 v156, v156, v140, vcc
	s_cselect_b64 vcc, -1, 0
	s_cmp_eq_u32 s3, 3
	v_cndmask_b32_e32 v156, v156, v141, vcc
	s_cselect_b64 vcc, -1, 0
	s_cmp_eq_u32 s3, 4
	v_cndmask_b32_e32 v156, v156, v142, vcc
	s_cselect_b64 vcc, -1, 0
	s_cmp_eq_u32 s3, 5
	v_cndmask_b32_e32 v156, v156, v143, vcc
	s_cselect_b64 vcc, -1, 0
	s_cmp_eq_u32 s3, 6
	v_cndmask_b32_e32 v156, v156, v144, vcc
	s_cselect_b64 vcc, -1, 0
	s_cmp_eq_u32 s3, 7
	v_cndmask_b32_e32 v156, v156, v145, vcc
	s_cselect_b64 vcc, -1, 0
	s_cmp_eq_u32 s3, 8
	v_cndmask_b32_e32 v156, v156, v146, vcc
	s_cselect_b64 vcc, -1, 0
	s_cmp_eq_u32 s3, 9
	v_cndmask_b32_e32 v156, v156, v147, vcc
	s_cselect_b64 vcc, -1, 0
	s_cmp_eq_u32 s3, 10
	v_cndmask_b32_e32 v156, v156, v148, vcc
	s_cselect_b64 vcc, -1, 0
	s_cmp_eq_u32 s3, 11
	v_cndmask_b32_e32 v156, v156, v149, vcc
	s_cselect_b64 vcc, -1, 0
	s_cmp_eq_u32 s3, 12
	v_cndmask_b32_e32 v156, v156, v150, vcc
	s_cselect_b64 vcc, -1, 0
	s_cmp_eq_u32 s3, 13
	v_cndmask_b32_e32 v156, v156, v151, vcc
	s_cselect_b64 vcc, -1, 0
	s_cmp_eq_u32 s3, 14
	v_cndmask_b32_e32 v156, v156, v152, vcc
	s_cselect_b64 vcc, -1, 0
	s_cmp_eq_u32 s3, 15
	v_cndmask_b32_e32 v156, v156, v153, vcc
	s_cselect_b64 vcc, -1, 0
	v_cndmask_b32_e32 v156, v156, v154, vcc
	v_cmp_ne_u32_e32 vcc, 0, v155
	s_add_i32 s3, 0, 0x20000
	s_nop 0
	v_cndmask_b32_e64 v155, 0, 1, vcc
	v_cmp_ne_u32_e32 vcc, 0, v140
	s_nop 1
	v_addc_co_u32_e32 v140, vcc, 0, v155, vcc
	v_cmp_ne_u32_e32 vcc, 0, v141
	s_nop 1
	v_cndmask_b32_e64 v141, 0, 1, vcc
	v_cmp_ne_u32_e32 vcc, 0, v142
	v_max_u32_e32 v142, 1, v156
	s_nop 0
	v_addc_co_u32_e32 v140, vcc, v140, v141, vcc
	v_cmp_ne_u32_e32 vcc, 0, v143
	s_nop 1
	v_cndmask_b32_e64 v141, 0, 1, vcc
	v_cmp_ne_u32_e32 vcc, 0, v144
	s_nop 1
	v_addc_co_u32_e32 v140, vcc, v140, v141, vcc
	v_cmp_ne_u32_e32 vcc, 0, v145
	s_nop 1
	v_cndmask_b32_e64 v141, 0, 1, vcc
	v_cmp_ne_u32_e32 vcc, 0, v146
	s_nop 1
	v_addc_co_u32_e32 v140, vcc, v140, v141, vcc
	v_cmp_ne_u32_e32 vcc, 0, v147
	s_nop 1
	v_cndmask_b32_e64 v141, 0, 1, vcc
	v_cmp_ne_u32_e32 vcc, 0, v148
	s_nop 1
	v_addc_co_u32_e32 v140, vcc, v140, v141, vcc
	v_cmp_ne_u32_e32 vcc, 0, v149
	s_nop 1
	v_cndmask_b32_e64 v141, 0, 1, vcc
	v_cmp_ne_u32_e32 vcc, 0, v150
	s_nop 1
	v_addc_co_u32_e32 v140, vcc, v140, v141, vcc
	v_cmp_ne_u32_e32 vcc, 0, v151
	s_nop 1
	v_cndmask_b32_e64 v141, 0, 1, vcc
	v_cmp_ne_u32_e32 vcc, 0, v152
	s_nop 1
	v_addc_co_u32_e32 v140, vcc, v140, v141, vcc
	v_cmp_ne_u32_e32 vcc, 0, v153
	s_nop 1
	v_cndmask_b32_e64 v141, 0, 1, vcc
	v_cmp_ne_u32_e32 vcc, 0, v154
	s_nop 1
	v_addc_co_u32_e32 v140, vcc, v140, v141, vcc
	v_mov_b32_e32 v141, s3
	s_add_i32 s3, 0, 0x20004
	v_max_u32_e32 v140, 1, v140
	ds_write_b32 v141, v142
	v_mov_b32_e32 v141, s3
	ds_write_b32 v141, v140
.LBB0_1207:
	s_mov_b64 s[10:11], exec
	v_readlane_b32 s3, v254, 3
	s_lshl_b32 s3, s3, 8
	v_mbcnt_lo_u32_b32 v141, s10, 0
	s_add_u32 s6, s54, s3
	v_mbcnt_hi_u32_b32 v141, s11, v141
	s_addc_u32 s7, s55, 0
	v_cmp_eq_u32_e32 vcc, 0, v141
	s_and_saveexec_b64 s[12:13], vcc
	s_cbranch_execz .LBB0_1209
	s_bcnt1_i32_b64 s3, s[10:11]
	v_mov_b32_e32 v143, 0x1000
	v_mov_b32_e32 v144, s3
	global_atomic_add v143, v143, v144, s[6:7] offset:1024 sc0
.LBB0_1209:
	s_or_b64 exec, exec, s[12:13]
	v_cvt_f32_u32_e32 v144, v142
	s_waitcnt vmcnt(0)
	v_readfirstlane_b32 s3, v143
	v_sub_u32_e32 v143, 0, v142
	v_rcp_iflag_f32_e32 v144, v144
	v_add_u32_e32 v145, s3, v141
	v_mul_f32_e32 v144, 0x4f7ffffe, v144
	v_cvt_u32_f32_e32 v144, v144
	v_mul_lo_u32 v141, v143, v144
	v_mul_hi_u32 v141, v144, v141
	v_add_u32_e32 v141, v144, v141
	v_mul_hi_u32 v141, v145, v141
	v_mul_lo_u32 v143, v141, v142
	v_sub_u32_e32 v143, v145, v143
	v_add_u32_e32 v144, 1, v141
	v_cmp_ge_u32_e32 vcc, v143, v142
	s_nop 1
	v_cndmask_b32_e32 v141, v141, v144, vcc
	v_sub_u32_e32 v144, v143, v142
	v_cndmask_b32_e32 v143, v143, v144, vcc
	v_add_u32_e32 v144, 1, v141
	v_cmp_ge_u32_e32 vcc, v143, v142
	v_add_u32_e32 v143, 1, v145
	s_nop 0
	v_cndmask_b32_e32 v141, v141, v144, vcc
	v_mul_lo_u32 v144, v142, v141
	v_add_u32_e32 v142, v144, v142
	v_cmp_ne_u32_e32 vcc, v143, v142
	s_and_saveexec_b64 s[10:11], vcc
	s_xor_b64 s[10:11], exec, s[10:11]
	s_cbranch_execz .LBB0_1223
	s_waitcnt lgkmcnt(0)
	v_mov_b32_e32 v140, 0x2000
	global_load_dword v140, v140, s[6:7] offset:1024 sc1
	s_add_u32 s14, s6, 0x2400
	s_addc_u32 s15, s7, 0
	s_waitcnt vmcnt(0)
	v_cmp_eq_u32_e32 vcc, v140, v141
	s_and_saveexec_b64 s[12:13], vcc
	s_cbranch_execz .LBB0_1222
	s_mov_b32 s3, 1
	s_mov_b64 s[16:17], 0
	v_mov_b32_e32 v140, 0
	s_branch .LBB0_1213

.LBB0_1215:
	global_load_dword v142, v140, s[14:15] sc1
	s_add_i32 s3, s3, 1
	s_mov_b64 s[22:23], -1
	s_waitcnt vmcnt(0)
	v_cmp_ne_u32_e32 vcc, v142, v141
	s_orn2_b64 s[20:21], vcc, exec
	s_branch .LBB0_1212
.LBB0_1216:
	global_load_dword v142, v140, s[54:55] offset:512 sc1
	s_waitcnt vmcnt(0)
	v_cmp_eq_u32_e32 vcc, 0, v142
	s_cbranch_vccnz .LBB0_1218
	s_mov_b64 s[22:23], -1
	s_branch .LBB0_1212

.LBB0_1219:
	s_or_b64 exec, exec, s[16:17]
	s_xor_b64 s[14:15], s[18:19], -1
	s_and_saveexec_b64 s[16:17], s[14:15]
	s_xor_b64 s[16:17], exec, s[16:17]
	s_cbranch_execz .LBB0_1222
	s_mov_b64 s[14:15], exec
	v_mbcnt_lo_u32_b32 v140, s14, 0
	v_mbcnt_hi_u32_b32 v140, s15, v140
	v_cmp_eq_u32_e32 vcc, 0, v140
	s_and_b64 s[16:17], exec, vcc
	s_mov_b64 exec, s[16:17]
	s_cbranch_execz .LBB0_1222
	s_bcnt1_i32_b64 s3, s[14:15]
	v_mov_b32_e32 v140, 0
	v_mov_b32_e32 v141, s3
	global_atomic_add v140, v141, s[54:55] offset:512

.LBB0_1223:
	s_andn2_saveexec_b64 s[10:11], s[10:11]
	s_cbranch_execz .LBB0_1243
	s_mov_b64 s[10:11], exec
	buffer_wbl2 sc1
	s_waitcnt lgkmcnt(0)
	s_waitcnt vmcnt(0)
	v_mbcnt_lo_u32_b32 v141, s10, 0
	v_mbcnt_hi_u32_b32 v141, s11, v141
	v_cmp_eq_u32_e32 vcc, 0, v141
	s_and_saveexec_b64 s[12:13], vcc
	s_cbranch_execz .LBB0_1226
	s_bcnt1_i32_b64 s3, s[10:11]
	v_mov_b32_e32 v142, 0x3000
	v_mov_b32_e32 v143, s3
	global_atomic_add v142, v142, v143, s[54:55] offset:1024 sc0
.LBB0_1226:
	s_or_b64 exec, exec, s[12:13]
	v_cvt_f32_u32_e32 v143, v140
	s_waitcnt vmcnt(0)
	v_readfirstlane_b32 s3, v142
	s_add_u32 s12, s54, 0x3500
	s_addc_u32 s13, s55, 0
	v_rcp_iflag_f32_e32 v143, v143
	v_add_u32_e32 v141, s3, v141
	v_add_u32_e32 v144, 1, v141
	s_mov_b64 s[14:15], -1
	v_mul_f32_e32 v142, 0x4f7ffffe, v143
	v_cvt_u32_f32_e32 v142, v142
	v_sub_u32_e32 v143, 0, v140
	v_mul_lo_u32 v143, v143, v142
	v_mul_hi_u32 v143, v142, v143
	v_add_u32_e32 v142, v142, v143
	v_mul_hi_u32 v142, v141, v142
	v_mul_lo_u32 v143, v142, v140
	v_sub_u32_e32 v141, v141, v143
	v_add_u32_e32 v145, 1, v142
	v_cmp_ge_u32_e32 vcc, v141, v140
	v_sub_u32_e32 v143, v141, v140
	s_nop 0
	v_cndmask_b32_e32 v142, v142, v145, vcc
	v_cndmask_b32_e32 v141, v141, v143, vcc
	v_add_u32_e32 v143, 1, v142
	v_cmp_ge_u32_e32 vcc, v141, v140
	s_nop 1
	v_cndmask_b32_e32 v142, v142, v143, vcc
	v_mul_lo_u32 v141, v140, v142
	v_add_u32_e32 v140, v141, v140
	v_cmp_ne_u32_e32 vcc, v144, v140
	v_mov_b64_e32 v[140:141], s[12:13]
	s_and_saveexec_b64 s[10:11], vcc
	s_cbranch_execz .LBB0_1238
	v_mov_b32_e32 v140, 0
	global_load_dword v141, v140, s[12:13] sc1
	s_mov_b64 s[18:19], 0
	s_waitcnt vmcnt(0)
	v_cmp_eq_u32_e32 vcc, v141, v142
	s_and_saveexec_b64 s[16:17], vcc
	s_cbranch_execz .LBB0_1237
	s_add_u32 s14, s54, 0x200
	s_addc_u32 s15, s55, 0
	s_mov_b32 s3, 1
	s_branch .LBB0_1230

.LBB0_1232:
	global_load_dword v141, v140, s[12:13] sc1
	s_add_i32 s3, s3, 1
	s_mov_b64 s[22:23], -1
	s_waitcnt vmcnt(0)
	v_cmp_ne_u32_e32 vcc, v141, v142
	s_orn2_b64 s[26:27], vcc, exec
	s_branch .LBB0_1229
.LBB0_1233:
	global_load_dword v141, v140, s[14:15] sc1
	s_waitcnt vmcnt(0)
	v_cmp_eq_u32_e32 vcc, 0, v141
	s_cbranch_vccnz .LBB0_1235
	s_mov_b64 s[22:23], -1
	s_mov_b64 s[26:27], -1
	s_branch .LBB0_1229

.LBB0_1237:
	s_or_b64 exec, exec, s[16:17]
	v_mov_b64_e32 v[140:141], s[14:15]
	s_orn2_b64 s[14:15], s[18:19], exec
.LBB0_1238:
	s_or_b64 exec, exec, s[10:11]
	s_and_saveexec_b64 s[10:11], s[14:15]
	s_cbranch_execz .LBB0_1240
	v_mov_b32_e32 v142, 1
	global_atomic_add v[140:141], v142, off
.LBB0_1240:
	s_or_b64 exec, exec, s[10:11]
	s_mov_b64 s[10:11], exec
	v_mbcnt_lo_u32_b32 v140, s10, 0
	v_mbcnt_hi_u32_b32 v140, s11, v140
	v_cmp_eq_u32_e32 vcc, 0, v140
	s_waitcnt vmcnt(0)
	buffer_inv sc1
	s_and_saveexec_b64 s[12:13], vcc
	s_cbranch_execz .LBB0_1242
	s_bcnt1_i32_b64 s3, s[10:11]
	v_mov_b32_e32 v140, 0x2000
	v_mov_b32_e32 v141, s3
	global_atomic_add v140, v141, s[6:7] offset:1024

.LBB0_1243:
	s_or_b64 exec, exec, s[0:1]
	s_waitcnt lgkmcnt(0)
	s_barrier
	s_and_b32 s98, s2, 7
	s_lshl_b32 s98, s98, 3
	s_bfe_u32 s99, s2, 0x30003
	s_or_b32 s98, s98, s99
	s_lshr_b32 s99, s2, 6
	v_and_b32_e32 v172, 0xff, v136
	v_lshrrev_b32_e32 v173, 8, v136
	v_mul_u32_u24_e32 v173, 0x84000, v173
	v_lshl_add_u32 v172, v172, 2, v173
	s_lshl_b32 s24, s98, 10
	s_add_u32 s18, s44, s24
	s_addc_u32 s19, s45, 0
	global_load_dword v164, v172, s[18:19]
	s_add_u32 s18, s18, 0x10800
	s_addc_u32 s19, s19, 0
	global_load_dword v165, v172, s[18:19]
	s_add_u32 s18, s18, 0x10800
	s_addc_u32 s19, s19, 0
	global_load_dword v166, v172, s[18:19]
	s_add_u32 s18, s18, 0x10800
	s_addc_u32 s19, s19, 0
	global_load_dword v167, v172, s[18:19]
	s_add_u32 s18, s18, 0x10800
	s_addc_u32 s19, s19, 0
	global_load_dword v168, v172, s[18:19]
	s_add_u32 s18, s18, 0x10800
	s_addc_u32 s19, s19, 0
	global_load_dword v169, v172, s[18:19]
	s_add_u32 s18, s18, 0x10800
	s_addc_u32 s19, s19, 0
	global_load_dword v170, v172, s[18:19]
	s_add_u32 s18, s18, 0x10800
	s_addc_u32 s19, s19, 0
	global_load_dword v171, v172, s[18:19]
	v_lshrrev_b32_e32 v141, 8, v136
	v_and_b32_e32 v142, 15, v136
	v_lshl_add_u32 v141, v141, 6, v142
	v_bfe_u32 v144, v136, 6, 2
	v_bfe_u32 v145, v136, 4, 2
	v_lshlrev_b32_e32 v144, 5, v144
	v_lshl_add_u32 v144, v145, 3, v144
	s_lshl_b32 s24, s99, 8
	v_add_u32_e32 v144, s24, v144
	s_lshl_b32 s25, s98, 8
	v_add_u32_e32 v145, s25, v141
	v_lshl_add_u32 v146, v145, 10, v144
	v_lshlrev_b32_e32 v140, 1, v146
	v_lshlrev_b32_e32 v147, 2, v144
	v_readlane_b32 s18, v253, 3
	v_readlane_b32 s19, v253, 4
	s_mov_b32 s20, s60
	s_mov_b32 s21, s61
	s_nop 4
	s_add_u32 s18, s18, 0x3000
	s_addc_u32 s19, s19, 0
	global_load_dwordx4 v[148:151], v147, s[18:19]
	global_load_dwordx4 v[152:155], v147, s[18:19] offset:16
	global_load_dwordx4 v[156:159], v147, s[18:19] offset:512
	global_load_dwordx4 v[160:163], v147, s[18:19] offset:528
	s_add_u32 s22, s20, 0x0
	s_addc_u32 s23, s21, 0
	global_load_dwordx4 v[188:191], v140, s[22:23] nt
	global_load_dwordx4 v[192:195], v140, s[22:23] offset:256 nt
	s_add_u32 s22, s20, 0x8000
	s_addc_u32 s23, s21, 0
	global_load_dwordx4 v[196:199], v140, s[22:23] nt
	global_load_dwordx4 v[200:203], v140, s[22:23] offset:256 nt
	s_add_u32 s22, s20, 0x10000
	s_addc_u32 s23, s21, 0
	global_load_dwordx4 v[204:207], v140, s[22:23] nt
	global_load_dwordx4 v[208:211], v140, s[22:23] offset:256 nt
	s_add_u32 s22, s20, 0x18000
	s_addc_u32 s23, s21, 0
	global_load_dwordx4 v[212:215], v140, s[22:23] nt
	global_load_dwordx4 v[216:219], v140, s[22:23] offset:256 nt
	s_add_u32 s22, s20, 0x40000
	s_addc_u32 s23, s21, 0
	global_load_dwordx4 v[220:223], v140, s[22:23] nt
	global_load_dwordx4 v[224:227], v140, s[22:23] offset:256 nt
	s_add_u32 s22, s20, 0x48000
	s_addc_u32 s23, s21, 0
	global_load_dwordx4 v[228:231], v140, s[22:23] nt
	global_load_dwordx4 v[232:235], v140, s[22:23] offset:256 nt
	s_add_u32 s22, s20, 0x50000
	s_addc_u32 s23, s21, 0
	global_load_dwordx4 v[236:239], v140, s[22:23] nt
	global_load_dwordx4 v[240:243], v140, s[22:23] offset:256 nt
	s_add_u32 s22, s20, 0x58000
	s_addc_u32 s23, s21, 0
	global_load_dwordx4 v[244:247], v140, s[22:23] nt
	global_load_dwordx4 v[248:251], v140, s[22:23] offset:256 nt
	s_waitcnt vmcnt(20)
	v_add_f32_e32 v164, v164, v165
	v_add_f32_e32 v164, v164, v166
	v_add_f32_e32 v164, v164, v167
	v_add_f32_e32 v164, v164, v168
	v_add_f32_e32 v164, v164, v169
	v_add_f32_e32 v164, v164, v170
	v_add_f32_e32 v164, v164, v171
	v_lshlrev_b32_e32 v173, 2, v136
	ds_write_b32 v173, v164
	s_waitcnt lgkmcnt(0)
	s_barrier
	v_lshlrev_b32_e32 v142, 2, v141
	ds_read_b32 v128, v142 offset:0
	ds_read_b32 v174, v142 offset:1024
	ds_read_b32 v129, v142 offset:64
	ds_read_b32 v175, v142 offset:1088
	ds_read_b32 v130, v142 offset:128
	ds_read_b32 v176, v142 offset:1152
	ds_read_b32 v131, v142 offset:192
	ds_read_b32 v177, v142 offset:1216
	ds_read_b32 v132, v142 offset:512
	ds_read_b32 v178, v142 offset:1536
	ds_read_b32 v133, v142 offset:576
	ds_read_b32 v179, v142 offset:1600
	ds_read_b32 v134, v142 offset:640
	ds_read_b32 v180, v142 offset:1664
	ds_read_b32 v135, v142 offset:704
	ds_read_b32 v181, v142 offset:1728
	s_waitcnt lgkmcnt(0)
	s_mov_b32 s101, 0x3a800000
	v_mov_b32_e32 v143, 0x358637bd
	v_add_f32_e32 v128, v128, v174
	v_add_f32_e32 v129, v129, v175
	v_add_f32_e32 v130, v130, v176
	v_add_f32_e32 v131, v131, v177
	v_add_f32_e32 v132, v132, v178
	v_add_f32_e32 v133, v133, v179
	v_add_f32_e32 v134, v134, v180
	v_add_f32_e32 v135, v135, v181
	v_fma_f32 v128, v128, s101, v143
	v_fma_f32 v129, v129, s101, v143
	v_fma_f32 v130, v130, s101, v143
	v_fma_f32 v131, v131, s101, v143
	v_fma_f32 v132, v132, s101, v143
	v_fma_f32 v133, v133, s101, v143
	v_fma_f32 v134, v134, s101, v143
	v_fma_f32 v135, v135, s101, v143
	v_rsq_f32_e32 v128, v128
	v_rsq_f32_e32 v129, v129
	v_rsq_f32_e32 v130, v130
	v_rsq_f32_e32 v131, v131
	v_rsq_f32_e32 v132, v132
	v_rsq_f32_e32 v133, v133
	v_rsq_f32_e32 v134, v134
	v_rsq_f32_e32 v135, v135
	s_waitcnt vmcnt(0)
	s_add_u32 s22, s64, 0x0
	s_addc_u32 s23, s65, 0
	v_lshlrev_b32_e32 v164, 16, v188
	v_and_b32_e32 v165, 0xffff0000, v188
	v_lshlrev_b32_e32 v166, 16, v189
	v_and_b32_e32 v167, 0xffff0000, v189
	v_lshlrev_b32_e32 v168, 16, v190
	v_and_b32_e32 v169, 0xffff0000, v190
	v_lshlrev_b32_e32 v170, 16, v191
	v_and_b32_e32 v171, 0xffff0000, v191
	v_mul_f32_e32 v124, v124, v128
	v_mul_f32_e32 v125, v125, v128
	v_mul_f32_e32 v126, v126, v128
	v_mul_f32_e32 v127, v127, v128
	v_mul_f32_e32 v112, v112, v128
	v_mul_f32_e32 v113, v113, v128
	v_mul_f32_e32 v114, v114, v128
	v_mul_f32_e32 v115, v115, v128
	v_fmac_f32_e32 v164, v124, v148
	v_fmac_f32_e32 v165, v125, v149
	v_fmac_f32_e32 v166, v126, v150
	v_fmac_f32_e32 v167, v127, v151
	v_fmac_f32_e32 v168, v112, v152
	v_fmac_f32_e32 v169, v113, v153
	v_fmac_f32_e32 v170, v114, v154
	v_fmac_f32_e32 v171, v115, v155
	v_mul_f32_e32 v138, v164, v164
	v_fmac_f32_e32 v138, v165, v165
	v_fmac_f32_e32 v138, v166, v166
	v_fmac_f32_e32 v138, v167, v167
	v_fmac_f32_e32 v138, v168, v168
	v_fmac_f32_e32 v138, v169, v169
	v_fmac_f32_e32 v138, v170, v170
	v_fmac_f32_e32 v138, v171, v171
	v_cvt_pk_bf16_f32 v180, v164, v165
	v_cvt_pk_bf16_f32 v181, v166, v167
	v_cvt_pk_bf16_f32 v182, v168, v169
	v_cvt_pk_bf16_f32 v183, v170, v171
	global_store_dwordx4 v140, v[180:183], s[22:23]
	v_lshlrev_b32_e32 v172, 16, v192
	v_and_b32_e32 v173, 0xffff0000, v192
	v_lshlrev_b32_e32 v174, 16, v193
	v_and_b32_e32 v175, 0xffff0000, v193
	v_lshlrev_b32_e32 v176, 16, v194
	v_and_b32_e32 v177, 0xffff0000, v194
	v_lshlrev_b32_e32 v178, 16, v195
	v_and_b32_e32 v179, 0xffff0000, v195
	v_mul_f32_e32 v120, v120, v128
	v_mul_f32_e32 v121, v121, v128
	v_mul_f32_e32 v122, v122, v128
	v_mul_f32_e32 v123, v123, v128
	v_mul_f32_e32 v116, v116, v128
	v_mul_f32_e32 v117, v117, v128
	v_mul_f32_e32 v118, v118, v128
	v_mul_f32_e32 v119, v119, v128
	v_fmac_f32_e32 v172, v120, v156
	v_fmac_f32_e32 v173, v121, v157
	v_fmac_f32_e32 v174, v122, v158
	v_fmac_f32_e32 v175, v123, v159
	v_fmac_f32_e32 v176, v116, v160
	v_fmac_f32_e32 v177, v117, v161
	v_fmac_f32_e32 v178, v118, v162
	v_fmac_f32_e32 v179, v119, v163
	v_fmac_f32_e32 v138, v172, v172
	v_fmac_f32_e32 v138, v173, v173
	v_fmac_f32_e32 v138, v174, v174
	v_fmac_f32_e32 v138, v175, v175
	v_fmac_f32_e32 v138, v176, v176
	v_fmac_f32_e32 v138, v177, v177
	v_fmac_f32_e32 v138, v178, v178
	v_fmac_f32_e32 v138, v179, v179
	v_cvt_pk_bf16_f32 v184, v172, v173
	v_cvt_pk_bf16_f32 v185, v174, v175
	v_cvt_pk_bf16_f32 v186, v176, v177
	v_cvt_pk_bf16_f32 v187, v178, v179
	global_store_dwordx4 v140, v[184:187], s[22:23] offset:256
	s_add_u32 s22, s64, 0x8000
	s_addc_u32 s23, s65, 0
	v_lshlrev_b32_e32 v164, 16, v196
	v_and_b32_e32 v165, 0xffff0000, v196
	v_lshlrev_b32_e32 v166, 16, v197
	v_and_b32_e32 v167, 0xffff0000, v197
	v_lshlrev_b32_e32 v168, 16, v198
	v_and_b32_e32 v169, 0xffff0000, v198
	v_lshlrev_b32_e32 v170, 16, v199
	v_and_b32_e32 v171, 0xffff0000, v199
	v_mul_f32_e32 v108, v108, v129
	v_mul_f32_e32 v109, v109, v129
	v_mul_f32_e32 v110, v110, v129
	v_mul_f32_e32 v111, v111, v129
	v_mul_f32_e32 v96, v96, v129
	v_mul_f32_e32 v97, v97, v129
	v_mul_f32_e32 v98, v98, v129
	v_mul_f32_e32 v99, v99, v129
	v_fmac_f32_e32 v164, v108, v148
	v_fmac_f32_e32 v165, v109, v149
	v_fmac_f32_e32 v166, v110, v150
	v_fmac_f32_e32 v167, v111, v151
	v_fmac_f32_e32 v168, v96, v152
	v_fmac_f32_e32 v169, v97, v153
	v_fmac_f32_e32 v170, v98, v154
	v_fmac_f32_e32 v171, v99, v155
	v_mul_f32_e32 v139, v164, v164
	v_fmac_f32_e32 v139, v165, v165
	v_fmac_f32_e32 v139, v166, v166
	v_fmac_f32_e32 v139, v167, v167
	v_fmac_f32_e32 v139, v168, v168
	v_fmac_f32_e32 v139, v169, v169
	v_fmac_f32_e32 v139, v170, v170
	v_fmac_f32_e32 v139, v171, v171
	v_cvt_pk_bf16_f32 v180, v164, v165
	v_cvt_pk_bf16_f32 v181, v166, v167
	v_cvt_pk_bf16_f32 v182, v168, v169
	v_cvt_pk_bf16_f32 v183, v170, v171
	global_store_dwordx4 v140, v[180:183], s[22:23]
	v_lshlrev_b32_e32 v172, 16, v200
	v_and_b32_e32 v173, 0xffff0000, v200
	v_lshlrev_b32_e32 v174, 16, v201
	v_and_b32_e32 v175, 0xffff0000, v201
	v_lshlrev_b32_e32 v176, 16, v202
	v_and_b32_e32 v177, 0xffff0000, v202
	v_lshlrev_b32_e32 v178, 16, v203
	v_and_b32_e32 v179, 0xffff0000, v203
	v_mul_f32_e32 v100, v100, v129
	v_mul_f32_e32 v101, v101, v129
	v_mul_f32_e32 v102, v102, v129
	v_mul_f32_e32 v103, v103, v129
	v_mul_f32_e32 v104, v104, v129
	v_mul_f32_e32 v105, v105, v129
	v_mul_f32_e32 v106, v106, v129
	v_mul_f32_e32 v107, v107, v129
	v_fmac_f32_e32 v172, v100, v156
	v_fmac_f32_e32 v173, v101, v157
	v_fmac_f32_e32 v174, v102, v158
	v_fmac_f32_e32 v175, v103, v159
	v_fmac_f32_e32 v176, v104, v160
	v_fmac_f32_e32 v177, v105, v161
	v_fmac_f32_e32 v178, v106, v162
	v_fmac_f32_e32 v179, v107, v163
	v_fmac_f32_e32 v139, v172, v172
	v_fmac_f32_e32 v139, v173, v173
	v_fmac_f32_e32 v139, v174, v174
	v_fmac_f32_e32 v139, v175, v175
	v_fmac_f32_e32 v139, v176, v176
	v_fmac_f32_e32 v139, v177, v177
	v_fmac_f32_e32 v139, v178, v178
	v_fmac_f32_e32 v139, v179, v179
	v_cvt_pk_bf16_f32 v184, v172, v173
	v_cvt_pk_bf16_f32 v185, v174, v175
	v_cvt_pk_bf16_f32 v186, v176, v177
	v_cvt_pk_bf16_f32 v187, v178, v179
	global_store_dwordx4 v140, v[184:187], s[22:23] offset:256
	s_add_u32 s22, s64, 0x10000
	s_addc_u32 s23, s65, 0
	v_lshlrev_b32_e32 v164, 16, v204
	v_and_b32_e32 v165, 0xffff0000, v204
	v_lshlrev_b32_e32 v166, 16, v205
	v_and_b32_e32 v167, 0xffff0000, v205
	v_lshlrev_b32_e32 v168, 16, v206
	v_and_b32_e32 v169, 0xffff0000, v206
	v_lshlrev_b32_e32 v170, 16, v207
	v_and_b32_e32 v171, 0xffff0000, v207
	v_mul_f32_e32 v92, v92, v130
	v_mul_f32_e32 v93, v93, v130
	v_mul_f32_e32 v94, v94, v130
	v_mul_f32_e32 v95, v95, v130
	v_mul_f32_e32 v80, v80, v130
	v_mul_f32_e32 v81, v81, v130
	v_mul_f32_e32 v82, v82, v130
	v_mul_f32_e32 v83, v83, v130
	v_fmac_f32_e32 v164, v92, v148
	v_fmac_f32_e32 v165, v93, v149
	v_fmac_f32_e32 v166, v94, v150
	v_fmac_f32_e32 v167, v95, v151
	v_fmac_f32_e32 v168, v80, v152
	v_fmac_f32_e32 v169, v81, v153
	v_fmac_f32_e32 v170, v82, v154
	v_fmac_f32_e32 v171, v83, v155
	v_mul_f32_e32 v141, v164, v164
	v_fmac_f32_e32 v141, v165, v165
	v_fmac_f32_e32 v141, v166, v166
	v_fmac_f32_e32 v141, v167, v167
	v_fmac_f32_e32 v141, v168, v168
	v_fmac_f32_e32 v141, v169, v169
	v_fmac_f32_e32 v141, v170, v170
	v_fmac_f32_e32 v141, v171, v171
	v_cvt_pk_bf16_f32 v180, v164, v165
	v_cvt_pk_bf16_f32 v181, v166, v167
	v_cvt_pk_bf16_f32 v182, v168, v169
	v_cvt_pk_bf16_f32 v183, v170, v171
	global_store_dwordx4 v140, v[180:183], s[22:23]
	v_lshlrev_b32_e32 v172, 16, v208
	v_and_b32_e32 v173, 0xffff0000, v208
	v_lshlrev_b32_e32 v174, 16, v209
	v_and_b32_e32 v175, 0xffff0000, v209
	v_lshlrev_b32_e32 v176, 16, v210
	v_and_b32_e32 v177, 0xffff0000, v210
	v_lshlrev_b32_e32 v178, 16, v211
	v_and_b32_e32 v179, 0xffff0000, v211
	v_mul_f32_e32 v84, v84, v130
	v_mul_f32_e32 v85, v85, v130
	v_mul_f32_e32 v86, v86, v130
	v_mul_f32_e32 v87, v87, v130
	v_mul_f32_e32 v88, v88, v130
	v_mul_f32_e32 v89, v89, v130
	v_mul_f32_e32 v90, v90, v130
	v_mul_f32_e32 v91, v91, v130
	v_fmac_f32_e32 v172, v84, v156
	v_fmac_f32_e32 v173, v85, v157
	v_fmac_f32_e32 v174, v86, v158
	v_fmac_f32_e32 v175, v87, v159
	v_fmac_f32_e32 v176, v88, v160
	v_fmac_f32_e32 v177, v89, v161
	v_fmac_f32_e32 v178, v90, v162
	v_fmac_f32_e32 v179, v91, v163
	v_fmac_f32_e32 v141, v172, v172
	v_fmac_f32_e32 v141, v173, v173
	v_fmac_f32_e32 v141, v174, v174
	v_fmac_f32_e32 v141, v175, v175
	v_fmac_f32_e32 v141, v176, v176
	v_fmac_f32_e32 v141, v177, v177
	v_fmac_f32_e32 v141, v178, v178
	v_fmac_f32_e32 v141, v179, v179
	v_cvt_pk_bf16_f32 v184, v172, v173
	v_cvt_pk_bf16_f32 v185, v174, v175
	v_cvt_pk_bf16_f32 v186, v176, v177
	v_cvt_pk_bf16_f32 v187, v178, v179
	global_store_dwordx4 v140, v[184:187], s[22:23] offset:256
	s_add_u32 s22, s64, 0x18000
	s_addc_u32 s23, s65, 0
	v_lshlrev_b32_e32 v164, 16, v212
	v_and_b32_e32 v165, 0xffff0000, v212
	v_lshlrev_b32_e32 v166, 16, v213
	v_and_b32_e32 v167, 0xffff0000, v213
	v_lshlrev_b32_e32 v168, 16, v214
	v_and_b32_e32 v169, 0xffff0000, v214
	v_lshlrev_b32_e32 v170, 16, v215
	v_and_b32_e32 v171, 0xffff0000, v215
	v_mul_f32_e32 v76, v76, v131
	v_mul_f32_e32 v77, v77, v131
	v_mul_f32_e32 v78, v78, v131
	v_mul_f32_e32 v79, v79, v131
	v_mul_f32_e32 v64, v64, v131
	v_mul_f32_e32 v65, v65, v131
	v_mul_f32_e32 v66, v66, v131
	v_mul_f32_e32 v67, v67, v131
	v_fmac_f32_e32 v164, v76, v148
	v_fmac_f32_e32 v165, v77, v149
	v_fmac_f32_e32 v166, v78, v150
	v_fmac_f32_e32 v167, v79, v151
	v_fmac_f32_e32 v168, v64, v152
	v_fmac_f32_e32 v169, v65, v153
	v_fmac_f32_e32 v170, v66, v154
	v_fmac_f32_e32 v171, v67, v155
	v_mul_f32_e32 v142, v164, v164
	v_fmac_f32_e32 v142, v165, v165
	v_fmac_f32_e32 v142, v166, v166
	v_fmac_f32_e32 v142, v167, v167
	v_fmac_f32_e32 v142, v168, v168
	v_fmac_f32_e32 v142, v169, v169
	v_fmac_f32_e32 v142, v170, v170
	v_fmac_f32_e32 v142, v171, v171
	v_cvt_pk_bf16_f32 v180, v164, v165
	v_cvt_pk_bf16_f32 v181, v166, v167
	v_cvt_pk_bf16_f32 v182, v168, v169
	v_cvt_pk_bf16_f32 v183, v170, v171
	global_store_dwordx4 v140, v[180:183], s[22:23]
	v_lshlrev_b32_e32 v172, 16, v216
	v_and_b32_e32 v173, 0xffff0000, v216
	v_lshlrev_b32_e32 v174, 16, v217
	v_and_b32_e32 v175, 0xffff0000, v217
	v_lshlrev_b32_e32 v176, 16, v218
	v_and_b32_e32 v177, 0xffff0000, v218
	v_lshlrev_b32_e32 v178, 16, v219
	v_and_b32_e32 v179, 0xffff0000, v219
	v_mul_f32_e32 v68, v68, v131
	v_mul_f32_e32 v69, v69, v131
	v_mul_f32_e32 v70, v70, v131
	v_mul_f32_e32 v71, v71, v131
	v_mul_f32_e32 v72, v72, v131
	v_mul_f32_e32 v73, v73, v131
	v_mul_f32_e32 v74, v74, v131
	v_mul_f32_e32 v75, v75, v131
	v_fmac_f32_e32 v172, v68, v156
	v_fmac_f32_e32 v173, v69, v157
	v_fmac_f32_e32 v174, v70, v158
	v_fmac_f32_e32 v175, v71, v159
	v_fmac_f32_e32 v176, v72, v160
	v_fmac_f32_e32 v177, v73, v161
	v_fmac_f32_e32 v178, v74, v162
	v_fmac_f32_e32 v179, v75, v163
	v_fmac_f32_e32 v142, v172, v172
	v_fmac_f32_e32 v142, v173, v173
	v_fmac_f32_e32 v142, v174, v174
	v_fmac_f32_e32 v142, v175, v175
	v_fmac_f32_e32 v142, v176, v176
	v_fmac_f32_e32 v142, v177, v177
	v_fmac_f32_e32 v142, v178, v178
	v_fmac_f32_e32 v142, v179, v179
	v_cvt_pk_bf16_f32 v184, v172, v173
	v_cvt_pk_bf16_f32 v185, v174, v175
	v_cvt_pk_bf16_f32 v186, v176, v177
	v_cvt_pk_bf16_f32 v187, v178, v179
	global_store_dwordx4 v140, v[184:187], s[22:23] offset:256
	s_add_u32 s22, s64, 0x40000
	s_addc_u32 s23, s65, 0
	v_lshlrev_b32_e32 v164, 16, v220
	v_and_b32_e32 v165, 0xffff0000, v220
	v_lshlrev_b32_e32 v166, 16, v221
	v_and_b32_e32 v167, 0xffff0000, v221
	v_lshlrev_b32_e32 v168, 16, v222
	v_and_b32_e32 v169, 0xffff0000, v222
	v_lshlrev_b32_e32 v170, 16, v223
	v_and_b32_e32 v171, 0xffff0000, v223
	v_mul_f32_e32 v60, v60, v132
	v_mul_f32_e32 v61, v61, v132
	v_mul_f32_e32 v62, v62, v132
	v_mul_f32_e32 v63, v63, v132
	v_mul_f32_e32 v48, v48, v132
	v_mul_f32_e32 v49, v49, v132
	v_mul_f32_e32 v50, v50, v132
	v_mul_f32_e32 v51, v51, v132
	v_fmac_f32_e32 v164, v60, v148
	v_fmac_f32_e32 v165, v61, v149
	v_fmac_f32_e32 v166, v62, v150
	v_fmac_f32_e32 v167, v63, v151
	v_fmac_f32_e32 v168, v48, v152
	v_fmac_f32_e32 v169, v49, v153
	v_fmac_f32_e32 v170, v50, v154
	v_fmac_f32_e32 v171, v51, v155
	v_mul_f32_e32 v143, v164, v164
	v_fmac_f32_e32 v143, v165, v165
	v_fmac_f32_e32 v143, v166, v166
	v_fmac_f32_e32 v143, v167, v167
	v_fmac_f32_e32 v143, v168, v168
	v_fmac_f32_e32 v143, v169, v169
	v_fmac_f32_e32 v143, v170, v170
	v_fmac_f32_e32 v143, v171, v171
	v_cvt_pk_bf16_f32 v180, v164, v165
	v_cvt_pk_bf16_f32 v181, v166, v167
	v_cvt_pk_bf16_f32 v182, v168, v169
	v_cvt_pk_bf16_f32 v183, v170, v171
	global_store_dwordx4 v140, v[180:183], s[22:23]
	v_lshlrev_b32_e32 v172, 16, v224
	v_and_b32_e32 v173, 0xffff0000, v224
	v_lshlrev_b32_e32 v174, 16, v225
	v_and_b32_e32 v175, 0xffff0000, v225
	v_lshlrev_b32_e32 v176, 16, v226
	v_and_b32_e32 v177, 0xffff0000, v226
	v_lshlrev_b32_e32 v178, 16, v227
	v_and_b32_e32 v179, 0xffff0000, v227
	v_mul_f32_e32 v52, v52, v132
	v_mul_f32_e32 v53, v53, v132
	v_mul_f32_e32 v54, v54, v132
	v_mul_f32_e32 v55, v55, v132
	v_mul_f32_e32 v56, v56, v132
	v_mul_f32_e32 v57, v57, v132
	v_mul_f32_e32 v58, v58, v132
	v_mul_f32_e32 v59, v59, v132
	v_fmac_f32_e32 v172, v52, v156
	v_fmac_f32_e32 v173, v53, v157
	v_fmac_f32_e32 v174, v54, v158
	v_fmac_f32_e32 v175, v55, v159
	v_fmac_f32_e32 v176, v56, v160
	v_fmac_f32_e32 v177, v57, v161
	v_fmac_f32_e32 v178, v58, v162
	v_fmac_f32_e32 v179, v59, v163
	v_fmac_f32_e32 v143, v172, v172
	v_fmac_f32_e32 v143, v173, v173
	v_fmac_f32_e32 v143, v174, v174
	v_fmac_f32_e32 v143, v175, v175
	v_fmac_f32_e32 v143, v176, v176
	v_fmac_f32_e32 v143, v177, v177
	v_fmac_f32_e32 v143, v178, v178
	v_fmac_f32_e32 v143, v179, v179
	v_cvt_pk_bf16_f32 v184, v172, v173
	v_cvt_pk_bf16_f32 v185, v174, v175
	v_cvt_pk_bf16_f32 v186, v176, v177
	v_cvt_pk_bf16_f32 v187, v178, v179
	global_store_dwordx4 v140, v[184:187], s[22:23] offset:256
	s_add_u32 s22, s64, 0x48000
	s_addc_u32 s23, s65, 0
	v_lshlrev_b32_e32 v164, 16, v228
	v_and_b32_e32 v165, 0xffff0000, v228
	v_lshlrev_b32_e32 v166, 16, v229
	v_and_b32_e32 v167, 0xffff0000, v229
	v_lshlrev_b32_e32 v168, 16, v230
	v_and_b32_e32 v169, 0xffff0000, v230
	v_lshlrev_b32_e32 v170, 16, v231
	v_and_b32_e32 v171, 0xffff0000, v231
	v_mul_f32_e32 v44, v44, v133
	v_mul_f32_e32 v45, v45, v133
	v_mul_f32_e32 v46, v46, v133
	v_mul_f32_e32 v47, v47, v133
	v_mul_f32_e32 v32, v32, v133
	v_mul_f32_e32 v33, v33, v133
	v_mul_f32_e32 v34, v34, v133
	v_mul_f32_e32 v35, v35, v133
	v_fmac_f32_e32 v164, v44, v148
	v_fmac_f32_e32 v165, v45, v149
	v_fmac_f32_e32 v166, v46, v150
	v_fmac_f32_e32 v167, v47, v151
	v_fmac_f32_e32 v168, v32, v152
	v_fmac_f32_e32 v169, v33, v153
	v_fmac_f32_e32 v170, v34, v154
	v_fmac_f32_e32 v171, v35, v155
	v_mul_f32_e32 v144, v164, v164
	v_fmac_f32_e32 v144, v165, v165
	v_fmac_f32_e32 v144, v166, v166
	v_fmac_f32_e32 v144, v167, v167
	v_fmac_f32_e32 v144, v168, v168
	v_fmac_f32_e32 v144, v169, v169
	v_fmac_f32_e32 v144, v170, v170
	v_fmac_f32_e32 v144, v171, v171
	v_cvt_pk_bf16_f32 v180, v164, v165
	v_cvt_pk_bf16_f32 v181, v166, v167
	v_cvt_pk_bf16_f32 v182, v168, v169
	v_cvt_pk_bf16_f32 v183, v170, v171
	global_store_dwordx4 v140, v[180:183], s[22:23]
	v_lshlrev_b32_e32 v172, 16, v232
	v_and_b32_e32 v173, 0xffff0000, v232
	v_lshlrev_b32_e32 v174, 16, v233
	v_and_b32_e32 v175, 0xffff0000, v233
	v_lshlrev_b32_e32 v176, 16, v234
	v_and_b32_e32 v177, 0xffff0000, v234
	v_lshlrev_b32_e32 v178, 16, v235
	v_and_b32_e32 v179, 0xffff0000, v235
	v_mul_f32_e32 v36, v36, v133
	v_mul_f32_e32 v37, v37, v133
	v_mul_f32_e32 v38, v38, v133
	v_mul_f32_e32 v39, v39, v133
	v_mul_f32_e32 v40, v40, v133
	v_mul_f32_e32 v41, v41, v133
	v_mul_f32_e32 v42, v42, v133
	v_mul_f32_e32 v43, v43, v133
	v_fmac_f32_e32 v172, v36, v156
	v_fmac_f32_e32 v173, v37, v157
	v_fmac_f32_e32 v174, v38, v158
	v_fmac_f32_e32 v175, v39, v159
	v_fmac_f32_e32 v176, v40, v160
	v_fmac_f32_e32 v177, v41, v161
	v_fmac_f32_e32 v178, v42, v162
	v_fmac_f32_e32 v179, v43, v163
	v_fmac_f32_e32 v144, v172, v172
	v_fmac_f32_e32 v144, v173, v173
	v_fmac_f32_e32 v144, v174, v174
	v_fmac_f32_e32 v144, v175, v175
	v_fmac_f32_e32 v144, v176, v176
	v_fmac_f32_e32 v144, v177, v177
	v_fmac_f32_e32 v144, v178, v178
	v_fmac_f32_e32 v144, v179, v179
	v_cvt_pk_bf16_f32 v184, v172, v173
	v_cvt_pk_bf16_f32 v185, v174, v175
	v_cvt_pk_bf16_f32 v186, v176, v177
	v_cvt_pk_bf16_f32 v187, v178, v179
	global_store_dwordx4 v140, v[184:187], s[22:23] offset:256
	s_add_u32 s22, s64, 0x50000
	s_addc_u32 s23, s65, 0
	v_lshlrev_b32_e32 v164, 16, v236
	v_and_b32_e32 v165, 0xffff0000, v236
	v_lshlrev_b32_e32 v166, 16, v237
	v_and_b32_e32 v167, 0xffff0000, v237
	v_lshlrev_b32_e32 v168, 16, v238
	v_and_b32_e32 v169, 0xffff0000, v238
	v_lshlrev_b32_e32 v170, 16, v239
	v_and_b32_e32 v171, 0xffff0000, v239
	v_mul_f32_e32 v28, v28, v134
	v_mul_f32_e32 v29, v29, v134
	v_mul_f32_e32 v30, v30, v134
	v_mul_f32_e32 v31, v31, v134
	v_mul_f32_e32 v16, v16, v134
	v_mul_f32_e32 v17, v17, v134
	v_mul_f32_e32 v18, v18, v134
	v_mul_f32_e32 v19, v19, v134
	v_fmac_f32_e32 v164, v28, v148
	v_fmac_f32_e32 v165, v29, v149
	v_fmac_f32_e32 v166, v30, v150
	v_fmac_f32_e32 v167, v31, v151
	v_fmac_f32_e32 v168, v16, v152
	v_fmac_f32_e32 v169, v17, v153
	v_fmac_f32_e32 v170, v18, v154
	v_fmac_f32_e32 v171, v19, v155
	v_mul_f32_e32 v145, v164, v164
	v_fmac_f32_e32 v145, v165, v165
	v_fmac_f32_e32 v145, v166, v166
	v_fmac_f32_e32 v145, v167, v167
	v_fmac_f32_e32 v145, v168, v168
	v_fmac_f32_e32 v145, v169, v169
	v_fmac_f32_e32 v145, v170, v170
	v_fmac_f32_e32 v145, v171, v171
	v_cvt_pk_bf16_f32 v180, v164, v165
	v_cvt_pk_bf16_f32 v181, v166, v167
	v_cvt_pk_bf16_f32 v182, v168, v169
	v_cvt_pk_bf16_f32 v183, v170, v171
	global_store_dwordx4 v140, v[180:183], s[22:23]
	v_lshlrev_b32_e32 v172, 16, v240
	v_and_b32_e32 v173, 0xffff0000, v240
	v_lshlrev_b32_e32 v174, 16, v241
	v_and_b32_e32 v175, 0xffff0000, v241
	v_lshlrev_b32_e32 v176, 16, v242
	v_and_b32_e32 v177, 0xffff0000, v242
	v_lshlrev_b32_e32 v178, 16, v243
	v_and_b32_e32 v179, 0xffff0000, v243
	v_mul_f32_e32 v20, v20, v134
	v_mul_f32_e32 v21, v21, v134
	v_mul_f32_e32 v22, v22, v134
	v_mul_f32_e32 v23, v23, v134
	v_mul_f32_e32 v24, v24, v134
	v_mul_f32_e32 v25, v25, v134
	v_mul_f32_e32 v26, v26, v134
	v_mul_f32_e32 v27, v27, v134
	v_fmac_f32_e32 v172, v20, v156
	v_fmac_f32_e32 v173, v21, v157
	v_fmac_f32_e32 v174, v22, v158
	v_fmac_f32_e32 v175, v23, v159
	v_fmac_f32_e32 v176, v24, v160
	v_fmac_f32_e32 v177, v25, v161
	v_fmac_f32_e32 v178, v26, v162
	v_fmac_f32_e32 v179, v27, v163
	v_fmac_f32_e32 v145, v172, v172
	v_fmac_f32_e32 v145, v173, v173
	v_fmac_f32_e32 v145, v174, v174
	v_fmac_f32_e32 v145, v175, v175
	v_fmac_f32_e32 v145, v176, v176
	v_fmac_f32_e32 v145, v177, v177
	v_fmac_f32_e32 v145, v178, v178
	v_fmac_f32_e32 v145, v179, v179
	v_cvt_pk_bf16_f32 v184, v172, v173
	v_cvt_pk_bf16_f32 v185, v174, v175
	v_cvt_pk_bf16_f32 v186, v176, v177
	v_cvt_pk_bf16_f32 v187, v178, v179
	global_store_dwordx4 v140, v[184:187], s[22:23] offset:256
	s_add_u32 s22, s64, 0x58000
	s_addc_u32 s23, s65, 0
	v_lshlrev_b32_e32 v164, 16, v244
	v_and_b32_e32 v165, 0xffff0000, v244
	v_lshlrev_b32_e32 v166, 16, v245
	v_and_b32_e32 v167, 0xffff0000, v245
	v_lshlrev_b32_e32 v168, 16, v246
	v_and_b32_e32 v169, 0xffff0000, v246
	v_lshlrev_b32_e32 v170, 16, v247
	v_and_b32_e32 v171, 0xffff0000, v247
	v_mul_f32_e32 v12, v12, v135
	v_mul_f32_e32 v13, v13, v135
	v_mul_f32_e32 v14, v14, v135
	v_mul_f32_e32 v15, v15, v135
	v_mul_f32_e32 v0, v0, v135
	v_mul_f32_e32 v1, v1, v135
	v_mul_f32_e32 v2, v2, v135
	v_mul_f32_e32 v3, v3, v135
	v_fmac_f32_e32 v164, v12, v148
	v_fmac_f32_e32 v165, v13, v149
	v_fmac_f32_e32 v166, v14, v150
	v_fmac_f32_e32 v167, v15, v151
	v_fmac_f32_e32 v168, v0, v152
	v_fmac_f32_e32 v169, v1, v153
	v_fmac_f32_e32 v170, v2, v154
	v_fmac_f32_e32 v171, v3, v155
	v_mul_f32_e32 v146, v164, v164
	v_fmac_f32_e32 v146, v165, v165
	v_fmac_f32_e32 v146, v166, v166
	v_fmac_f32_e32 v146, v167, v167
	v_fmac_f32_e32 v146, v168, v168
	v_fmac_f32_e32 v146, v169, v169
	v_fmac_f32_e32 v146, v170, v170
	v_fmac_f32_e32 v146, v171, v171
	v_cvt_pk_bf16_f32 v180, v164, v165
	v_cvt_pk_bf16_f32 v181, v166, v167
	v_cvt_pk_bf16_f32 v182, v168, v169
	v_cvt_pk_bf16_f32 v183, v170, v171
	global_store_dwordx4 v140, v[180:183], s[22:23]
	v_lshlrev_b32_e32 v172, 16, v248
	v_and_b32_e32 v173, 0xffff0000, v248
	v_lshlrev_b32_e32 v174, 16, v249
	v_and_b32_e32 v175, 0xffff0000, v249
	v_lshlrev_b32_e32 v176, 16, v250
	v_and_b32_e32 v177, 0xffff0000, v250
	v_lshlrev_b32_e32 v178, 16, v251
	v_and_b32_e32 v179, 0xffff0000, v251
	v_mul_f32_e32 v4, v4, v135
	v_mul_f32_e32 v5, v5, v135
	v_mul_f32_e32 v6, v6, v135
	v_mul_f32_e32 v7, v7, v135
	v_mul_f32_e32 v8, v8, v135
	v_mul_f32_e32 v9, v9, v135
	v_mul_f32_e32 v10, v10, v135
	v_mul_f32_e32 v11, v11, v135
	v_fmac_f32_e32 v172, v4, v156
	v_fmac_f32_e32 v173, v5, v157
	v_fmac_f32_e32 v174, v6, v158
	v_fmac_f32_e32 v175, v7, v159
	v_fmac_f32_e32 v176, v8, v160
	v_fmac_f32_e32 v177, v9, v161
	v_fmac_f32_e32 v178, v10, v162
	v_fmac_f32_e32 v179, v11, v163
	v_fmac_f32_e32 v146, v172, v172
	v_fmac_f32_e32 v146, v173, v173
	v_fmac_f32_e32 v146, v174, v174
	v_fmac_f32_e32 v146, v175, v175
	v_fmac_f32_e32 v146, v176, v176
	v_fmac_f32_e32 v146, v177, v177
	v_fmac_f32_e32 v146, v178, v178
	v_fmac_f32_e32 v146, v179, v179
	v_cvt_pk_bf16_f32 v184, v172, v173
	v_cvt_pk_bf16_f32 v185, v174, v175
	v_cvt_pk_bf16_f32 v186, v176, v177
	v_cvt_pk_bf16_f32 v187, v178, v179
	global_store_dwordx4 v140, v[184:187], s[22:23] offset:256
	v_mov_b32_e32 v148, v138
	v_mov_b32_e32 v149, v139
	v_mov_b32_e32 v150, v141
	v_mov_b32_e32 v151, v142
	v_mov_b32_e32 v152, v143
	v_mov_b32_e32 v153, v144
	v_mov_b32_e32 v154, v145
	v_mov_b32_e32 v155, v146
	v_xor_b32_e32 v138, 16, v137
	v_xor_b32_e32 v139, 32, v137
	v_lshlrev_b32_e32 v138, 2, v138
	v_lshlrev_b32_e32 v139, 2, v139
	ds_bpermute_b32 v164, v138, v148
	ds_bpermute_b32 v165, v138, v149
	ds_bpermute_b32 v166, v138, v150
	ds_bpermute_b32 v167, v138, v151
	ds_bpermute_b32 v168, v138, v152
	ds_bpermute_b32 v169, v138, v153
	ds_bpermute_b32 v170, v138, v154
	ds_bpermute_b32 v171, v138, v155
	s_waitcnt lgkmcnt(0)
	v_add_f32_e32 v148, v148, v164
	v_add_f32_e32 v149, v149, v165
	v_add_f32_e32 v150, v150, v166
	v_add_f32_e32 v151, v151, v167
	v_add_f32_e32 v152, v152, v168
	v_add_f32_e32 v153, v153, v169
	v_add_f32_e32 v154, v154, v170
	v_add_f32_e32 v155, v155, v171
	ds_bpermute_b32 v164, v139, v148
	ds_bpermute_b32 v165, v139, v149
	ds_bpermute_b32 v166, v139, v150
	ds_bpermute_b32 v167, v139, v151
	ds_bpermute_b32 v168, v139, v152
	ds_bpermute_b32 v169, v139, v153
	ds_bpermute_b32 v170, v139, v154
	ds_bpermute_b32 v171, v139, v155
	s_waitcnt lgkmcnt(0)
	v_add_f32_e32 v148, v148, v164
	v_add_f32_e32 v149, v149, v165
	v_add_f32_e32 v150, v150, v166
	v_add_f32_e32 v151, v151, v167
	v_add_f32_e32 v152, v152, v168
	v_add_f32_e32 v153, v153, v169
	v_add_f32_e32 v154, v154, v170
	v_add_f32_e32 v155, v155, v171
	s_and_b32 s98, s2, 7
	s_lshl_b32 s98, s98, 3
	s_bfe_u32 s99, s2, 0x30003
	s_or_b32 s98, s98, s99
	s_lshr_b32 s99, s2, 6
	s_mul_i32 s99, s99, 0x42000
	s_lshl_b32 s98, s98, 10
	s_add_u32 s100, s62, s99
	s_addc_u32 s101, s63, 0
	s_add_u32 s100, s100, s98
	s_addc_u32 s101, s101, 0
	v_lshrrev_b32_e32 v158, 8, v136
	v_bfe_u32 v159, v136, 6, 2
	v_and_b32_e32 v160, 15, v136
	v_lshl_add_u32 v160, v158, 6, v160
	v_mul_u32_u24_e32 v159, 0x4200, v159
	v_add_u32_e32 v160, v160, v159
	v_lshlrev_b32_e32 v160, 2, v160
	v_bfe_u32 v161, v136, 4, 2
	v_cmp_eq_u32_e32 vcc, 0, v161
	s_and_saveexec_b64 s[0:1], vcc
	global_store_dword v160, v148, s[100:101]
	global_store_dword v160, v149, s[100:101] offset:64
	global_store_dword v160, v150, s[100:101] offset:128
	global_store_dword v160, v151, s[100:101] offset:192
	global_store_dword v160, v152, s[100:101] offset:512
	global_store_dword v160, v153, s[100:101] offset:576
	global_store_dword v160, v154, s[100:101] offset:640
	global_store_dword v160, v155, s[100:101] offset:704
	s_or_b64 exec, exec, s[0:1]
	v_bfe_u32 v183, v136, 1, 2
	v_lshrrev_b32_e32 v187, 6, v136
	v_lshlrev_b32_e32 v190, 11, v136
	v_lshrrev_b32_e32 v252, 1, v136
	v_and_b32_e32 v132, 48, v136
	v_and_b32_e32 v189, 63, v136
	v_lshrrev_b32_e32 v182, 3, v136
	v_lshlrev_b32_e32 v188, 2, v136
	v_lshl_add_u32 v186, v183, 6, 0
	v_and_b32_e32 v191, 15, v136
	v_cndmask_b32_e64 v1, 0, 1, s[8:9]
	v_mov_b32_e32 v0, v136
	v_cmp_ne_u32_e64 s[6:7], 1, v1
	s_andn2_b64 vcc, exec, s[8:9]
	s_cbranch_vccnz .LBB0_1254
	v_and_b32_e32 v4, 63, v0
	v_ashrrev_i32_e32 v0, 5, v0
	v_readlane_b32 s8, v253, 3
	v_and_b32_e32 v5, -2, v0
	v_lshlrev_b32_e32 v0, 4, v4
	v_mov_b32_e32 v1, 0
	v_readlane_b32 s9, v253, 4
	s_mov_b64 s[0:1], 0x3000
	v_readlane_b32 s12, v253, 7
	v_lshl_add_u64 v[2:3], s[8:9], 0, v[0:1]
	v_lshl_add_u64 v[16:17], v[2:3], 0, s[0:1]
	v_and_b32_e32 v2, 64, v137
	v_add_u32_e32 v2, 64, v2
	v_xor_b32_e32 v3, 32, v137
	v_cmp_lt_i32_e64 s[0:1], v3, v2
	v_mul_u32_u24_e32 v0, 0x4200, v4
	v_lshlrev_b32_e32 v0, 2, v0
	v_cndmask_b32_e64 v3, v137, v3, s[0:1]
	v_lshlrev_b32_e32 v50, 2, v3
	v_xor_b32_e32 v3, 16, v137
	v_cmp_lt_i32_e64 s[0:1], v3, v2
	v_readlane_b32 s13, v253, 8
	v_lshl_add_u64 v[18:19], s[44:45], 0, v[0:1]
	v_cndmask_b32_e64 v3, v137, v3, s[0:1]
	v_lshlrev_b32_e32 v51, 2, v3
	v_xor_b32_e32 v3, 8, v137
	v_cmp_lt_i32_e64 s[0:1], v3, v2
	v_lshlrev_b32_e32 v0, 3, v4
	v_cmp_gt_u32_e32 vcc, 16, v4
	v_cndmask_b32_e64 v3, v137, v3, s[0:1]
	v_lshlrev_b32_e32 v52, 2, v3
	v_xor_b32_e32 v3, 4, v137
	v_cmp_lt_i32_e64 s[0:1], v3, v2
	v_lshl_add_u64 v[20:21], s[64:65], 0, v[0:1]
	v_lshl_add_u64 v[22:23], s[60:61], 0, v[0:1]
	v_cndmask_b32_e64 v3, v137, v3, s[0:1]
	v_lshlrev_b32_e32 v53, 2, v3
	v_xor_b32_e32 v3, 2, v137
	v_cmp_lt_i32_e64 s[0:1], v3, v2
	v_lshl_add_u64 v[24:25], s[58:59], 0, v[0:1]
	v_lshl_add_u32 v26, s2, 4, v5
	v_cndmask_b32_e64 v3, v137, v3, s[0:1]
	v_lshlrev_b32_e32 v54, 2, v3
	v_xor_b32_e32 v3, 1, v137
	v_cmp_lt_i32_e64 s[0:1], v3, v2
	s_lshl_b32 s3, s38, 4
	v_mov_b32_e32 v56, 0x358637bd
	v_cndmask_b32_e64 v2, v137, v3, s[0:1]
	v_lshlrev_b32_e32 v55, 2, v2
	v_cmp_eq_u32_e64 s[0:1], 0, v4
	s_mov_b32 s12, 0x800000
	s_mov_b32 s13, s2
	v_readlane_b32 s10, v253, 5
	v_readlane_b32 s11, v253, 6
	v_readlane_b32 s14, v253, 9
	v_readlane_b32 s15, v253, 10
	v_readlane_b32 s16, v253, 11
	v_readlane_b32 s17, v253, 12
	v_readlane_b32 s18, v253, 13
	v_readlane_b32 s19, v253, 14
	v_readlane_b32 s20, v253, 15
	v_readlane_b32 s21, v253, 16
	v_readlane_b32 s22, v253, 17
	v_readlane_b32 s23, v253, 18
	s_addk_i32 s13, 0x400
	v_add_u32_e32 v26, 0x4000, v26
	s_cmpk_lt_i32 s13, 0x420
	s_cbranch_scc0 .LBB0_1254
	s_branch .LBB0_1246

.LBB0_1306:
	s_or_b64 exec, exec, s[0:1]
	s_mov_b32 s3, 0
	s_mov_b64 s[20:21], 0
	v_mov_b32_e32 v129, 0
	s_mov_b64 s[0:1], 0x80
	s_mov_b64 s[8:9], 0x40080
	s_mov_b64 s[10:11], 0x100
	s_mov_b64 s[12:13], 0x40100
	s_mov_b64 s[14:15], 0x180
	s_mov_b64 s[16:17], 0x40180
	s_movk_i32 s36, 0x1600
	v_mov_b32_e32 v133, 1
	s_mov_b32 s37, s96
	s_waitcnt lgkmcnt(0)
	s_barrier
	s_and_b32 s24, s2, 7
	s_lshl_b32 s24, s24, 5
	s_lshr_b32 s25, s2, 3
	s_add_u32 s24, s24, s25
	s_add_u32 s98, s24, 0x0
	s_mul_hi_u32 s99, s98, 0x2e8ba2f
	s_mul_i32 s100, s99, 0x58
	s_sub_u32 s100, s98, s100
	s_lshl_b32 s99, s99, 2
	s_and_b32 s100, s100, 3
	s_add_u32 s26, s99, s100
	s_add_u32 s98, s24, 0x100
	s_mul_hi_u32 s99, s98, 0x2e8ba2f
	s_mul_i32 s100, s99, 0x58
	s_sub_u32 s100, s98, s100
	s_lshl_b32 s99, s99, 2
	s_and_b32 s100, s100, 3
	s_add_u32 s27, s99, s100
	s_cmpk_lt_u32 s98, 0x5ac
	s_cselect_b32 s27, s27, s26
	s_cmpk_lt_u32 s99, 0x40
	s_cselect_b32 s27, s27, s26
	s_add_u32 s98, s24, 0x200
	s_mul_hi_u32 s99, s98, 0x2e8ba2f
	s_mul_i32 s100, s99, 0x58
	s_sub_u32 s100, s98, s100
	s_lshl_b32 s99, s99, 2
	s_and_b32 s100, s100, 3
	s_add_u32 s28, s99, s100
	s_cmpk_lt_u32 s98, 0x5ac
	s_cselect_b32 s28, s28, s26
	s_cmpk_lt_u32 s99, 0x40
	s_cselect_b32 s28, s28, s26
	s_add_u32 s98, s24, 0x300
	s_mul_hi_u32 s99, s98, 0x2e8ba2f
	s_mul_i32 s100, s99, 0x58
	s_sub_u32 s100, s98, s100
	s_lshl_b32 s99, s99, 2
	s_and_b32 s100, s100, 3
	s_add_u32 s29, s99, s100
	s_cmpk_lt_u32 s98, 0x5ac
	s_cselect_b32 s29, s29, s26
	s_cmpk_lt_u32 s99, 0x40
	s_cselect_b32 s29, s29, s26
	s_add_u32 s98, s24, 0x400
	s_mul_hi_u32 s99, s98, 0x2e8ba2f
	s_mul_i32 s100, s99, 0x58
	s_sub_u32 s100, s98, s100
	s_lshl_b32 s99, s99, 2
	s_and_b32 s100, s100, 3
	s_add_u32 s30, s99, s100
	s_cmpk_lt_u32 s98, 0x5ac
	s_cselect_b32 s30, s30, s26
	s_cmpk_lt_u32 s99, 0x40
	s_cselect_b32 s30, s30, s26
	s_add_u32 s98, s24, 0x500
	s_mul_hi_u32 s99, s98, 0x2e8ba2f
	s_mul_i32 s100, s99, 0x58
	s_sub_u32 s100, s98, s100
	s_lshl_b32 s99, s99, 2
	s_and_b32 s100, s100, 3
	s_add_u32 s31, s99, s100
	s_cmpk_lt_u32 s98, 0x5ac
	s_cselect_b32 s31, s31, s26
	s_cmpk_lt_u32 s99, 0x40
	s_cselect_b32 s31, s31, s26
	v_and_b32_e32 v140, 0xff, v136
	v_lshrrev_b32_e32 v141, 8, v136
	v_mul_u32_u24_e32 v141, 0x84000, v141
	v_lshl_add_u32 v140, v140, 2, v141
	v_lshlrev_b32_e32 v141, 2, v136
	s_lshl_b32 s98, s26, 10
	s_add_u32 s18, s62, s98
	s_addc_u32 s19, s63, 0
	global_load_dword v192, v140, s[18:19]
	s_add_u32 s18, s18, 0x10800
	s_addc_u32 s19, s19, 0
	global_load_dword v193, v140, s[18:19]
	s_add_u32 s18, s18, 0x10800
	s_addc_u32 s19, s19, 0
	global_load_dword v194, v140, s[18:19]
	s_add_u32 s18, s18, 0x10800
	s_addc_u32 s19, s19, 0
	global_load_dword v195, v140, s[18:19]
	s_add_u32 s18, s18, 0x10800
	s_addc_u32 s19, s19, 0
	global_load_dword v196, v140, s[18:19]
	s_add_u32 s18, s18, 0x10800
	s_addc_u32 s19, s19, 0
	global_load_dword v197, v140, s[18:19]
	s_add_u32 s18, s18, 0x10800
	s_addc_u32 s19, s19, 0
	global_load_dword v198, v140, s[18:19]
	s_add_u32 s18, s18, 0x10800
	s_addc_u32 s19, s19, 0
	global_load_dword v199, v140, s[18:19]
	s_lshl_b32 s98, s27, 10
	s_add_u32 s18, s62, s98
	s_addc_u32 s19, s63, 0
	global_load_dword v200, v140, s[18:19]
	s_add_u32 s18, s18, 0x10800
	s_addc_u32 s19, s19, 0
	global_load_dword v201, v140, s[18:19]
	s_add_u32 s18, s18, 0x10800
	s_addc_u32 s19, s19, 0
	global_load_dword v202, v140, s[18:19]
	s_add_u32 s18, s18, 0x10800
	s_addc_u32 s19, s19, 0
	global_load_dword v203, v140, s[18:19]
	s_add_u32 s18, s18, 0x10800
	s_addc_u32 s19, s19, 0
	global_load_dword v204, v140, s[18:19]
	s_add_u32 s18, s18, 0x10800
	s_addc_u32 s19, s19, 0
	global_load_dword v205, v140, s[18:19]
	s_add_u32 s18, s18, 0x10800
	s_addc_u32 s19, s19, 0
	global_load_dword v206, v140, s[18:19]
	s_add_u32 s18, s18, 0x10800
	s_addc_u32 s19, s19, 0
	global_load_dword v207, v140, s[18:19]
	s_lshl_b32 s98, s28, 10
	s_add_u32 s18, s62, s98
	s_addc_u32 s19, s63, 0
	global_load_dword v208, v140, s[18:19]
	s_add_u32 s18, s18, 0x10800
	s_addc_u32 s19, s19, 0
	global_load_dword v209, v140, s[18:19]
	s_add_u32 s18, s18, 0x10800
	s_addc_u32 s19, s19, 0
	global_load_dword v210, v140, s[18:19]
	s_add_u32 s18, s18, 0x10800
	s_addc_u32 s19, s19, 0
	global_load_dword v211, v140, s[18:19]
	s_add_u32 s18, s18, 0x10800
	s_addc_u32 s19, s19, 0
	global_load_dword v212, v140, s[18:19]
	s_add_u32 s18, s18, 0x10800
	s_addc_u32 s19, s19, 0
	global_load_dword v213, v140, s[18:19]
	s_add_u32 s18, s18, 0x10800
	s_addc_u32 s19, s19, 0
	global_load_dword v214, v140, s[18:19]
	s_add_u32 s18, s18, 0x10800
	s_addc_u32 s19, s19, 0
	global_load_dword v215, v140, s[18:19]
	s_lshl_b32 s98, s29, 10
	s_add_u32 s18, s62, s98
	s_addc_u32 s19, s63, 0
	global_load_dword v216, v140, s[18:19]
	s_add_u32 s18, s18, 0x10800
	s_addc_u32 s19, s19, 0
	global_load_dword v217, v140, s[18:19]
	s_add_u32 s18, s18, 0x10800
	s_addc_u32 s19, s19, 0
	global_load_dword v218, v140, s[18:19]
	s_add_u32 s18, s18, 0x10800
	s_addc_u32 s19, s19, 0
	global_load_dword v219, v140, s[18:19]
	s_add_u32 s18, s18, 0x10800
	s_addc_u32 s19, s19, 0
	global_load_dword v220, v140, s[18:19]
	s_add_u32 s18, s18, 0x10800
	s_addc_u32 s19, s19, 0
	global_load_dword v221, v140, s[18:19]
	s_add_u32 s18, s18, 0x10800
	s_addc_u32 s19, s19, 0
	global_load_dword v222, v140, s[18:19]
	s_add_u32 s18, s18, 0x10800
	s_addc_u32 s19, s19, 0
	global_load_dword v223, v140, s[18:19]
	s_lshl_b32 s98, s30, 10
	s_add_u32 s18, s62, s98
	s_addc_u32 s19, s63, 0
	global_load_dword v224, v140, s[18:19]
	s_add_u32 s18, s18, 0x10800
	s_addc_u32 s19, s19, 0
	global_load_dword v225, v140, s[18:19]
	s_add_u32 s18, s18, 0x10800
	s_addc_u32 s19, s19, 0
	global_load_dword v226, v140, s[18:19]
	s_add_u32 s18, s18, 0x10800
	s_addc_u32 s19, s19, 0
	global_load_dword v227, v140, s[18:19]
	s_add_u32 s18, s18, 0x10800
	s_addc_u32 s19, s19, 0
	global_load_dword v228, v140, s[18:19]
	s_add_u32 s18, s18, 0x10800
	s_addc_u32 s19, s19, 0
	global_load_dword v229, v140, s[18:19]
	s_add_u32 s18, s18, 0x10800
	s_addc_u32 s19, s19, 0
	global_load_dword v230, v140, s[18:19]
	s_add_u32 s18, s18, 0x10800
	s_addc_u32 s19, s19, 0
	global_load_dword v231, v140, s[18:19]
	s_lshl_b32 s98, s31, 10
	s_add_u32 s18, s62, s98
	s_addc_u32 s19, s63, 0
	global_load_dword v232, v140, s[18:19]
	s_add_u32 s18, s18, 0x10800
	s_addc_u32 s19, s19, 0
	global_load_dword v233, v140, s[18:19]
	s_add_u32 s18, s18, 0x10800
	s_addc_u32 s19, s19, 0
	global_load_dword v234, v140, s[18:19]
	s_add_u32 s18, s18, 0x10800
	s_addc_u32 s19, s19, 0
	global_load_dword v235, v140, s[18:19]
	s_add_u32 s18, s18, 0x10800
	s_addc_u32 s19, s19, 0
	global_load_dword v236, v140, s[18:19]
	s_add_u32 s18, s18, 0x10800
	s_addc_u32 s19, s19, 0
	global_load_dword v237, v140, s[18:19]
	s_add_u32 s18, s18, 0x10800
	s_addc_u32 s19, s19, 0
	global_load_dword v238, v140, s[18:19]
	s_add_u32 s18, s18, 0x10800
	s_addc_u32 s19, s19, 0
	global_load_dword v239, v140, s[18:19]
	s_waitcnt vmcnt(0)
	v_add_f32_e32 v192, v192, v193
	v_add_f32_e32 v192, v192, v194
	v_add_f32_e32 v192, v192, v195
	v_add_f32_e32 v192, v192, v196
	v_add_f32_e32 v192, v192, v197
	v_add_f32_e32 v192, v192, v198
	v_add_f32_e32 v192, v192, v199
	ds_write_b32 v141, v192 offset:32768
	v_add_f32_e32 v200, v200, v201
	v_add_f32_e32 v200, v200, v202
	v_add_f32_e32 v200, v200, v203
	v_add_f32_e32 v200, v200, v204
	v_add_f32_e32 v200, v200, v205
	v_add_f32_e32 v200, v200, v206
	v_add_f32_e32 v200, v200, v207
	ds_write_b32 v141, v200 offset:34816
	v_add_f32_e32 v208, v208, v209
	v_add_f32_e32 v208, v208, v210
	v_add_f32_e32 v208, v208, v211
	v_add_f32_e32 v208, v208, v212
	v_add_f32_e32 v208, v208, v213
	v_add_f32_e32 v208, v208, v214
	v_add_f32_e32 v208, v208, v215
	ds_write_b32 v141, v208 offset:36864
	v_add_f32_e32 v216, v216, v217
	v_add_f32_e32 v216, v216, v218
	v_add_f32_e32 v216, v216, v219
	v_add_f32_e32 v216, v216, v220
	v_add_f32_e32 v216, v216, v221
	v_add_f32_e32 v216, v216, v222
	v_add_f32_e32 v216, v216, v223
	ds_write_b32 v141, v216 offset:38912
	v_add_f32_e32 v224, v224, v225
	v_add_f32_e32 v224, v224, v226
	v_add_f32_e32 v224, v224, v227
	v_add_f32_e32 v224, v224, v228
	v_add_f32_e32 v224, v224, v229
	v_add_f32_e32 v224, v224, v230
	v_add_f32_e32 v224, v224, v231
	ds_write_b32 v141, v224 offset:40960
	v_add_f32_e32 v232, v232, v233
	v_add_f32_e32 v232, v232, v234
	v_add_f32_e32 v232, v232, v235
	v_add_f32_e32 v232, v232, v236
	v_add_f32_e32 v232, v232, v237
	v_add_f32_e32 v232, v232, v238
	v_add_f32_e32 v232, v232, v239
	ds_write_b32 v141, v232 offset:43008
	s_waitcnt lgkmcnt(0)
	s_barrier
	v_cmp_gt_u32_e32 vcc, 0x100, v136
	s_and_saveexec_b64 s[18:19], vcc
	ds_read_b32 v192, v141 offset:32768
	ds_read_b32 v193, v141 offset:33792
	ds_read_b32 v194, v141 offset:34816
	ds_read_b32 v195, v141 offset:35840
	ds_read_b32 v196, v141 offset:36864
	ds_read_b32 v197, v141 offset:37888
	ds_read_b32 v198, v141 offset:38912
	ds_read_b32 v199, v141 offset:39936
	ds_read_b32 v200, v141 offset:40960
	ds_read_b32 v201, v141 offset:41984
	ds_read_b32 v202, v141 offset:43008
	ds_read_b32 v203, v141 offset:44032
	s_mov_b32 s25, 0x3a800000
	v_mov_b32_e32 v144, 0x358637bd
	s_waitcnt lgkmcnt(0)
	v_add_f32_e32 v192, v192, v193
	v_add_f32_e32 v194, v194, v195
	v_add_f32_e32 v196, v196, v197
	v_add_f32_e32 v198, v198, v199
	v_add_f32_e32 v200, v200, v201
	v_add_f32_e32 v202, v202, v203
	v_fma_f32 v192, v192, s25, v144
	v_fma_f32 v194, v194, s25, v144
	v_fma_f32 v196, v196, s25, v144
	v_fma_f32 v198, v198, s25, v144
	v_fma_f32 v200, v200, s25, v144
	v_fma_f32 v202, v202, s25, v144
	v_rsq_f32_e32 v192, v192
	v_rsq_f32_e32 v194, v194
	v_rsq_f32_e32 v196, v196
	v_rsq_f32_e32 v198, v198
	v_rsq_f32_e32 v200, v200
	v_rsq_f32_e32 v202, v202
	s_lshl_b32 s98, s26, 10
	s_add_u32 s100, s48, s98
	s_addc_u32 s101, s49, 0
	global_store_dword v141, v192, s[100:101]
	s_lshl_b32 s98, s27, 10
	s_add_u32 s100, s48, s98
	s_addc_u32 s101, s49, 0
	global_store_dword v141, v194, s[100:101]
	s_lshl_b32 s98, s28, 10
	s_add_u32 s100, s48, s98
	s_addc_u32 s101, s49, 0
	global_store_dword v141, v196, s[100:101]
	s_lshl_b32 s98, s29, 10
	s_add_u32 s100, s48, s98
	s_addc_u32 s101, s49, 0
	global_store_dword v141, v198, s[100:101]
	s_lshl_b32 s98, s30, 10
	s_add_u32 s100, s48, s98
	s_addc_u32 s101, s49, 0
	global_store_dword v141, v200, s[100:101]
	s_lshl_b32 s98, s31, 10
	s_add_u32 s100, s48, s98
	s_addc_u32 s101, s49, 0
	global_store_dword v141, v202, s[100:101]
	s_or_b64 exec, exec, s[18:19]
	s_waitcnt vmcnt(0)
	s_barrier
	s_branch .LBB0_1310

.LBB0_1468:
	s_or_b64 exec, exec, s[0:1]
	s_and_b64 vcc, exec, s[6:7]
	s_waitcnt lgkmcnt(0)
	s_barrier
	s_and_b32 s99, s2, 7
	s_lshl_b32 s99, s99, 3
	s_bfe_u32 s100, s2, 0x30003
	s_or_b32 s99, s99, s100
	s_lshr_b32 s100, s2, 6
	v_and_b32_e32 v172, 0xff, v136
	v_lshrrev_b32_e32 v173, 8, v136
	v_mul_u32_u24_e32 v173, 0x84000, v173
	v_lshl_add_u32 v172, v172, 2, v173
	s_lshl_b32 s24, s99, 10
	s_add_u32 s18, s44, s24
	s_addc_u32 s19, s45, 0
	global_load_dword v164, v172, s[18:19]
	s_add_u32 s18, s18, 0x10800
	s_addc_u32 s19, s19, 0
	global_load_dword v165, v172, s[18:19]
	s_add_u32 s18, s18, 0x10800
	s_addc_u32 s19, s19, 0
	global_load_dword v166, v172, s[18:19]
	s_add_u32 s18, s18, 0x10800
	s_addc_u32 s19, s19, 0
	global_load_dword v167, v172, s[18:19]
	s_add_u32 s18, s18, 0x10800
	s_addc_u32 s19, s19, 0
	global_load_dword v168, v172, s[18:19]
	s_add_u32 s18, s18, 0x10800
	s_addc_u32 s19, s19, 0
	global_load_dword v169, v172, s[18:19]
	s_add_u32 s18, s18, 0x10800
	s_addc_u32 s19, s19, 0
	global_load_dword v170, v172, s[18:19]
	s_add_u32 s18, s18, 0x10800
	s_addc_u32 s19, s19, 0
	global_load_dword v171, v172, s[18:19]
	v_lshrrev_b32_e32 v141, 8, v136
	v_and_b32_e32 v142, 15, v136
	v_lshl_add_u32 v141, v141, 6, v142
	v_bfe_u32 v144, v136, 6, 2
	v_bfe_u32 v145, v136, 4, 2
	v_lshlrev_b32_e32 v144, 5, v144
	v_lshl_add_u32 v144, v145, 3, v144
	s_lshl_b32 s24, s100, 8
	v_add_u32_e32 v144, s24, v144
	s_lshl_b32 s25, s99, 8
	v_add_u32_e32 v145, s25, v141
	v_lshl_add_u32 v146, v145, 10, v144
	v_lshlrev_b32_e32 v139, 1, v146
	v_lshlrev_b32_e32 v140, 2, v146
	v_lshlrev_b32_e32 v138, 2, v144
	v_readlane_b32 s18, v253, 3
	v_readlane_b32 s19, v253, 4
	v_readlane_b32 s20, v254, 52
	v_readlane_b32 s21, v254, 53
	s_nop 4
	s_add_u32 s18, s18, 0x5000
	s_addc_u32 s19, s19, 0
	global_load_dwordx4 v[148:151], v138, s[18:19]
	global_load_dwordx4 v[152:155], v138, s[18:19] offset:16
	global_load_dwordx4 v[156:159], v138, s[18:19] offset:512
	global_load_dwordx4 v[160:163], v138, s[18:19] offset:528
	s_add_u32 s22, s64, 0x0
	s_addc_u32 s23, s65, 0
	global_load_dwordx4 v[188:191], v139, s[22:23] nt
	global_load_dwordx4 v[192:195], v139, s[22:23] offset:256 nt
	s_add_u32 s22, s64, 0x8000
	s_addc_u32 s23, s65, 0
	global_load_dwordx4 v[196:199], v139, s[22:23] nt
	global_load_dwordx4 v[200:203], v139, s[22:23] offset:256 nt
	s_add_u32 s22, s64, 0x10000
	s_addc_u32 s23, s65, 0
	global_load_dwordx4 v[204:207], v139, s[22:23] nt
	global_load_dwordx4 v[208:211], v139, s[22:23] offset:256 nt
	s_add_u32 s22, s64, 0x18000
	s_addc_u32 s23, s65, 0
	global_load_dwordx4 v[212:215], v139, s[22:23] nt
	global_load_dwordx4 v[216:219], v139, s[22:23] offset:256 nt
	s_add_u32 s22, s64, 0x40000
	s_addc_u32 s23, s65, 0
	global_load_dwordx4 v[220:223], v139, s[22:23] nt
	global_load_dwordx4 v[224:227], v139, s[22:23] offset:256 nt
	s_add_u32 s22, s64, 0x48000
	s_addc_u32 s23, s65, 0
	global_load_dwordx4 v[228:231], v139, s[22:23] nt
	global_load_dwordx4 v[232:235], v139, s[22:23] offset:256 nt
	s_add_u32 s22, s64, 0x50000
	s_addc_u32 s23, s65, 0
	global_load_dwordx4 v[236:239], v139, s[22:23] nt
	global_load_dwordx4 v[240:243], v139, s[22:23] offset:256 nt
	s_add_u32 s22, s64, 0x58000
	s_addc_u32 s23, s65, 0
	global_load_dwordx4 v[244:247], v139, s[22:23] nt
	global_load_dwordx4 v[248:251], v139, s[22:23] offset:256 nt
	s_waitcnt vmcnt(20)
	v_add_f32_e32 v164, v164, v165
	v_add_f32_e32 v164, v164, v166
	v_add_f32_e32 v164, v164, v167
	v_add_f32_e32 v164, v164, v168
	v_add_f32_e32 v164, v164, v169
	v_add_f32_e32 v164, v164, v170
	v_add_f32_e32 v164, v164, v171
	v_lshlrev_b32_e32 v173, 2, v136
	ds_write_b32 v173, v164
	s_waitcnt lgkmcnt(0)
	s_barrier
	v_lshlrev_b32_e32 v142, 2, v141
	ds_read_b32 v128, v142 offset:0
	ds_read_b32 v174, v142 offset:1024
	ds_read_b32 v129, v142 offset:64
	ds_read_b32 v175, v142 offset:1088
	ds_read_b32 v130, v142 offset:128
	ds_read_b32 v176, v142 offset:1152
	ds_read_b32 v131, v142 offset:192
	ds_read_b32 v177, v142 offset:1216
	ds_read_b32 v132, v142 offset:512
	ds_read_b32 v178, v142 offset:1536
	ds_read_b32 v133, v142 offset:576
	ds_read_b32 v179, v142 offset:1600
	ds_read_b32 v134, v142 offset:640
	ds_read_b32 v180, v142 offset:1664
	ds_read_b32 v135, v142 offset:704
	ds_read_b32 v181, v142 offset:1728
	s_waitcnt lgkmcnt(0)
	s_mov_b32 s101, 0x3a800000
	v_mov_b32_e32 v143, 0x358637bd
	v_add_f32_e32 v128, v128, v174
	v_add_f32_e32 v129, v129, v175
	v_add_f32_e32 v130, v130, v176
	v_add_f32_e32 v131, v131, v177
	v_add_f32_e32 v132, v132, v178
	v_add_f32_e32 v133, v133, v179
	v_add_f32_e32 v134, v134, v180
	v_add_f32_e32 v135, v135, v181
	v_fma_f32 v128, v128, s101, v143
	v_fma_f32 v129, v129, s101, v143
	v_fma_f32 v130, v130, s101, v143
	v_fma_f32 v131, v131, s101, v143
	v_fma_f32 v132, v132, s101, v143
	v_fma_f32 v133, v133, s101, v143
	v_fma_f32 v134, v134, s101, v143
	v_fma_f32 v135, v135, s101, v143
	v_rsq_f32_e32 v128, v128
	v_rsq_f32_e32 v129, v129
	v_rsq_f32_e32 v130, v130
	v_rsq_f32_e32 v131, v131
	v_rsq_f32_e32 v132, v132
	v_rsq_f32_e32 v133, v133
	v_rsq_f32_e32 v134, v134
	v_rsq_f32_e32 v135, v135
	s_waitcnt vmcnt(0)
	s_add_u32 s22, s20, 0x0
	s_addc_u32 s23, s21, 0
	v_lshlrev_b32_e32 v164, 16, v188
	v_and_b32_e32 v165, 0xffff0000, v188
	v_lshlrev_b32_e32 v166, 16, v189
	v_and_b32_e32 v167, 0xffff0000, v189
	v_lshlrev_b32_e32 v168, 16, v190
	v_and_b32_e32 v169, 0xffff0000, v190
	v_lshlrev_b32_e32 v170, 16, v191
	v_and_b32_e32 v171, 0xffff0000, v191
	v_mul_f32_e32 v124, v124, v128
	v_mul_f32_e32 v125, v125, v128
	v_mul_f32_e32 v126, v126, v128
	v_mul_f32_e32 v127, v127, v128
	v_mul_f32_e32 v112, v112, v128
	v_mul_f32_e32 v113, v113, v128
	v_mul_f32_e32 v114, v114, v128
	v_mul_f32_e32 v115, v115, v128
	v_fmac_f32_e32 v164, v124, v148
	v_fmac_f32_e32 v165, v125, v149
	v_fmac_f32_e32 v166, v126, v150
	v_fmac_f32_e32 v167, v127, v151
	v_fmac_f32_e32 v168, v112, v152
	v_fmac_f32_e32 v169, v113, v153
	v_fmac_f32_e32 v170, v114, v154
	v_fmac_f32_e32 v171, v115, v155
	global_store_dwordx4 v140, v[164:167], s[22:23]
	global_store_dwordx4 v140, v[168:171], s[22:23] offset:16
	v_lshlrev_b32_e32 v172, 16, v192
	v_and_b32_e32 v173, 0xffff0000, v192
	v_lshlrev_b32_e32 v174, 16, v193
	v_and_b32_e32 v175, 0xffff0000, v193
	v_lshlrev_b32_e32 v176, 16, v194
	v_and_b32_e32 v177, 0xffff0000, v194
	v_lshlrev_b32_e32 v178, 16, v195
	v_and_b32_e32 v179, 0xffff0000, v195
	v_mul_f32_e32 v120, v120, v128
	v_mul_f32_e32 v121, v121, v128
	v_mul_f32_e32 v122, v122, v128
	v_mul_f32_e32 v123, v123, v128
	v_mul_f32_e32 v116, v116, v128
	v_mul_f32_e32 v117, v117, v128
	v_mul_f32_e32 v118, v118, v128
	v_mul_f32_e32 v119, v119, v128
	v_fmac_f32_e32 v172, v120, v156
	v_fmac_f32_e32 v173, v121, v157
	v_fmac_f32_e32 v174, v122, v158
	v_fmac_f32_e32 v175, v123, v159
	v_fmac_f32_e32 v176, v116, v160
	v_fmac_f32_e32 v177, v117, v161
	v_fmac_f32_e32 v178, v118, v162
	v_fmac_f32_e32 v179, v119, v163
	global_store_dwordx4 v140, v[172:175], s[22:23] offset:512
	global_store_dwordx4 v140, v[176:179], s[22:23] offset:528
	s_add_u32 s22, s20, 0x10000
	s_addc_u32 s23, s21, 0
	v_lshlrev_b32_e32 v180, 16, v196
	v_and_b32_e32 v181, 0xffff0000, v196
	v_lshlrev_b32_e32 v182, 16, v197
	v_and_b32_e32 v183, 0xffff0000, v197
	v_lshlrev_b32_e32 v184, 16, v198
	v_and_b32_e32 v185, 0xffff0000, v198
	v_lshlrev_b32_e32 v186, 16, v199
	v_and_b32_e32 v187, 0xffff0000, v199
	v_mul_f32_e32 v108, v108, v129
	v_mul_f32_e32 v109, v109, v129
	v_mul_f32_e32 v110, v110, v129
	v_mul_f32_e32 v111, v111, v129
	v_mul_f32_e32 v96, v96, v129
	v_mul_f32_e32 v97, v97, v129
	v_mul_f32_e32 v98, v98, v129
	v_mul_f32_e32 v99, v99, v129
	v_fmac_f32_e32 v180, v108, v148
	v_fmac_f32_e32 v181, v109, v149
	v_fmac_f32_e32 v182, v110, v150
	v_fmac_f32_e32 v183, v111, v151
	v_fmac_f32_e32 v184, v96, v152
	v_fmac_f32_e32 v185, v97, v153
	v_fmac_f32_e32 v186, v98, v154
	v_fmac_f32_e32 v187, v99, v155
	global_store_dwordx4 v140, v[180:183], s[22:23]
	global_store_dwordx4 v140, v[184:187], s[22:23] offset:16
	v_lshlrev_b32_e32 v164, 16, v200
	v_and_b32_e32 v165, 0xffff0000, v200
	v_lshlrev_b32_e32 v166, 16, v201
	v_and_b32_e32 v167, 0xffff0000, v201
	v_lshlrev_b32_e32 v168, 16, v202
	v_and_b32_e32 v169, 0xffff0000, v202
	v_lshlrev_b32_e32 v170, 16, v203
	v_and_b32_e32 v171, 0xffff0000, v203
	v_mul_f32_e32 v100, v100, v129
	v_mul_f32_e32 v101, v101, v129
	v_mul_f32_e32 v102, v102, v129
	v_mul_f32_e32 v103, v103, v129
	v_mul_f32_e32 v104, v104, v129
	v_mul_f32_e32 v105, v105, v129
	v_mul_f32_e32 v106, v106, v129
	v_mul_f32_e32 v107, v107, v129
	v_fmac_f32_e32 v164, v100, v156
	v_fmac_f32_e32 v165, v101, v157
	v_fmac_f32_e32 v166, v102, v158
	v_fmac_f32_e32 v167, v103, v159
	v_fmac_f32_e32 v168, v104, v160
	v_fmac_f32_e32 v169, v105, v161
	v_fmac_f32_e32 v170, v106, v162
	v_fmac_f32_e32 v171, v107, v163
	global_store_dwordx4 v140, v[164:167], s[22:23] offset:512
	global_store_dwordx4 v140, v[168:171], s[22:23] offset:528
	s_add_u32 s22, s20, 0x20000
	s_addc_u32 s23, s21, 0
	v_lshlrev_b32_e32 v172, 16, v204
	v_and_b32_e32 v173, 0xffff0000, v204
	v_lshlrev_b32_e32 v174, 16, v205
	v_and_b32_e32 v175, 0xffff0000, v205
	v_lshlrev_b32_e32 v176, 16, v206
	v_and_b32_e32 v177, 0xffff0000, v206
	v_lshlrev_b32_e32 v178, 16, v207
	v_and_b32_e32 v179, 0xffff0000, v207
	v_mul_f32_e32 v92, v92, v130
	v_mul_f32_e32 v93, v93, v130
	v_mul_f32_e32 v94, v94, v130
	v_mul_f32_e32 v95, v95, v130
	v_mul_f32_e32 v80, v80, v130
	v_mul_f32_e32 v81, v81, v130
	v_mul_f32_e32 v82, v82, v130
	v_mul_f32_e32 v83, v83, v130
	v_fmac_f32_e32 v172, v92, v148
	v_fmac_f32_e32 v173, v93, v149
	v_fmac_f32_e32 v174, v94, v150
	v_fmac_f32_e32 v175, v95, v151
	v_fmac_f32_e32 v176, v80, v152
	v_fmac_f32_e32 v177, v81, v153
	v_fmac_f32_e32 v178, v82, v154
	v_fmac_f32_e32 v179, v83, v155
	global_store_dwordx4 v140, v[172:175], s[22:23]
	global_store_dwordx4 v140, v[176:179], s[22:23] offset:16
	v_lshlrev_b32_e32 v180, 16, v208
	v_and_b32_e32 v181, 0xffff0000, v208
	v_lshlrev_b32_e32 v182, 16, v209
	v_and_b32_e32 v183, 0xffff0000, v209
	v_lshlrev_b32_e32 v184, 16, v210
	v_and_b32_e32 v185, 0xffff0000, v210
	v_lshlrev_b32_e32 v186, 16, v211
	v_and_b32_e32 v187, 0xffff0000, v211
	v_mul_f32_e32 v84, v84, v130
	v_mul_f32_e32 v85, v85, v130
	v_mul_f32_e32 v86, v86, v130
	v_mul_f32_e32 v87, v87, v130
	v_mul_f32_e32 v88, v88, v130
	v_mul_f32_e32 v89, v89, v130
	v_mul_f32_e32 v90, v90, v130
	v_mul_f32_e32 v91, v91, v130
	v_fmac_f32_e32 v180, v84, v156
	v_fmac_f32_e32 v181, v85, v157
	v_fmac_f32_e32 v182, v86, v158
	v_fmac_f32_e32 v183, v87, v159
	v_fmac_f32_e32 v184, v88, v160
	v_fmac_f32_e32 v185, v89, v161
	v_fmac_f32_e32 v186, v90, v162
	v_fmac_f32_e32 v187, v91, v163
	global_store_dwordx4 v140, v[180:183], s[22:23] offset:512
	global_store_dwordx4 v140, v[184:187], s[22:23] offset:528
	s_add_u32 s22, s20, 0x30000
	s_addc_u32 s23, s21, 0
	v_lshlrev_b32_e32 v164, 16, v212
	v_and_b32_e32 v165, 0xffff0000, v212
	v_lshlrev_b32_e32 v166, 16, v213
	v_and_b32_e32 v167, 0xffff0000, v213
	v_lshlrev_b32_e32 v168, 16, v214
	v_and_b32_e32 v169, 0xffff0000, v214
	v_lshlrev_b32_e32 v170, 16, v215
	v_and_b32_e32 v171, 0xffff0000, v215
	v_mul_f32_e32 v76, v76, v131
	v_mul_f32_e32 v77, v77, v131
	v_mul_f32_e32 v78, v78, v131
	v_mul_f32_e32 v79, v79, v131
	v_mul_f32_e32 v64, v64, v131
	v_mul_f32_e32 v65, v65, v131
	v_mul_f32_e32 v66, v66, v131
	v_mul_f32_e32 v67, v67, v131
	v_fmac_f32_e32 v164, v76, v148
	v_fmac_f32_e32 v165, v77, v149
	v_fmac_f32_e32 v166, v78, v150
	v_fmac_f32_e32 v167, v79, v151
	v_fmac_f32_e32 v168, v64, v152
	v_fmac_f32_e32 v169, v65, v153
	v_fmac_f32_e32 v170, v66, v154
	v_fmac_f32_e32 v171, v67, v155
	global_store_dwordx4 v140, v[164:167], s[22:23]
	global_store_dwordx4 v140, v[168:171], s[22:23] offset:16
	v_lshlrev_b32_e32 v172, 16, v216
	v_and_b32_e32 v173, 0xffff0000, v216
	v_lshlrev_b32_e32 v174, 16, v217
	v_and_b32_e32 v175, 0xffff0000, v217
	v_lshlrev_b32_e32 v176, 16, v218
	v_and_b32_e32 v177, 0xffff0000, v218
	v_lshlrev_b32_e32 v178, 16, v219
	v_and_b32_e32 v179, 0xffff0000, v219
	v_mul_f32_e32 v68, v68, v131
	v_mul_f32_e32 v69, v69, v131
	v_mul_f32_e32 v70, v70, v131
	v_mul_f32_e32 v71, v71, v131
	v_mul_f32_e32 v72, v72, v131
	v_mul_f32_e32 v73, v73, v131
	v_mul_f32_e32 v74, v74, v131
	v_mul_f32_e32 v75, v75, v131
	v_fmac_f32_e32 v172, v68, v156
	v_fmac_f32_e32 v173, v69, v157
	v_fmac_f32_e32 v174, v70, v158
	v_fmac_f32_e32 v175, v71, v159
	v_fmac_f32_e32 v176, v72, v160
	v_fmac_f32_e32 v177, v73, v161
	v_fmac_f32_e32 v178, v74, v162
	v_fmac_f32_e32 v179, v75, v163
	global_store_dwordx4 v140, v[172:175], s[22:23] offset:512
	global_store_dwordx4 v140, v[176:179], s[22:23] offset:528
	s_add_u32 s22, s20, 0x80000
	s_addc_u32 s23, s21, 0
	v_lshlrev_b32_e32 v180, 16, v220
	v_and_b32_e32 v181, 0xffff0000, v220
	v_lshlrev_b32_e32 v182, 16, v221
	v_and_b32_e32 v183, 0xffff0000, v221
	v_lshlrev_b32_e32 v184, 16, v222
	v_and_b32_e32 v185, 0xffff0000, v222
	v_lshlrev_b32_e32 v186, 16, v223
	v_and_b32_e32 v187, 0xffff0000, v223
	v_mul_f32_e32 v60, v60, v132
	v_mul_f32_e32 v61, v61, v132
	v_mul_f32_e32 v62, v62, v132
	v_mul_f32_e32 v63, v63, v132
	v_mul_f32_e32 v48, v48, v132
	v_mul_f32_e32 v49, v49, v132
	v_mul_f32_e32 v50, v50, v132
	v_mul_f32_e32 v51, v51, v132
	v_fmac_f32_e32 v180, v60, v148
	v_fmac_f32_e32 v181, v61, v149
	v_fmac_f32_e32 v182, v62, v150
	v_fmac_f32_e32 v183, v63, v151
	v_fmac_f32_e32 v184, v48, v152
	v_fmac_f32_e32 v185, v49, v153
	v_fmac_f32_e32 v186, v50, v154
	v_fmac_f32_e32 v187, v51, v155
	global_store_dwordx4 v140, v[180:183], s[22:23]
	global_store_dwordx4 v140, v[184:187], s[22:23] offset:16
	v_lshlrev_b32_e32 v164, 16, v224
	v_and_b32_e32 v165, 0xffff0000, v224
	v_lshlrev_b32_e32 v166, 16, v225
	v_and_b32_e32 v167, 0xffff0000, v225
	v_lshlrev_b32_e32 v168, 16, v226
	v_and_b32_e32 v169, 0xffff0000, v226
	v_lshlrev_b32_e32 v170, 16, v227
	v_and_b32_e32 v171, 0xffff0000, v227
	v_mul_f32_e32 v52, v52, v132
	v_mul_f32_e32 v53, v53, v132
	v_mul_f32_e32 v54, v54, v132
	v_mul_f32_e32 v55, v55, v132
	v_mul_f32_e32 v56, v56, v132
	v_mul_f32_e32 v57, v57, v132
	v_mul_f32_e32 v58, v58, v132
	v_mul_f32_e32 v59, v59, v132
	v_fmac_f32_e32 v164, v52, v156
	v_fmac_f32_e32 v165, v53, v157
	v_fmac_f32_e32 v166, v54, v158
	v_fmac_f32_e32 v167, v55, v159
	v_fmac_f32_e32 v168, v56, v160
	v_fmac_f32_e32 v169, v57, v161
	v_fmac_f32_e32 v170, v58, v162
	v_fmac_f32_e32 v171, v59, v163
	global_store_dwordx4 v140, v[164:167], s[22:23] offset:512
	global_store_dwordx4 v140, v[168:171], s[22:23] offset:528
	s_add_u32 s22, s20, 0x90000
	s_addc_u32 s23, s21, 0
	v_lshlrev_b32_e32 v172, 16, v228
	v_and_b32_e32 v173, 0xffff0000, v228
	v_lshlrev_b32_e32 v174, 16, v229
	v_and_b32_e32 v175, 0xffff0000, v229
	v_lshlrev_b32_e32 v176, 16, v230
	v_and_b32_e32 v177, 0xffff0000, v230
	v_lshlrev_b32_e32 v178, 16, v231
	v_and_b32_e32 v179, 0xffff0000, v231
	v_mul_f32_e32 v44, v44, v133
	v_mul_f32_e32 v45, v45, v133
	v_mul_f32_e32 v46, v46, v133
	v_mul_f32_e32 v47, v47, v133
	v_mul_f32_e32 v32, v32, v133
	v_mul_f32_e32 v33, v33, v133
	v_mul_f32_e32 v34, v34, v133
	v_mul_f32_e32 v35, v35, v133
	v_fmac_f32_e32 v172, v44, v148
	v_fmac_f32_e32 v173, v45, v149
	v_fmac_f32_e32 v174, v46, v150
	v_fmac_f32_e32 v175, v47, v151
	v_fmac_f32_e32 v176, v32, v152
	v_fmac_f32_e32 v177, v33, v153
	v_fmac_f32_e32 v178, v34, v154
	v_fmac_f32_e32 v179, v35, v155
	global_store_dwordx4 v140, v[172:175], s[22:23]
	global_store_dwordx4 v140, v[176:179], s[22:23] offset:16
	v_lshlrev_b32_e32 v180, 16, v232
	v_and_b32_e32 v181, 0xffff0000, v232
	v_lshlrev_b32_e32 v182, 16, v233
	v_and_b32_e32 v183, 0xffff0000, v233
	v_lshlrev_b32_e32 v184, 16, v234
	v_and_b32_e32 v185, 0xffff0000, v234
	v_lshlrev_b32_e32 v186, 16, v235
	v_and_b32_e32 v187, 0xffff0000, v235
	v_mul_f32_e32 v36, v36, v133
	v_mul_f32_e32 v37, v37, v133
	v_mul_f32_e32 v38, v38, v133
	v_mul_f32_e32 v39, v39, v133
	v_mul_f32_e32 v40, v40, v133
	v_mul_f32_e32 v41, v41, v133
	v_mul_f32_e32 v42, v42, v133
	v_mul_f32_e32 v43, v43, v133
	v_fmac_f32_e32 v180, v36, v156
	v_fmac_f32_e32 v181, v37, v157
	v_fmac_f32_e32 v182, v38, v158
	v_fmac_f32_e32 v183, v39, v159
	v_fmac_f32_e32 v184, v40, v160
	v_fmac_f32_e32 v185, v41, v161
	v_fmac_f32_e32 v186, v42, v162
	v_fmac_f32_e32 v187, v43, v163
	global_store_dwordx4 v140, v[180:183], s[22:23] offset:512
	global_store_dwordx4 v140, v[184:187], s[22:23] offset:528
	s_add_u32 s22, s20, 0xa0000
	s_addc_u32 s23, s21, 0
	v_lshlrev_b32_e32 v164, 16, v236
	v_and_b32_e32 v165, 0xffff0000, v236
	v_lshlrev_b32_e32 v166, 16, v237
	v_and_b32_e32 v167, 0xffff0000, v237
	v_lshlrev_b32_e32 v168, 16, v238
	v_and_b32_e32 v169, 0xffff0000, v238
	v_lshlrev_b32_e32 v170, 16, v239
	v_and_b32_e32 v171, 0xffff0000, v239
	v_mul_f32_e32 v28, v28, v134
	v_mul_f32_e32 v29, v29, v134
	v_mul_f32_e32 v30, v30, v134
	v_mul_f32_e32 v31, v31, v134
	v_mul_f32_e32 v16, v16, v134
	v_mul_f32_e32 v17, v17, v134
	v_mul_f32_e32 v18, v18, v134
	v_mul_f32_e32 v19, v19, v134
	v_fmac_f32_e32 v164, v28, v148
	v_fmac_f32_e32 v165, v29, v149
	v_fmac_f32_e32 v166, v30, v150
	v_fmac_f32_e32 v167, v31, v151
	v_fmac_f32_e32 v168, v16, v152
	v_fmac_f32_e32 v169, v17, v153
	v_fmac_f32_e32 v170, v18, v154
	v_fmac_f32_e32 v171, v19, v155
	global_store_dwordx4 v140, v[164:167], s[22:23]
	global_store_dwordx4 v140, v[168:171], s[22:23] offset:16
	v_lshlrev_b32_e32 v172, 16, v240
	v_and_b32_e32 v173, 0xffff0000, v240
	v_lshlrev_b32_e32 v174, 16, v241
	v_and_b32_e32 v175, 0xffff0000, v241
	v_lshlrev_b32_e32 v176, 16, v242
	v_and_b32_e32 v177, 0xffff0000, v242
	v_lshlrev_b32_e32 v178, 16, v243
	v_and_b32_e32 v179, 0xffff0000, v243
	v_mul_f32_e32 v20, v20, v134
	v_mul_f32_e32 v21, v21, v134
	v_mul_f32_e32 v22, v22, v134
	v_mul_f32_e32 v23, v23, v134
	v_mul_f32_e32 v24, v24, v134
	v_mul_f32_e32 v25, v25, v134
	v_mul_f32_e32 v26, v26, v134
	v_mul_f32_e32 v27, v27, v134
	v_fmac_f32_e32 v172, v20, v156
	v_fmac_f32_e32 v173, v21, v157
	v_fmac_f32_e32 v174, v22, v158
	v_fmac_f32_e32 v175, v23, v159
	v_fmac_f32_e32 v176, v24, v160
	v_fmac_f32_e32 v177, v25, v161
	v_fmac_f32_e32 v178, v26, v162
	v_fmac_f32_e32 v179, v27, v163
	global_store_dwordx4 v140, v[172:175], s[22:23] offset:512
	global_store_dwordx4 v140, v[176:179], s[22:23] offset:528
	s_add_u32 s22, s20, 0xb0000
	s_addc_u32 s23, s21, 0
	v_lshlrev_b32_e32 v180, 16, v244
	v_and_b32_e32 v181, 0xffff0000, v244
	v_lshlrev_b32_e32 v182, 16, v245
	v_and_b32_e32 v183, 0xffff0000, v245
	v_lshlrev_b32_e32 v184, 16, v246
	v_and_b32_e32 v185, 0xffff0000, v246
	v_lshlrev_b32_e32 v186, 16, v247
	v_and_b32_e32 v187, 0xffff0000, v247
	v_mul_f32_e32 v12, v12, v135
	v_mul_f32_e32 v13, v13, v135
	v_mul_f32_e32 v14, v14, v135
	v_mul_f32_e32 v15, v15, v135
	v_mul_f32_e32 v0, v0, v135
	v_mul_f32_e32 v1, v1, v135
	v_mul_f32_e32 v2, v2, v135
	v_mul_f32_e32 v3, v3, v135
	v_fmac_f32_e32 v180, v12, v148
	v_fmac_f32_e32 v181, v13, v149
	v_fmac_f32_e32 v182, v14, v150
	v_fmac_f32_e32 v183, v15, v151
	v_fmac_f32_e32 v184, v0, v152
	v_fmac_f32_e32 v185, v1, v153
	v_fmac_f32_e32 v186, v2, v154
	v_fmac_f32_e32 v187, v3, v155
	global_store_dwordx4 v140, v[180:183], s[22:23]
	global_store_dwordx4 v140, v[184:187], s[22:23] offset:16
	v_lshlrev_b32_e32 v164, 16, v248
	v_and_b32_e32 v165, 0xffff0000, v248
	v_lshlrev_b32_e32 v166, 16, v249
	v_and_b32_e32 v167, 0xffff0000, v249
	v_lshlrev_b32_e32 v168, 16, v250
	v_and_b32_e32 v169, 0xffff0000, v250
	v_lshlrev_b32_e32 v170, 16, v251
	v_and_b32_e32 v171, 0xffff0000, v251
	v_mul_f32_e32 v4, v4, v135
	v_mul_f32_e32 v5, v5, v135
	v_mul_f32_e32 v6, v6, v135
	v_mul_f32_e32 v7, v7, v135
	v_mul_f32_e32 v8, v8, v135
	v_mul_f32_e32 v9, v9, v135
	v_mul_f32_e32 v10, v10, v135
	v_mul_f32_e32 v11, v11, v135
	v_fmac_f32_e32 v164, v4, v156
	v_fmac_f32_e32 v165, v5, v157
	v_fmac_f32_e32 v166, v6, v158
	v_fmac_f32_e32 v167, v7, v159
	v_fmac_f32_e32 v168, v8, v160
	v_fmac_f32_e32 v169, v9, v161
	v_fmac_f32_e32 v170, v10, v162
	v_fmac_f32_e32 v171, v11, v163
	global_store_dwordx4 v140, v[164:167], s[22:23] offset:512
	global_store_dwordx4 v140, v[168:171], s[22:23] offset:528
	s_addk_i32 s2, 0x400
	s_cmpk_ge_u32 s2, 0x420
	s_cselect_b64 vcc, -1, 0
	s_cbranch_vccnz .LBB0_1475
	v_and_b32_e32 v4, 63, v136
	v_ashrrev_i32_e32 v0, 5, v136
	v_readlane_b32 s4, v253, 3
	v_and_b32_e32 v5, -2, v0
	v_lshlrev_b32_e32 v0, 4, v4
	v_mov_b32_e32 v1, 0
	v_readlane_b32 s5, v253, 4
	s_mov_b64 s[0:1], 0x5000
	v_xor_b32_e32 v6, 32, v137
	v_lshl_add_u64 v[2:3], s[4:5], 0, v[0:1]
	v_lshl_add_u64 v[16:17], v[2:3], 0, s[0:1]
	v_and_b32_e32 v3, 64, v137
	v_add_u32_e32 v3, 64, v3
	v_cmp_lt_i32_e64 s[0:1], v6, v3
	v_readlane_b32 s6, v253, 5
	v_readlane_b32 s7, v253, 6
	v_cndmask_b32_e64 v6, v137, v6, s[0:1]
	v_lshlrev_b32_e32 v29, 2, v6
	v_xor_b32_e32 v6, 16, v137
	v_cmp_lt_i32_e64 s[0:1], v6, v3
	v_readlane_b32 s8, v253, 7
	v_readlane_b32 s9, v253, 8
	v_cndmask_b32_e64 v6, v137, v6, s[0:1]
	v_lshlrev_b32_e32 v50, 2, v6
	v_xor_b32_e32 v6, 8, v137
	v_cmp_lt_i32_e64 s[0:1], v6, v3
	v_readlane_b32 s10, v253, 9
	v_readlane_b32 s11, v253, 10
	v_cndmask_b32_e64 v6, v137, v6, s[0:1]
	v_lshlrev_b32_e32 v51, 2, v6
	v_xor_b32_e32 v6, 4, v137
	v_cmp_lt_i32_e64 s[0:1], v6, v3
	v_readlane_b32 s12, v253, 11
	v_readlane_b32 s13, v253, 12
	v_cndmask_b32_e64 v6, v137, v6, s[0:1]
	v_lshlrev_b32_e32 v52, 2, v6
	v_xor_b32_e32 v6, 2, v137
	v_cmp_lt_i32_e64 s[0:1], v6, v3
	v_readlane_b32 s14, v253, 13
	v_readlane_b32 s15, v253, 14
	v_cndmask_b32_e64 v6, v137, v6, s[0:1]
	v_lshlrev_b32_e32 v53, 2, v6
	v_xor_b32_e32 v6, 1, v137
	v_cmp_lt_i32_e64 s[0:1], v6, v3
	v_readlane_b32 s16, v253, 15
	v_readlane_b32 s17, v253, 16
	v_readlane_b32 s18, v253, 17
	v_readlane_b32 s19, v253, 18
	v_mul_u32_u24_e32 v2, 0x4200, v4
	v_cndmask_b32_e64 v3, v137, v6, s[0:1]
	v_lshlrev_b32_e32 v54, 2, v3
	v_lshlrev_b32_e32 v2, 2, v2
	v_mov_b32_e32 v3, v1
	v_readlane_b32 s4, v254, 52
	v_lshl_add_u64 v[18:19], s[44:45], 0, v[2:3]
	v_lshlrev_b32_e32 v2, 3, v4
	v_readlane_b32 s5, v254, 53
	v_cmp_gt_u32_e32 vcc, 16, v4
	v_lshl_add_u64 v[20:21], s[64:65], 0, v[2:3]
	v_lshl_add_u64 v[22:23], s[58:59], 0, v[2:3]
	v_lshl_add_u64 v[24:25], s[4:5], 0, v[0:1]
	v_lshl_add_u32 v26, s2, 4, v5
	s_lshl_b32 s3, s38, 4
	s_mov_b32 s4, 0x3a800000
	s_mov_b32 s5, 0x800000
	v_mov_b32_e32 v28, 0x358637bd
	v_readlane_b32 s6, v254, 54
	v_readlane_b32 s7, v254, 55
	v_readlane_b32 s8, v254, 56
	v_readlane_b32 s9, v254, 57
	v_readlane_b32 s10, v254, 58
	v_readlane_b32 s11, v254, 59
	v_readlane_b32 s12, v254, 60
	v_readlane_b32 s13, v254, 61
	v_readlane_b32 s14, v254, 62
	v_readlane_b32 s15, v254, 63
	v_readlane_b32 s16, v255, 0
	v_readlane_b32 s17, v255, 1
	v_readlane_b32 s18, v255, 2
	v_readlane_b32 s19, v255, 3
	s_branch .LBB0_1471
